# c18 + s_setprio 1 issued before the pre-MMA barrier instead of after it (first MFMA issues one slot sooner after release)
# baseline (speedup 1.0000x reference)
.LBB0_42:
	s_add_u32 s82, s80, 0xfffc0080
	s_addc_u32 s83, s81, -1
	s_add_i32 s94, 0, 0x10000
	v_add_u32_e32 v0, s94, v189
	ds_read_b128 v[122:125], v0
	ds_read_b128 v[126:129], v0 offset:1024
	ds_read_b128 v[130:133], v0 offset:2048
	ds_read_b128 v[134:137], v0 offset:3072
	s_cmp_eq_u32 s93, 12
	s_cselect_b32 s85, s11, s83
	s_cselect_b32 s84, s89, s82
	s_cselect_b32 s83, s9, s92
	s_cselect_b32 s82, s90, s91
	v_lshl_add_u64 v[186:187], s[80:81], 0, v[184:185]
	s_add_i32 m0, s59, 0xc000
	ds_read_b128 v[146:149], v193
	ds_read_b128 v[150:153], v193 offset:1024
	ds_read_b128 v[154:157], v193 offset:2048
	ds_read_b128 v[158:161], v193 offset:3072
	ds_read_b128 v[162:165], v193 offset:4096
	ds_read_b128 v[166:169], v193 offset:5120
	ds_read_b128 v[170:173], v193 offset:6144
	ds_read_b128 v[174:177], v193 offset:7168
	global_load_lds_dwordx4 v[186:187], off
	v_lshl_add_u64 v[186:187], s[80:81], 0, v[182:183]
	s_add_i32 m0, s59, 0xe000
	s_nop 0
	global_load_lds_dwordx4 v[186:187], off
	s_waitcnt lgkmcnt(8)
	s_setprio 1
	s_barrier
	s_waitcnt lgkmcnt(0)
	v_mfma_f32_16x16x32_bf16 v[142:145], v[122:125], v[146:149], v[142:145]
	v_mfma_f32_16x16x32_bf16 v[138:141], v[130:133], v[146:149], v[138:141]
	v_mfma_f32_16x16x32_bf16 v[110:113], v[122:125], v[154:157], v[110:113]
	v_mfma_f32_16x16x32_bf16 v[106:109], v[130:133], v[154:157], v[106:109]
	v_mfma_f32_16x16x32_bf16 v[94:97], v[122:125], v[162:165], v[94:97]
	v_mfma_f32_16x16x32_bf16 v[90:93], v[130:133], v[162:165], v[90:93]
	v_mfma_f32_16x16x32_bf16 v[78:81], v[122:125], v[170:173], v[78:81]
	v_mfma_f32_16x16x32_bf16 v[74:77], v[130:133], v[170:173], v[74:77]
	v_mfma_f32_16x16x32_bf16 v[142:145], v[126:129], v[150:153], v[142:145]
	v_mfma_f32_16x16x32_bf16 v[138:141], v[134:137], v[150:153], v[138:141]
	v_mfma_f32_16x16x32_bf16 v[110:113], v[126:129], v[158:161], v[110:113]
	v_mfma_f32_16x16x32_bf16 v[106:109], v[134:137], v[158:161], v[106:109]
	v_mfma_f32_16x16x32_bf16 v[94:97], v[126:129], v[166:169], v[94:97]
	v_mfma_f32_16x16x32_bf16 v[90:93], v[134:137], v[166:169], v[90:93]
	v_mfma_f32_16x16x32_bf16 v[78:81], v[126:129], v[174:177], v[78:81]
	v_mfma_f32_16x16x32_bf16 v[74:77], v[134:137], v[174:177], v[74:77]
	s_setprio 0
	s_barrier
	s_add_i32 s96, 0, 0x14000
	s_add_i32 s94, s94, s46
	v_add_u32_e32 v0, s96, v189
	v_lshl_add_u64 v[186:187], s[82:83], 0, v[180:181]
	s_mov_b32 m0, s94
	ds_read_b128 v[194:197], v0
	ds_read_b128 v[198:201], v0 offset:1024
	ds_read_b128 v[202:205], v0 offset:2048
	ds_read_b128 v[206:209], v0 offset:3072
	global_load_lds_dwordx4 v[186:187], off
	v_lshl_add_u64 v[210:211], s[82:83], 0, v[178:179]
	s_add_i32 m0, s94, 0x2000
	s_nop 0
	global_load_lds_dwordx4 v[210:211], off
	s_setprio 1
	s_barrier
	s_waitcnt lgkmcnt(0)
	v_mfma_f32_16x16x32_bf16 v[118:121], v[194:197], v[146:149], v[118:121]
	v_mfma_f32_16x16x32_bf16 v[114:117], v[202:205], v[146:149], v[114:117]
	v_mfma_f32_16x16x32_bf16 v[102:105], v[194:197], v[154:157], v[102:105]
	v_mfma_f32_16x16x32_bf16 v[98:101], v[202:205], v[154:157], v[98:101]
	v_mfma_f32_16x16x32_bf16 v[86:89], v[194:197], v[162:165], v[86:89]
	v_mfma_f32_16x16x32_bf16 v[82:85], v[202:205], v[162:165], v[82:85]
	v_mfma_f32_16x16x32_bf16 v[70:73], v[194:197], v[170:173], v[70:73]
	v_mfma_f32_16x16x32_bf16 v[66:69], v[202:205], v[170:173], v[66:69]
	v_mfma_f32_16x16x32_bf16 v[118:121], v[198:201], v[150:153], v[118:121]
	v_mfma_f32_16x16x32_bf16 v[114:117], v[206:209], v[150:153], v[114:117]
	v_mfma_f32_16x16x32_bf16 v[102:105], v[198:201], v[158:161], v[102:105]
	v_mfma_f32_16x16x32_bf16 v[98:101], v[206:209], v[158:161], v[98:101]
	v_mfma_f32_16x16x32_bf16 v[86:89], v[198:201], v[166:169], v[86:89]
	v_mfma_f32_16x16x32_bf16 v[82:85], v[206:209], v[166:169], v[82:85]
	v_mfma_f32_16x16x32_bf16 v[70:73], v[198:201], v[174:177], v[70:73]
	v_mfma_f32_16x16x32_bf16 v[66:69], v[206:209], v[174:177], v[66:69]
	s_setprio 0
	s_mov_b32 m0, s59
	v_lshl_add_u64 v[212:213], s[84:85], 0, v[180:181]
	s_barrier
	ds_read_b128 v[146:149], v193 offset:16384
	ds_read_b128 v[150:153], v193 offset:17408
	ds_read_b128 v[154:157], v193 offset:18432
	ds_read_b128 v[158:161], v193 offset:19456
	ds_read_b128 v[162:165], v193 offset:20480
	ds_read_b128 v[166:169], v193 offset:21504
	ds_read_b128 v[170:173], v193 offset:22528
	ds_read_b128 v[174:177], v193 offset:23552
	global_load_lds_dwordx4 v[212:213], off
	v_lshl_add_u64 v[214:215], s[84:85], 0, v[178:179]
	s_mov_b32 m0, s60
	s_nop 0
	global_load_lds_dwordx4 v[214:215], off
	s_setprio 1
	s_barrier
	s_waitcnt lgkmcnt(0)
	v_mfma_f32_16x16x32_bf16 v[62:65], v[122:125], v[146:149], v[62:65]
	v_mfma_f32_16x16x32_bf16 v[58:61], v[130:133], v[146:149], v[58:61]
	v_mfma_f32_16x16x32_bf16 v[46:49], v[122:125], v[154:157], v[46:49]
	v_mfma_f32_16x16x32_bf16 v[42:45], v[130:133], v[154:157], v[42:45]
	v_mfma_f32_16x16x32_bf16 v[30:33], v[122:125], v[162:165], v[30:33]
	v_mfma_f32_16x16x32_bf16 v[26:29], v[130:133], v[162:165], v[26:29]
	v_mfma_f32_16x16x32_bf16 v[14:17], v[122:125], v[170:173], v[14:17]
	v_mfma_f32_16x16x32_bf16 v[10:13], v[130:133], v[170:173], v[10:13]
	v_mfma_f32_16x16x32_bf16 v[62:65], v[126:129], v[150:153], v[62:65]
	v_mfma_f32_16x16x32_bf16 v[58:61], v[134:137], v[150:153], v[58:61]
	v_mfma_f32_16x16x32_bf16 v[46:49], v[126:129], v[158:161], v[46:49]
	v_mfma_f32_16x16x32_bf16 v[42:45], v[134:137], v[158:161], v[42:45]
	v_mfma_f32_16x16x32_bf16 v[30:33], v[126:129], v[166:169], v[30:33]
	v_mfma_f32_16x16x32_bf16 v[26:29], v[134:137], v[166:169], v[26:29]
	v_mfma_f32_16x16x32_bf16 v[14:17], v[126:129], v[174:177], v[14:17]
	v_mfma_f32_16x16x32_bf16 v[10:13], v[134:137], v[174:177], v[10:13]
	s_setprio 0
	s_barrier
	s_add_u32 s94, s82, 0x40000
	s_addc_u32 s95, s83, 0
	s_add_i32 s96, s96, s46
	v_lshl_add_u64 v[122:123], s[94:95], 0, v[180:181]
	s_mov_b32 m0, s96
	s_nop 0
	global_load_lds_dwordx4 v[122:123], off
	v_lshl_add_u64 v[122:123], s[94:95], 0, v[178:179]
	s_add_i32 m0, s96, 0x2000
	s_nop 0
	global_load_lds_dwordx4 v[122:123], off
	s_waitcnt vmcnt(6)
	s_setprio 1
	s_barrier
	v_mfma_f32_16x16x32_bf16 v[54:57], v[194:197], v[146:149], v[54:57]
	v_mfma_f32_16x16x32_bf16 v[50:53], v[202:205], v[146:149], v[50:53]
	v_mfma_f32_16x16x32_bf16 v[38:41], v[194:197], v[154:157], v[38:41]
	v_mfma_f32_16x16x32_bf16 v[34:37], v[202:205], v[154:157], v[34:37]
	v_mfma_f32_16x16x32_bf16 v[22:25], v[194:197], v[162:165], v[22:25]
	v_mfma_f32_16x16x32_bf16 v[18:21], v[202:205], v[162:165], v[18:21]
	v_mfma_f32_16x16x32_bf16 v[6:9], v[194:197], v[170:173], v[6:9]
	v_mfma_f32_16x16x32_bf16 v[2:5], v[202:205], v[170:173], v[2:5]
	v_mfma_f32_16x16x32_bf16 v[54:57], v[198:201], v[150:153], v[54:57]
	v_mfma_f32_16x16x32_bf16 v[50:53], v[206:209], v[150:153], v[50:53]
	v_mfma_f32_16x16x32_bf16 v[38:41], v[198:201], v[158:161], v[38:41]
	v_mfma_f32_16x16x32_bf16 v[34:37], v[206:209], v[158:161], v[34:37]
	v_mfma_f32_16x16x32_bf16 v[22:25], v[198:201], v[166:169], v[22:25]
	v_mfma_f32_16x16x32_bf16 v[18:21], v[206:209], v[166:169], v[18:21]
	v_mfma_f32_16x16x32_bf16 v[6:9], v[198:201], v[174:177], v[6:9]
	v_mfma_f32_16x16x32_bf16 v[2:5], v[206:209], v[174:177], v[2:5]
	s_setprio 0
	s_add_i32 s94, 0, 0x18000
	v_add_u32_e32 v0, s94, v189
	s_barrier
	ds_read_b128 v[122:125], v0
	ds_read_b128 v[126:129], v0 offset:1024
	ds_read_b128 v[130:133], v0 offset:2048
	ds_read_b128 v[134:137], v0 offset:3072
	s_add_u32 s84, s84, 0x40000
	s_addc_u32 s85, s85, 0
	s_mov_b32 m0, s61
	v_lshl_add_u64 v[194:195], s[84:85], 0, v[180:181]
	ds_read_b128 v[146:149], v193 offset:32768
	ds_read_b128 v[150:153], v193 offset:33792
	ds_read_b128 v[154:157], v193 offset:34816
	ds_read_b128 v[158:161], v193 offset:35840
	ds_read_b128 v[162:165], v193 offset:36864
	ds_read_b128 v[166:169], v193 offset:37888
	ds_read_b128 v[170:173], v193 offset:38912
	ds_read_b128 v[174:177], v193 offset:39936
	global_load_lds_dwordx4 v[194:195], off
	v_lshl_add_u64 v[194:195], s[84:85], 0, v[178:179]
	s_mov_b32 m0, s76
	s_nop 0
	global_load_lds_dwordx4 v[194:195], off
	s_waitcnt lgkmcnt(8)
	s_setprio 1
	s_barrier
	s_waitcnt lgkmcnt(0)
	v_mfma_f32_16x16x32_bf16 v[142:145], v[122:125], v[146:149], v[142:145]
	v_mfma_f32_16x16x32_bf16 v[138:141], v[130:133], v[146:149], v[138:141]
	v_mfma_f32_16x16x32_bf16 v[110:113], v[122:125], v[154:157], v[110:113]
	v_mfma_f32_16x16x32_bf16 v[106:109], v[130:133], v[154:157], v[106:109]
	v_mfma_f32_16x16x32_bf16 v[94:97], v[122:125], v[162:165], v[94:97]
	v_mfma_f32_16x16x32_bf16 v[90:93], v[130:133], v[162:165], v[90:93]
	v_mfma_f32_16x16x32_bf16 v[78:81], v[122:125], v[170:173], v[78:81]
	v_mfma_f32_16x16x32_bf16 v[74:77], v[130:133], v[170:173], v[74:77]
	v_mfma_f32_16x16x32_bf16 v[142:145], v[126:129], v[150:153], v[142:145]
	v_mfma_f32_16x16x32_bf16 v[138:141], v[134:137], v[150:153], v[138:141]
	v_mfma_f32_16x16x32_bf16 v[110:113], v[126:129], v[158:161], v[110:113]
	v_mfma_f32_16x16x32_bf16 v[106:109], v[134:137], v[158:161], v[106:109]
	v_mfma_f32_16x16x32_bf16 v[94:97], v[126:129], v[166:169], v[94:97]
	v_mfma_f32_16x16x32_bf16 v[90:93], v[134:137], v[166:169], v[90:93]
	v_mfma_f32_16x16x32_bf16 v[78:81], v[126:129], v[174:177], v[78:81]
	v_mfma_f32_16x16x32_bf16 v[74:77], v[134:137], v[174:177], v[74:77]
	s_setprio 0
	s_barrier
	s_add_i32 s84, 0, 0x1c000
	s_add_i32 s85, s94, s46
	v_add_u32_e32 v0, s84, v189
	v_lshl_add_u64 v[186:187], v[186:187], 0, s[48:49]
	s_mov_b32 m0, s85
	ds_read_b128 v[194:197], v0
	ds_read_b128 v[198:201], v0 offset:1024
	ds_read_b128 v[202:205], v0 offset:2048
	ds_read_b128 v[206:209], v0 offset:3072
	global_load_lds_dwordx4 v[186:187], off
	v_lshl_add_u64 v[186:187], v[210:211], 0, s[48:49]
	s_add_i32 m0, s85, 0x2000
	s_nop 0
	global_load_lds_dwordx4 v[186:187], off
	s_setprio 1
	s_barrier
	s_waitcnt lgkmcnt(0)
	v_mfma_f32_16x16x32_bf16 v[118:121], v[194:197], v[146:149], v[118:121]
	v_mfma_f32_16x16x32_bf16 v[114:117], v[202:205], v[146:149], v[114:117]
	v_mfma_f32_16x16x32_bf16 v[102:105], v[194:197], v[154:157], v[102:105]
	v_mfma_f32_16x16x32_bf16 v[98:101], v[202:205], v[154:157], v[98:101]
	v_mfma_f32_16x16x32_bf16 v[86:89], v[194:197], v[162:165], v[86:89]
	v_mfma_f32_16x16x32_bf16 v[82:85], v[202:205], v[162:165], v[82:85]
	v_mfma_f32_16x16x32_bf16 v[70:73], v[194:197], v[170:173], v[70:73]
	v_mfma_f32_16x16x32_bf16 v[66:69], v[202:205], v[170:173], v[66:69]
	v_mfma_f32_16x16x32_bf16 v[118:121], v[198:201], v[150:153], v[118:121]
	v_mfma_f32_16x16x32_bf16 v[114:117], v[206:209], v[150:153], v[114:117]
	v_mfma_f32_16x16x32_bf16 v[102:105], v[198:201], v[158:161], v[102:105]
	v_mfma_f32_16x16x32_bf16 v[98:101], v[206:209], v[158:161], v[98:101]
	v_mfma_f32_16x16x32_bf16 v[86:89], v[198:201], v[166:169], v[86:89]
	v_mfma_f32_16x16x32_bf16 v[82:85], v[206:209], v[166:169], v[82:85]
	v_mfma_f32_16x16x32_bf16 v[70:73], v[198:201], v[174:177], v[70:73]
	v_mfma_f32_16x16x32_bf16 v[66:69], v[206:209], v[174:177], v[66:69]
	s_setprio 0
	s_mov_b32 m0, s79
	v_lshl_add_u64 v[186:187], v[212:213], 0, s[48:49]
	s_barrier
	ds_read_b128 v[146:149], v193 offset:49152
	ds_read_b128 v[150:153], v193 offset:50176
	ds_read_b128 v[154:157], v193 offset:51200
	ds_read_b128 v[158:161], v193 offset:52224
	ds_read_b128 v[162:165], v193 offset:53248
	ds_read_b128 v[166:169], v193 offset:54272
	ds_read_b128 v[170:173], v193 offset:55296
	ds_read_b128 v[174:177], v193 offset:56320
	global_load_lds_dwordx4 v[186:187], off
	v_lshl_add_u64 v[186:187], v[214:215], 0, s[48:49]
	s_mov_b32 m0, s86
	s_nop 0
	global_load_lds_dwordx4 v[186:187], off
	s_setprio 1
	s_barrier
; template <int CTRL> DEVI float dpp(float x) { return __builtin_bit_cast(float, __builtin_amdgcn_mov_dpp(__builtin_bit_cast(int, x), CTRL, 0xf, 0xf, true)); }
;     DEVI void operator()(AccRef acc, const pg8::Unit& u, int wr, int wc, int fr, int fq) const {
;         unsigned o = (unsigned)((u.pm * 256 + wr * 64 + fr) * DM + u.pn * 256 + wc * 32 + 4 * fq) * 4u;
;         const bool lo = fr < 8;
;         unsigned os = (unsigned)((u.pm * 256 + wr * 64 + (fr & 7)) * DM + u.pn * 256 + wc * 32 + 4 * fq) * 4u + (lo ? 0u : 64u);
; #pragma unroll
;         for (int ai = 0; ai < 2; ++ai) {
;             asm volatile("" : "+v"(o), "+v"(os));
;             f32x4 b[4][2][2];
; #pragma unroll
;             for (int m = 0; m < 4; ++m)
; #pragma unroll
;                 for (int bj = 0; bj < 2; ++bj)
; #pragma unroll
;                     for (int n = 0; n < 2; ++n) b[m][bj][n] = *(const f32x4*)((const char*)base + o + (unsigned)(m * 16 * DM * 4 + bj * 512 + n * 64));
; #pragma unroll
;             for (int m = 0; m < 4; ++m)
; #pragma unroll
;                 for (int bj = 0; bj < 2; ++bj) { const f32x4 d0 = b[m][bj][0] + alpha * acc[ai][bj][m][0], d1 = b[m][bj][1] + alpha * acc[ai][bj][m][1];
;                     f32x4 t0, t1;
; #pragma unroll
;                     for (int i = 0; i < 4; ++i) { t0[i] = dpp<0x128>(d0[i]); t1[i] = dpp<0x128>(d1[i]); }
;                     const f32x4 sa = lo ? d0 : t1, sb = lo ? t0 : d1;
;                     const unsigned oo = os + (unsigned)(m * 16 * DM * 4 + bj * 512);
;                     *(f32x4*)((char*)out + oo) = sa; *(f32x4*)((char*)out + oo + 8u * DM * 4u) = sb; }
;             o += 128u * DM * 4u; os += 128u * DM * 4u; }
	s_waitcnt lgkmcnt(0)
	v_mfma_f32_16x16x32_bf16 v[62:65], v[122:125], v[146:149], v[62:65]
	v_mfma_f32_16x16x32_bf16 v[58:61], v[130:133], v[146:149], v[58:61]
	v_mfma_f32_16x16x32_bf16 v[46:49], v[122:125], v[154:157], v[46:49]
	v_mfma_f32_16x16x32_bf16 v[42:45], v[130:133], v[154:157], v[42:45]
	v_mfma_f32_16x16x32_bf16 v[30:33], v[122:125], v[162:165], v[30:33]
	v_mfma_f32_16x16x32_bf16 v[26:29], v[130:133], v[162:165], v[26:29]
	v_mfma_f32_16x16x32_bf16 v[14:17], v[122:125], v[170:173], v[14:17]
	v_mfma_f32_16x16x32_bf16 v[10:13], v[130:133], v[170:173], v[10:13]
	v_mfma_f32_16x16x32_bf16 v[62:65], v[126:129], v[150:153], v[62:65]
	v_mfma_f32_16x16x32_bf16 v[58:61], v[134:137], v[150:153], v[58:61]
	v_mfma_f32_16x16x32_bf16 v[46:49], v[126:129], v[158:161], v[46:49]
	v_mfma_f32_16x16x32_bf16 v[42:45], v[134:137], v[158:161], v[42:45]
	v_mfma_f32_16x16x32_bf16 v[30:33], v[126:129], v[166:169], v[30:33]
	v_mfma_f32_16x16x32_bf16 v[26:29], v[134:137], v[166:169], v[26:29]
	v_mfma_f32_16x16x32_bf16 v[14:17], v[126:129], v[174:177], v[14:17]
	v_mfma_f32_16x16x32_bf16 v[10:13], v[134:137], v[174:177], v[10:13]
	s_setprio 0
	s_barrier
	s_add_u32 s82, s82, 0x40080
	s_addc_u32 s83, s83, 0
	s_add_i32 s84, s84, s46
	v_lshl_add_u64 v[122:123], s[82:83], 0, v[180:181]
	s_mov_b32 m0, s84
	s_nop 0
	global_load_lds_dwordx4 v[122:123], off
	v_lshl_add_u64 v[122:123], s[82:83], 0, v[178:179]
	s_add_i32 m0, s84, 0x2000
	s_nop 0
	global_load_lds_dwordx4 v[122:123], off
	s_waitcnt vmcnt(6)
	s_setprio 1
	s_barrier
	v_mfma_f32_16x16x32_bf16 v[54:57], v[194:197], v[146:149], v[54:57]
	v_mfma_f32_16x16x32_bf16 v[50:53], v[202:205], v[146:149], v[50:53]
	v_mfma_f32_16x16x32_bf16 v[38:41], v[194:197], v[154:157], v[38:41]
	v_mfma_f32_16x16x32_bf16 v[34:37], v[202:205], v[154:157], v[34:37]
	v_mfma_f32_16x16x32_bf16 v[22:25], v[194:197], v[162:165], v[22:25]
	v_mfma_f32_16x16x32_bf16 v[18:21], v[202:205], v[162:165], v[18:21]
	v_mfma_f32_16x16x32_bf16 v[6:9], v[194:197], v[170:173], v[6:9]
	v_mfma_f32_16x16x32_bf16 v[2:5], v[202:205], v[170:173], v[2:5]
	v_mfma_f32_16x16x32_bf16 v[54:57], v[198:201], v[150:153], v[54:57]
	v_mfma_f32_16x16x32_bf16 v[50:53], v[206:209], v[150:153], v[50:53]
	v_mfma_f32_16x16x32_bf16 v[38:41], v[198:201], v[158:161], v[38:41]
	v_mfma_f32_16x16x32_bf16 v[34:37], v[206:209], v[158:161], v[34:37]
	v_mfma_f32_16x16x32_bf16 v[22:25], v[198:201], v[166:169], v[22:25]
	v_mfma_f32_16x16x32_bf16 v[18:21], v[206:209], v[166:169], v[18:21]
	v_mfma_f32_16x16x32_bf16 v[6:9], v[198:201], v[174:177], v[6:9]
	v_mfma_f32_16x16x32_bf16 v[2:5], v[206:209], v[174:177], v[2:5]
	s_setprio 0
	s_add_i32 s93, s93, 2
	s_add_u32 s91, s91, 0x100
	s_addc_u32 s92, s92, 0
	s_add_u32 s80, s80, 0x100
	s_addc_u32 s81, s81, 0
	s_cmp_gt_u32 s93, 13
	s_barrier
	s_cbranch_scc0 .LBB0_42
	s_lshl_b32 s9, s78, 8
	s_add_i32 s9, s9, s77
	v_or_b32_e32 v0, s9, v188
	s_lshl_b32 s11, s88, 8
	v_or_b32_e32 v122, s9, v190
	v_lshl_add_u32 v0, v0, 10, s11
	v_lshl_add_u32 v122, v122, 10, s11
	v_or_b32_e32 v0, v0, v192
	v_or_b32_e32 v122, v122, v192
	v_lshlrev_b32_e32 v0, 2, v0
	v_lshl_or_b32 v186, v122, 2, v191
	s_mov_b32 s88, s8
	s_mov_b32 s78, s10
	s_mov_b64 s[80:81], s[24:25]
	s_mov_b64 s[82:83], s[22:23]
	v_add_u32_e32 v187, 0x8000, v186
	s_add_u32 s98, s28, 0x0
	s_addc_u32 s99, s29, 0
	global_load_dwordx4 v[194:197], v0, s[98:99]
	global_load_dwordx4 v[198:201], v0, s[98:99] offset:64
	global_load_dwordx4 v[202:205], v0, s[98:99] offset:512
	global_load_dwordx4 v[206:209], v0, s[98:99] offset:576
	s_add_u32 s98, s28, 0x10000
	s_addc_u32 s99, s29, 0
	global_load_dwordx4 v[174:177], v0, s[98:99]
	global_load_dwordx4 v[170:173], v0, s[98:99] offset:64
	global_load_dwordx4 v[166:169], v0, s[98:99] offset:512
	global_load_dwordx4 v[162:165], v0, s[98:99] offset:576
	s_add_u32 s98, s28, 0x20000
	s_addc_u32 s99, s29, 0
	global_load_dwordx4 v[158:161], v0, s[98:99]
	global_load_dwordx4 v[154:157], v0, s[98:99] offset:64
	global_load_dwordx4 v[150:153], v0, s[98:99] offset:512
	global_load_dwordx4 v[146:149], v0, s[98:99] offset:576
	s_add_u32 s98, s28, 0x30000
	s_addc_u32 s99, s29, 0
	global_load_dwordx4 v[134:137], v0, s[98:99]
	global_load_dwordx4 v[130:133], v0, s[98:99] offset:64
	global_load_dwordx4 v[126:129], v0, s[98:99] offset:512
	global_load_dwordx4 v[122:125], v0, s[98:99] offset:576
	s_waitcnt vmcnt(12)
	v_pk_add_f32 v[142:143], v[142:143], v[194:195]
	v_pk_add_f32 v[144:145], v[144:145], v[196:197]
	v_pk_add_f32 v[138:139], v[138:139], v[198:199]
	v_pk_add_f32 v[140:141], v[140:141], v[200:201]
	v_pk_add_f32 v[118:119], v[118:119], v[202:203]
	v_pk_add_f32 v[120:121], v[120:121], v[204:205]
	v_pk_add_f32 v[114:115], v[114:115], v[206:207]
	v_pk_add_f32 v[116:117], v[116:117], v[208:209]
	s_mov_b64 vcc, s[4:5]
	v_cndmask_b32_dpp v194, v138, v142, vcc row_ror:8 row_mask:0xf bank_mask:0xf bound_ctrl:1
	v_cndmask_b32_dpp v195, v139, v143, vcc row_ror:8 row_mask:0xf bank_mask:0xf bound_ctrl:1
	v_cndmask_b32_dpp v196, v140, v144, vcc row_ror:8 row_mask:0xf bank_mask:0xf bound_ctrl:1
	v_cndmask_b32_dpp v197, v141, v145, vcc row_ror:8 row_mask:0xf bank_mask:0xf bound_ctrl:1
	v_cndmask_b32_dpp v202, v114, v118, vcc row_ror:8 row_mask:0xf bank_mask:0xf bound_ctrl:1
	v_cndmask_b32_dpp v203, v115, v119, vcc row_ror:8 row_mask:0xf bank_mask:0xf bound_ctrl:1
	v_cndmask_b32_dpp v204, v116, v120, vcc row_ror:8 row_mask:0xf bank_mask:0xf bound_ctrl:1
	v_cndmask_b32_dpp v205, v117, v121, vcc row_ror:8 row_mask:0xf bank_mask:0xf bound_ctrl:1
	s_not_b64 vcc, s[4:5]
	v_cndmask_b32_dpp v198, v142, v138, vcc row_ror:8 row_mask:0xf bank_mask:0xf bound_ctrl:1
	v_cndmask_b32_dpp v199, v143, v139, vcc row_ror:8 row_mask:0xf bank_mask:0xf bound_ctrl:1
	v_cndmask_b32_dpp v200, v144, v140, vcc row_ror:8 row_mask:0xf bank_mask:0xf bound_ctrl:1
	v_cndmask_b32_dpp v201, v145, v141, vcc row_ror:8 row_mask:0xf bank_mask:0xf bound_ctrl:1
	v_cndmask_b32_dpp v206, v118, v114, vcc row_ror:8 row_mask:0xf bank_mask:0xf bound_ctrl:1
	v_cndmask_b32_dpp v207, v119, v115, vcc row_ror:8 row_mask:0xf bank_mask:0xf bound_ctrl:1
	v_cndmask_b32_dpp v208, v120, v116, vcc row_ror:8 row_mask:0xf bank_mask:0xf bound_ctrl:1
	v_cndmask_b32_dpp v209, v121, v117, vcc row_ror:8 row_mask:0xf bank_mask:0xf bound_ctrl:1
	s_add_u32 s100, s28, 0x0
	s_addc_u32 s101, s29, 0
	global_store_dwordx4 v186, v[194:197], s[100:101]
	global_store_dwordx4 v187, v[198:201], s[100:101]
	global_store_dwordx4 v186, v[202:205], s[100:101] offset:512
	global_store_dwordx4 v187, v[206:209], s[100:101] offset:512
	s_add_u32 s98, s28, 0x80000
	s_addc_u32 s99, s29, 0
	global_load_dwordx4 v[142:145], v0, s[98:99]
	global_load_dwordx4 v[138:141], v0, s[98:99] offset:64
	global_load_dwordx4 v[118:121], v0, s[98:99] offset:512
	global_load_dwordx4 v[114:117], v0, s[98:99] offset:576
	s_waitcnt vmcnt(16)
; template <int CTRL> DEVI float dpp(float x) { return __builtin_bit_cast(float, __builtin_amdgcn_mov_dpp(__builtin_bit_cast(int, x), CTRL, 0xf, 0xf, true)); }
;     DEVI void operator()(AccRef acc, const pg8::Unit& u, int wr, int wc, int fr, int fq) const {
;     ...
;             for (int m = 0; m < 4; ++m)
; #pragma unroll
;                 for (int bj = 0; bj < 2; ++bj)
; #pragma unroll
;                     for (int n = 0; n < 2; ++n) b[m][bj][n] = *(const f32x4*)((const char*)base + o + (unsigned)(m * 16 * DM * 4 + bj * 512 + n * 64));
; #pragma unroll
;             for (int m = 0; m < 4; ++m)
; #pragma unroll
;                 for (int bj = 0; bj < 2; ++bj) { const f32x4 d0 = b[m][bj][0] + alpha * acc[ai][bj][m][0], d1 = b[m][bj][1] + alpha * acc[ai][bj][m][1];
;                     f32x4 t0, t1;
; #pragma unroll
;                     for (int i = 0; i < 4; ++i) { t0[i] = dpp<0x128>(d0[i]); t1[i] = dpp<0x128>(d1[i]); }
;                     const f32x4 sa = lo ? d0 : t1, sb = lo ? t0 : d1;
;                     const unsigned oo = os + (unsigned)(m * 16 * DM * 4 + bj * 512);
;                     *(f32x4*)((char*)out + oo) = sa; *(f32x4*)((char*)out + oo + 8u * DM * 4u) = sb; }
;             o += 128u * DM * 4u; os += 128u * DM * 4u; }
	v_pk_add_f32 v[110:111], v[110:111], v[174:175]
	v_pk_add_f32 v[112:113], v[112:113], v[176:177]
	v_pk_add_f32 v[106:107], v[106:107], v[170:171]
	v_pk_add_f32 v[108:109], v[108:109], v[172:173]
	v_pk_add_f32 v[102:103], v[102:103], v[166:167]
	v_pk_add_f32 v[104:105], v[104:105], v[168:169]
	v_pk_add_f32 v[98:99], v[98:99], v[162:163]
	v_pk_add_f32 v[100:101], v[100:101], v[164:165]
	s_mov_b64 vcc, s[4:5]
	v_cndmask_b32_dpp v174, v106, v110, vcc row_ror:8 row_mask:0xf bank_mask:0xf bound_ctrl:1
	v_cndmask_b32_dpp v175, v107, v111, vcc row_ror:8 row_mask:0xf bank_mask:0xf bound_ctrl:1
	v_cndmask_b32_dpp v176, v108, v112, vcc row_ror:8 row_mask:0xf bank_mask:0xf bound_ctrl:1
	v_cndmask_b32_dpp v177, v109, v113, vcc row_ror:8 row_mask:0xf bank_mask:0xf bound_ctrl:1
	v_cndmask_b32_dpp v166, v98, v102, vcc row_ror:8 row_mask:0xf bank_mask:0xf bound_ctrl:1
	v_cndmask_b32_dpp v167, v99, v103, vcc row_ror:8 row_mask:0xf bank_mask:0xf bound_ctrl:1
	v_cndmask_b32_dpp v168, v100, v104, vcc row_ror:8 row_mask:0xf bank_mask:0xf bound_ctrl:1
	v_cndmask_b32_dpp v169, v101, v105, vcc row_ror:8 row_mask:0xf bank_mask:0xf bound_ctrl:1
	s_not_b64 vcc, s[4:5]
	v_cndmask_b32_dpp v170, v110, v106, vcc row_ror:8 row_mask:0xf bank_mask:0xf bound_ctrl:1
	v_cndmask_b32_dpp v171, v111, v107, vcc row_ror:8 row_mask:0xf bank_mask:0xf bound_ctrl:1
	v_cndmask_b32_dpp v172, v112, v108, vcc row_ror:8 row_mask:0xf bank_mask:0xf bound_ctrl:1
	v_cndmask_b32_dpp v173, v113, v109, vcc row_ror:8 row_mask:0xf bank_mask:0xf bound_ctrl:1
	v_cndmask_b32_dpp v162, v102, v98, vcc row_ror:8 row_mask:0xf bank_mask:0xf bound_ctrl:1
	v_cndmask_b32_dpp v163, v103, v99, vcc row_ror:8 row_mask:0xf bank_mask:0xf bound_ctrl:1
	v_cndmask_b32_dpp v164, v104, v100, vcc row_ror:8 row_mask:0xf bank_mask:0xf bound_ctrl:1
	v_cndmask_b32_dpp v165, v105, v101, vcc row_ror:8 row_mask:0xf bank_mask:0xf bound_ctrl:1
	s_add_u32 s100, s28, 0x10000
	s_addc_u32 s101, s29, 0
	global_store_dwordx4 v186, v[174:177], s[100:101]
	global_store_dwordx4 v187, v[170:173], s[100:101]
	global_store_dwordx4 v186, v[166:169], s[100:101] offset:512
	global_store_dwordx4 v187, v[162:165], s[100:101] offset:512
	s_add_u32 s98, s28, 0x90000
	s_addc_u32 s99, s29, 0
	global_load_dwordx4 v[110:113], v0, s[98:99]
	global_load_dwordx4 v[106:109], v0, s[98:99] offset:64
	global_load_dwordx4 v[102:105], v0, s[98:99] offset:512
	global_load_dwordx4 v[98:101], v0, s[98:99] offset:576
	s_waitcnt vmcnt(20)
	v_pk_add_f32 v[94:95], v[94:95], v[158:159]
	v_pk_add_f32 v[96:97], v[96:97], v[160:161]
	v_pk_add_f32 v[90:91], v[90:91], v[154:155]
	v_pk_add_f32 v[92:93], v[92:93], v[156:157]
	v_pk_add_f32 v[86:87], v[86:87], v[150:151]
	v_pk_add_f32 v[88:89], v[88:89], v[152:153]
	v_pk_add_f32 v[82:83], v[82:83], v[146:147]
	v_pk_add_f32 v[84:85], v[84:85], v[148:149]
	s_mov_b64 vcc, s[4:5]
	v_cndmask_b32_dpp v158, v90, v94, vcc row_ror:8 row_mask:0xf bank_mask:0xf bound_ctrl:1
	v_cndmask_b32_dpp v159, v91, v95, vcc row_ror:8 row_mask:0xf bank_mask:0xf bound_ctrl:1
	v_cndmask_b32_dpp v160, v92, v96, vcc row_ror:8 row_mask:0xf bank_mask:0xf bound_ctrl:1
	v_cndmask_b32_dpp v161, v93, v97, vcc row_ror:8 row_mask:0xf bank_mask:0xf bound_ctrl:1
	v_cndmask_b32_dpp v150, v82, v86, vcc row_ror:8 row_mask:0xf bank_mask:0xf bound_ctrl:1
	v_cndmask_b32_dpp v151, v83, v87, vcc row_ror:8 row_mask:0xf bank_mask:0xf bound_ctrl:1
	v_cndmask_b32_dpp v152, v84, v88, vcc row_ror:8 row_mask:0xf bank_mask:0xf bound_ctrl:1
	v_cndmask_b32_dpp v153, v85, v89, vcc row_ror:8 row_mask:0xf bank_mask:0xf bound_ctrl:1
	s_not_b64 vcc, s[4:5]
	v_cndmask_b32_dpp v154, v94, v90, vcc row_ror:8 row_mask:0xf bank_mask:0xf bound_ctrl:1
	v_cndmask_b32_dpp v155, v95, v91, vcc row_ror:8 row_mask:0xf bank_mask:0xf bound_ctrl:1
	v_cndmask_b32_dpp v156, v96, v92, vcc row_ror:8 row_mask:0xf bank_mask:0xf bound_ctrl:1
	v_cndmask_b32_dpp v157, v97, v93, vcc row_ror:8 row_mask:0xf bank_mask:0xf bound_ctrl:1
	v_cndmask_b32_dpp v146, v86, v82, vcc row_ror:8 row_mask:0xf bank_mask:0xf bound_ctrl:1
	v_cndmask_b32_dpp v147, v87, v83, vcc row_ror:8 row_mask:0xf bank_mask:0xf bound_ctrl:1
	v_cndmask_b32_dpp v148, v88, v84, vcc row_ror:8 row_mask:0xf bank_mask:0xf bound_ctrl:1
	v_cndmask_b32_dpp v149, v89, v85, vcc row_ror:8 row_mask:0xf bank_mask:0xf bound_ctrl:1
	s_add_u32 s100, s28, 0x20000
	s_addc_u32 s101, s29, 0
	global_store_dwordx4 v186, v[158:161], s[100:101]
	global_store_dwordx4 v187, v[154:157], s[100:101]
	global_store_dwordx4 v186, v[150:153], s[100:101] offset:512
	global_store_dwordx4 v187, v[146:149], s[100:101] offset:512
	s_add_u32 s98, s28, 0xa0000
	s_addc_u32 s99, s29, 0
	global_load_dwordx4 v[94:97], v0, s[98:99]
	global_load_dwordx4 v[90:93], v0, s[98:99] offset:64
	global_load_dwordx4 v[86:89], v0, s[98:99] offset:512
	global_load_dwordx4 v[82:85], v0, s[98:99] offset:576
	s_waitcnt vmcnt(24)
; template <int CTRL> DEVI float dpp(float x) { return __builtin_bit_cast(float, __builtin_amdgcn_mov_dpp(__builtin_bit_cast(int, x), CTRL, 0xf, 0xf, true)); }
;     DEVI void operator()(AccRef acc, const pg8::Unit& u, int wr, int wc, int fr, int fq) const {
;     ...
;             for (int m = 0; m < 4; ++m)
; #pragma unroll
;                 for (int bj = 0; bj < 2; ++bj)
; #pragma unroll
;                     for (int n = 0; n < 2; ++n) b[m][bj][n] = *(const f32x4*)((const char*)base + o + (unsigned)(m * 16 * DM * 4 + bj * 512 + n * 64));
; #pragma unroll
;             for (int m = 0; m < 4; ++m)
; #pragma unroll
;                 for (int bj = 0; bj < 2; ++bj) { const f32x4 d0 = b[m][bj][0] + alpha * acc[ai][bj][m][0], d1 = b[m][bj][1] + alpha * acc[ai][bj][m][1];
;                     f32x4 t0, t1;
; #pragma unroll
;                     for (int i = 0; i < 4; ++i) { t0[i] = dpp<0x128>(d0[i]); t1[i] = dpp<0x128>(d1[i]); }
;                     const f32x4 sa = lo ? d0 : t1, sb = lo ? t0 : d1;
;                     const unsigned oo = os + (unsigned)(m * 16 * DM * 4 + bj * 512);
;                     *(f32x4*)((char*)out + oo) = sa; *(f32x4*)((char*)out + oo + 8u * DM * 4u) = sb; }
;             o += 128u * DM * 4u; os += 128u * DM * 4u; }
	v_pk_add_f32 v[78:79], v[78:79], v[134:135]
	v_pk_add_f32 v[80:81], v[80:81], v[136:137]
	v_pk_add_f32 v[74:75], v[74:75], v[130:131]
	v_pk_add_f32 v[76:77], v[76:77], v[132:133]
	v_pk_add_f32 v[70:71], v[70:71], v[126:127]
	v_pk_add_f32 v[72:73], v[72:73], v[128:129]
	v_pk_add_f32 v[66:67], v[66:67], v[122:123]
	v_pk_add_f32 v[68:69], v[68:69], v[124:125]
	s_mov_b64 vcc, s[4:5]
	v_cndmask_b32_dpp v134, v74, v78, vcc row_ror:8 row_mask:0xf bank_mask:0xf bound_ctrl:1
	v_cndmask_b32_dpp v135, v75, v79, vcc row_ror:8 row_mask:0xf bank_mask:0xf bound_ctrl:1
	v_cndmask_b32_dpp v136, v76, v80, vcc row_ror:8 row_mask:0xf bank_mask:0xf bound_ctrl:1
	v_cndmask_b32_dpp v137, v77, v81, vcc row_ror:8 row_mask:0xf bank_mask:0xf bound_ctrl:1
	v_cndmask_b32_dpp v126, v66, v70, vcc row_ror:8 row_mask:0xf bank_mask:0xf bound_ctrl:1
	v_cndmask_b32_dpp v127, v67, v71, vcc row_ror:8 row_mask:0xf bank_mask:0xf bound_ctrl:1
	v_cndmask_b32_dpp v128, v68, v72, vcc row_ror:8 row_mask:0xf bank_mask:0xf bound_ctrl:1
	v_cndmask_b32_dpp v129, v69, v73, vcc row_ror:8 row_mask:0xf bank_mask:0xf bound_ctrl:1
	s_not_b64 vcc, s[4:5]
	v_cndmask_b32_dpp v130, v78, v74, vcc row_ror:8 row_mask:0xf bank_mask:0xf bound_ctrl:1
	v_cndmask_b32_dpp v131, v79, v75, vcc row_ror:8 row_mask:0xf bank_mask:0xf bound_ctrl:1
	v_cndmask_b32_dpp v132, v80, v76, vcc row_ror:8 row_mask:0xf bank_mask:0xf bound_ctrl:1
	v_cndmask_b32_dpp v133, v81, v77, vcc row_ror:8 row_mask:0xf bank_mask:0xf bound_ctrl:1
	v_cndmask_b32_dpp v122, v70, v66, vcc row_ror:8 row_mask:0xf bank_mask:0xf bound_ctrl:1
	v_cndmask_b32_dpp v123, v71, v67, vcc row_ror:8 row_mask:0xf bank_mask:0xf bound_ctrl:1
	v_cndmask_b32_dpp v124, v72, v68, vcc row_ror:8 row_mask:0xf bank_mask:0xf bound_ctrl:1
	v_cndmask_b32_dpp v125, v73, v69, vcc row_ror:8 row_mask:0xf bank_mask:0xf bound_ctrl:1
	s_add_u32 s100, s28, 0x30000
	s_addc_u32 s101, s29, 0
	global_store_dwordx4 v186, v[134:137], s[100:101]
	global_store_dwordx4 v187, v[130:133], s[100:101]
	global_store_dwordx4 v186, v[126:129], s[100:101] offset:512
	global_store_dwordx4 v187, v[122:125], s[100:101] offset:512
	s_add_u32 s98, s28, 0xb0000
	s_addc_u32 s99, s29, 0
	global_load_dwordx4 v[78:81], v0, s[98:99]
	global_load_dwordx4 v[74:77], v0, s[98:99] offset:64
	global_load_dwordx4 v[70:73], v0, s[98:99] offset:512
	global_load_dwordx4 v[66:69], v0, s[98:99] offset:576
	s_waitcnt vmcnt(24)
	v_pk_add_f32 v[62:63], v[62:63], v[142:143]
	v_pk_add_f32 v[64:65], v[64:65], v[144:145]
	v_pk_add_f32 v[58:59], v[58:59], v[138:139]
	v_pk_add_f32 v[60:61], v[60:61], v[140:141]
	v_pk_add_f32 v[54:55], v[54:55], v[118:119]
	v_pk_add_f32 v[56:57], v[56:57], v[120:121]
	v_pk_add_f32 v[50:51], v[50:51], v[114:115]
	v_pk_add_f32 v[52:53], v[52:53], v[116:117]
	s_mov_b64 vcc, s[4:5]
	v_cndmask_b32_dpp v142, v58, v62, vcc row_ror:8 row_mask:0xf bank_mask:0xf bound_ctrl:1
	v_cndmask_b32_dpp v143, v59, v63, vcc row_ror:8 row_mask:0xf bank_mask:0xf bound_ctrl:1
	v_cndmask_b32_dpp v144, v60, v64, vcc row_ror:8 row_mask:0xf bank_mask:0xf bound_ctrl:1
	v_cndmask_b32_dpp v145, v61, v65, vcc row_ror:8 row_mask:0xf bank_mask:0xf bound_ctrl:1
	v_cndmask_b32_dpp v118, v50, v54, vcc row_ror:8 row_mask:0xf bank_mask:0xf bound_ctrl:1
	v_cndmask_b32_dpp v119, v51, v55, vcc row_ror:8 row_mask:0xf bank_mask:0xf bound_ctrl:1
	v_cndmask_b32_dpp v120, v52, v56, vcc row_ror:8 row_mask:0xf bank_mask:0xf bound_ctrl:1
	v_cndmask_b32_dpp v121, v53, v57, vcc row_ror:8 row_mask:0xf bank_mask:0xf bound_ctrl:1
	s_not_b64 vcc, s[4:5]
	v_cndmask_b32_dpp v138, v62, v58, vcc row_ror:8 row_mask:0xf bank_mask:0xf bound_ctrl:1
	v_cndmask_b32_dpp v139, v63, v59, vcc row_ror:8 row_mask:0xf bank_mask:0xf bound_ctrl:1
	v_cndmask_b32_dpp v140, v64, v60, vcc row_ror:8 row_mask:0xf bank_mask:0xf bound_ctrl:1
	v_cndmask_b32_dpp v141, v65, v61, vcc row_ror:8 row_mask:0xf bank_mask:0xf bound_ctrl:1
	v_cndmask_b32_dpp v114, v54, v50, vcc row_ror:8 row_mask:0xf bank_mask:0xf bound_ctrl:1
	v_cndmask_b32_dpp v115, v55, v51, vcc row_ror:8 row_mask:0xf bank_mask:0xf bound_ctrl:1
	v_cndmask_b32_dpp v116, v56, v52, vcc row_ror:8 row_mask:0xf bank_mask:0xf bound_ctrl:1
	v_cndmask_b32_dpp v117, v57, v53, vcc row_ror:8 row_mask:0xf bank_mask:0xf bound_ctrl:1
	s_add_u32 s100, s28, 0x80000
	s_addc_u32 s101, s29, 0
	global_store_dwordx4 v186, v[142:145], s[100:101]
	global_store_dwordx4 v187, v[138:141], s[100:101]
	global_store_dwordx4 v186, v[118:121], s[100:101] offset:512
	global_store_dwordx4 v187, v[114:117], s[100:101] offset:512
	s_waitcnt vmcnt(20)
; template <int CTRL> DEVI float dpp(float x) { return __builtin_bit_cast(float, __builtin_amdgcn_mov_dpp(__builtin_bit_cast(int, x), CTRL, 0xf, 0xf, true)); }
; #define PG8_WAIT_V(n) asm volatile("s_waitcnt vmcnt(" #n ")" ::: "memory")
; #define PG8_BAR __builtin_amdgcn_s_barrier()
; template <class Epi, class Sched>
; __device__ __forceinline__ void gemm_phase(PG8_LAS unsigned char* lds, const Gemm g, const Sched& S, const Epi& E, int wv) {
;     ...
;         if (!has_next) break;
; #pragma unroll
;         for (int a = 0; a < 2; ++a)
; #pragma unroll
;             for (int b = 0; b < 2; ++b)
; #pragma unroll
;                 for (int m = 0; m < 4; ++m)
; #pragma unroll
;                     for (int n = 0; n < 2; ++n) acc[a][b][m][n] = (f32x4){0.f, 0.f, 0.f, 0.f};
;         cur = nxt; cA = nA; cB = nB; ++ui;
;     }
;     PG8_WAIT_V(0);
;     if (wr == 0) PG8_BAR;
;     PG8_BAR;
;     DEVI void operator()(AccRef acc, const pg8::Unit& u, int wr, int wc, int fr, int fq) const {
;     ...
;                     for (int n = 0; n < 2; ++n) b[m][bj][n] = *(const f32x4*)((const char*)base + o + (unsigned)(m * 16 * DM * 4 + bj * 512 + n * 64));
; #pragma unroll
;             for (int m = 0; m < 4; ++m)
; #pragma unroll
;                 for (int bj = 0; bj < 2; ++bj) { const f32x4 d0 = b[m][bj][0] + alpha * acc[ai][bj][m][0], d1 = b[m][bj][1] + alpha * acc[ai][bj][m][1];
;                     f32x4 t0, t1;
; #pragma unroll
;                     for (int i = 0; i < 4; ++i) { t0[i] = dpp<0x128>(d0[i]); t1[i] = dpp<0x128>(d1[i]); }
;                     const f32x4 sa = lo ? d0 : t1, sb = lo ? t0 : d1;
;                     const unsigned oo = os + (unsigned)(m * 16 * DM * 4 + bj * 512);
;                     *(f32x4*)((char*)out + oo) = sa; *(f32x4*)((char*)out + oo + 8u * DM * 4u) = sb; }
;             o += 128u * DM * 4u; os += 128u * DM * 4u; }
	v_pk_add_f32 v[46:47], v[46:47], v[110:111]
	v_pk_add_f32 v[48:49], v[48:49], v[112:113]
	v_pk_add_f32 v[42:43], v[42:43], v[106:107]
	v_pk_add_f32 v[44:45], v[44:45], v[108:109]
	v_pk_add_f32 v[38:39], v[38:39], v[102:103]
	v_pk_add_f32 v[40:41], v[40:41], v[104:105]
	v_pk_add_f32 v[34:35], v[34:35], v[98:99]
	v_pk_add_f32 v[36:37], v[36:37], v[100:101]
	s_mov_b64 vcc, s[4:5]
	v_cndmask_b32_dpp v110, v42, v46, vcc row_ror:8 row_mask:0xf bank_mask:0xf bound_ctrl:1
	v_cndmask_b32_dpp v111, v43, v47, vcc row_ror:8 row_mask:0xf bank_mask:0xf bound_ctrl:1
	v_cndmask_b32_dpp v112, v44, v48, vcc row_ror:8 row_mask:0xf bank_mask:0xf bound_ctrl:1
	v_cndmask_b32_dpp v113, v45, v49, vcc row_ror:8 row_mask:0xf bank_mask:0xf bound_ctrl:1
	v_cndmask_b32_dpp v102, v34, v38, vcc row_ror:8 row_mask:0xf bank_mask:0xf bound_ctrl:1
	v_cndmask_b32_dpp v103, v35, v39, vcc row_ror:8 row_mask:0xf bank_mask:0xf bound_ctrl:1
	v_cndmask_b32_dpp v104, v36, v40, vcc row_ror:8 row_mask:0xf bank_mask:0xf bound_ctrl:1
	v_cndmask_b32_dpp v105, v37, v41, vcc row_ror:8 row_mask:0xf bank_mask:0xf bound_ctrl:1
	s_not_b64 vcc, s[4:5]
	v_cndmask_b32_dpp v106, v46, v42, vcc row_ror:8 row_mask:0xf bank_mask:0xf bound_ctrl:1
	v_cndmask_b32_dpp v107, v47, v43, vcc row_ror:8 row_mask:0xf bank_mask:0xf bound_ctrl:1
	v_cndmask_b32_dpp v108, v48, v44, vcc row_ror:8 row_mask:0xf bank_mask:0xf bound_ctrl:1
	v_cndmask_b32_dpp v109, v49, v45, vcc row_ror:8 row_mask:0xf bank_mask:0xf bound_ctrl:1
	v_cndmask_b32_dpp v98, v38, v34, vcc row_ror:8 row_mask:0xf bank_mask:0xf bound_ctrl:1
	v_cndmask_b32_dpp v99, v39, v35, vcc row_ror:8 row_mask:0xf bank_mask:0xf bound_ctrl:1
	v_cndmask_b32_dpp v100, v40, v36, vcc row_ror:8 row_mask:0xf bank_mask:0xf bound_ctrl:1
	v_cndmask_b32_dpp v101, v41, v37, vcc row_ror:8 row_mask:0xf bank_mask:0xf bound_ctrl:1
	s_add_u32 s100, s28, 0x90000
	s_addc_u32 s101, s29, 0
	global_store_dwordx4 v186, v[110:113], s[100:101]
	global_store_dwordx4 v187, v[106:109], s[100:101]
	global_store_dwordx4 v186, v[102:105], s[100:101] offset:512
	global_store_dwordx4 v187, v[98:101], s[100:101] offset:512
	s_waitcnt vmcnt(16)
	v_pk_add_f32 v[30:31], v[30:31], v[94:95]
	v_pk_add_f32 v[32:33], v[32:33], v[96:97]
	v_pk_add_f32 v[26:27], v[26:27], v[90:91]
	v_pk_add_f32 v[28:29], v[28:29], v[92:93]
	v_pk_add_f32 v[22:23], v[22:23], v[86:87]
	v_pk_add_f32 v[24:25], v[24:25], v[88:89]
	v_pk_add_f32 v[18:19], v[18:19], v[82:83]
	v_pk_add_f32 v[20:21], v[20:21], v[84:85]
	s_mov_b64 vcc, s[4:5]
	v_cndmask_b32_dpp v94, v26, v30, vcc row_ror:8 row_mask:0xf bank_mask:0xf bound_ctrl:1
	v_cndmask_b32_dpp v95, v27, v31, vcc row_ror:8 row_mask:0xf bank_mask:0xf bound_ctrl:1
	v_cndmask_b32_dpp v96, v28, v32, vcc row_ror:8 row_mask:0xf bank_mask:0xf bound_ctrl:1
	v_cndmask_b32_dpp v97, v29, v33, vcc row_ror:8 row_mask:0xf bank_mask:0xf bound_ctrl:1
	v_cndmask_b32_dpp v86, v18, v22, vcc row_ror:8 row_mask:0xf bank_mask:0xf bound_ctrl:1
	v_cndmask_b32_dpp v87, v19, v23, vcc row_ror:8 row_mask:0xf bank_mask:0xf bound_ctrl:1
	v_cndmask_b32_dpp v88, v20, v24, vcc row_ror:8 row_mask:0xf bank_mask:0xf bound_ctrl:1
	v_cndmask_b32_dpp v89, v21, v25, vcc row_ror:8 row_mask:0xf bank_mask:0xf bound_ctrl:1
	s_not_b64 vcc, s[4:5]
	v_cndmask_b32_dpp v90, v30, v26, vcc row_ror:8 row_mask:0xf bank_mask:0xf bound_ctrl:1
	v_cndmask_b32_dpp v91, v31, v27, vcc row_ror:8 row_mask:0xf bank_mask:0xf bound_ctrl:1
	v_cndmask_b32_dpp v92, v32, v28, vcc row_ror:8 row_mask:0xf bank_mask:0xf bound_ctrl:1
	v_cndmask_b32_dpp v93, v33, v29, vcc row_ror:8 row_mask:0xf bank_mask:0xf bound_ctrl:1
	v_cndmask_b32_dpp v82, v22, v18, vcc row_ror:8 row_mask:0xf bank_mask:0xf bound_ctrl:1
	v_cndmask_b32_dpp v83, v23, v19, vcc row_ror:8 row_mask:0xf bank_mask:0xf bound_ctrl:1
	v_cndmask_b32_dpp v84, v24, v20, vcc row_ror:8 row_mask:0xf bank_mask:0xf bound_ctrl:1
	v_cndmask_b32_dpp v85, v25, v21, vcc row_ror:8 row_mask:0xf bank_mask:0xf bound_ctrl:1
	s_add_u32 s100, s28, 0xa0000
	s_addc_u32 s101, s29, 0
	global_store_dwordx4 v186, v[94:97], s[100:101]
	global_store_dwordx4 v187, v[90:93], s[100:101]
	global_store_dwordx4 v186, v[86:89], s[100:101] offset:512
	global_store_dwordx4 v187, v[82:85], s[100:101] offset:512
	s_waitcnt vmcnt(12)
	v_pk_add_f32 v[14:15], v[14:15], v[78:79]
	v_pk_add_f32 v[16:17], v[16:17], v[80:81]
	v_pk_add_f32 v[10:11], v[10:11], v[74:75]
	v_pk_add_f32 v[12:13], v[12:13], v[76:77]
	v_pk_add_f32 v[6:7], v[6:7], v[70:71]
	v_pk_add_f32 v[8:9], v[8:9], v[72:73]
	v_pk_add_f32 v[2:3], v[2:3], v[66:67]
	v_pk_add_f32 v[4:5], v[4:5], v[68:69]
	s_mov_b64 vcc, s[4:5]
	v_cndmask_b32_dpp v78, v10, v14, vcc row_ror:8 row_mask:0xf bank_mask:0xf bound_ctrl:1
	v_cndmask_b32_dpp v79, v11, v15, vcc row_ror:8 row_mask:0xf bank_mask:0xf bound_ctrl:1
	v_cndmask_b32_dpp v80, v12, v16, vcc row_ror:8 row_mask:0xf bank_mask:0xf bound_ctrl:1
	v_cndmask_b32_dpp v81, v13, v17, vcc row_ror:8 row_mask:0xf bank_mask:0xf bound_ctrl:1
	v_cndmask_b32_dpp v70, v2, v6, vcc row_ror:8 row_mask:0xf bank_mask:0xf bound_ctrl:1
	v_cndmask_b32_dpp v71, v3, v7, vcc row_ror:8 row_mask:0xf bank_mask:0xf bound_ctrl:1
	v_cndmask_b32_dpp v72, v4, v8, vcc row_ror:8 row_mask:0xf bank_mask:0xf bound_ctrl:1
	v_cndmask_b32_dpp v73, v5, v9, vcc row_ror:8 row_mask:0xf bank_mask:0xf bound_ctrl:1
	s_not_b64 vcc, s[4:5]
	v_cndmask_b32_dpp v74, v14, v10, vcc row_ror:8 row_mask:0xf bank_mask:0xf bound_ctrl:1
	v_cndmask_b32_dpp v75, v15, v11, vcc row_ror:8 row_mask:0xf bank_mask:0xf bound_ctrl:1
	v_cndmask_b32_dpp v76, v16, v12, vcc row_ror:8 row_mask:0xf bank_mask:0xf bound_ctrl:1
	v_cndmask_b32_dpp v77, v17, v13, vcc row_ror:8 row_mask:0xf bank_mask:0xf bound_ctrl:1
	v_cndmask_b32_dpp v66, v6, v2, vcc row_ror:8 row_mask:0xf bank_mask:0xf bound_ctrl:1
	v_cndmask_b32_dpp v67, v7, v3, vcc row_ror:8 row_mask:0xf bank_mask:0xf bound_ctrl:1
	v_cndmask_b32_dpp v68, v8, v4, vcc row_ror:8 row_mask:0xf bank_mask:0xf bound_ctrl:1
	v_cndmask_b32_dpp v69, v9, v5, vcc row_ror:8 row_mask:0xf bank_mask:0xf bound_ctrl:1
	s_add_u32 s100, s28, 0xb0000
	s_addc_u32 s101, s29, 0
	global_store_dwordx4 v186, v[78:81], s[100:101]
	global_store_dwordx4 v187, v[74:77], s[100:101]
	global_store_dwordx4 v186, v[70:73], s[100:101] offset:512
	global_store_dwordx4 v187, v[66:69], s[100:101] offset:512
	s_and_b64 vcc, exec, s[6:7]
	s_cbranch_vccz .LBB0_35
	s_waitcnt vmcnt(0)
	s_cmpk_gt_u32 s13, 0xff
	s_cbranch_scc1 .LBB0_46
	s_barrier

.LBB0_63:
	s_add_i32 s96, s96, 2
	s_cmp_gt_u32 s96, 15
	s_cselect_b32 s97, 0x13fff800, 0
	s_cmp_gt_u32 s96, 13
	s_cselect_b32 s86, 0x13fff800, 0
	s_add_u32 s86, s86, s84
	s_addc_u32 s87, 0, s85
	s_add_u32 s86, s82, s86
	s_addc_u32 s87, s83, s87
	s_add_u32 s86, s86, 0x100
	s_addc_u32 s87, s87, 0
	s_add_u32 vcc_lo, s94, s84
	s_addc_u32 vcc_hi, s95, s85
	s_add_i32 s13, 0, 0x10000
	v_add_u32_e32 v0, s13, v202
	ds_read_b128 v[132:135], v0
	ds_read_b128 v[136:139], v0 offset:1024
	ds_read_b128 v[140:143], v0 offset:2048
	ds_read_b128 v[144:147], v0 offset:3072
	s_cmpk_eq_i32 s84, 0xf00
	s_cselect_b32 s89, s25, s87
	s_cselect_b32 s88, s92, s86
	s_cselect_b32 s87, s23, vcc_hi
	s_cselect_b32 s86, s93, vcc_lo
	s_add_u32 vcc_lo, s97, s84
	s_addc_u32 vcc_hi, 0, s85
	v_lshl_add_u64 v[2:3], v[200:201], 0, vcc
	s_add_i32 m0, s59, 0xc000
	ds_read_b128 v[148:151], v204
	ds_read_b128 v[152:155], v204 offset:1024
	ds_read_b128 v[156:159], v204 offset:2048
	ds_read_b128 v[160:163], v204 offset:3072
	ds_read_b128 v[164:167], v204 offset:4096
	ds_read_b128 v[168:171], v204 offset:5120
	ds_read_b128 v[172:175], v204 offset:6144
	ds_read_b128 v[176:179], v204 offset:7168
	global_load_lds_dwordx4 v[2:3], off
	v_lshl_add_u64 v[2:3], v[194:195], 0, vcc
	s_add_i32 m0, s59, 0xe000
	s_nop 0
	global_load_lds_dwordx4 v[2:3], off
	s_waitcnt lgkmcnt(8)
	s_setprio 1
	s_barrier
	s_waitcnt lgkmcnt(0)
	v_mfma_f32_16x16x32_bf16 v[128:131], v[132:135], v[148:151], v[128:131]
	v_mfma_f32_16x16x32_bf16 v[124:127], v[140:143], v[148:151], v[124:127]
	v_mfma_f32_16x16x32_bf16 v[112:115], v[132:135], v[156:159], v[112:115]
	v_mfma_f32_16x16x32_bf16 v[108:111], v[140:143], v[156:159], v[108:111]
	v_mfma_f32_16x16x32_bf16 v[96:99], v[132:135], v[164:167], v[96:99]
	v_mfma_f32_16x16x32_bf16 v[92:95], v[140:143], v[164:167], v[92:95]
	v_mfma_f32_16x16x32_bf16 v[80:83], v[132:135], v[172:175], v[80:83]
	v_mfma_f32_16x16x32_bf16 v[76:79], v[140:143], v[172:175], v[76:79]
	v_mfma_f32_16x16x32_bf16 v[128:131], v[136:139], v[152:155], v[128:131]
	v_mfma_f32_16x16x32_bf16 v[124:127], v[144:147], v[152:155], v[124:127]
	v_mfma_f32_16x16x32_bf16 v[112:115], v[136:139], v[160:163], v[112:115]
	v_mfma_f32_16x16x32_bf16 v[108:111], v[144:147], v[160:163], v[108:111]
	v_mfma_f32_16x16x32_bf16 v[96:99], v[136:139], v[168:171], v[96:99]
	v_mfma_f32_16x16x32_bf16 v[92:95], v[144:147], v[168:171], v[92:95]
	v_mfma_f32_16x16x32_bf16 v[80:83], v[136:139], v[176:179], v[80:83]
	v_mfma_f32_16x16x32_bf16 v[76:79], v[144:147], v[176:179], v[76:79]
	s_setprio 0
	s_barrier
	s_add_i32 s97, 0, 0x14000
	s_add_i32 s13, s13, s46
	v_add_u32_e32 v0, s97, v202
	v_lshl_add_u64 v[214:215], s[86:87], 0, v[184:185]
	s_mov_b32 m0, s13
	ds_read_b128 v[196:199], v0
	ds_read_b128 v[206:209], v0 offset:1024
	ds_read_b128 v[210:213], v0 offset:2048
	ds_read_b128 v[218:221], v0 offset:3072
	global_load_lds_dwordx4 v[214:215], off
	v_lshl_add_u64 v[222:223], s[86:87], 0, v[180:181]
	s_add_i32 m0, s13, 0x2000
	s_nop 0
	global_load_lds_dwordx4 v[222:223], off
	s_setprio 1
	s_barrier
	s_waitcnt lgkmcnt(0)
	v_mfma_f32_16x16x32_bf16 v[120:123], v[196:199], v[148:151], v[120:123]
	v_mfma_f32_16x16x32_bf16 v[116:119], v[210:213], v[148:151], v[116:119]
	v_mfma_f32_16x16x32_bf16 v[104:107], v[196:199], v[156:159], v[104:107]
	v_mfma_f32_16x16x32_bf16 v[100:103], v[210:213], v[156:159], v[100:103]
	v_mfma_f32_16x16x32_bf16 v[88:91], v[196:199], v[164:167], v[88:91]
	v_mfma_f32_16x16x32_bf16 v[84:87], v[210:213], v[164:167], v[84:87]
	v_mfma_f32_16x16x32_bf16 v[72:75], v[196:199], v[172:175], v[72:75]
	v_mfma_f32_16x16x32_bf16 v[68:71], v[210:213], v[172:175], v[68:71]
	v_mfma_f32_16x16x32_bf16 v[120:123], v[206:209], v[152:155], v[120:123]
	v_mfma_f32_16x16x32_bf16 v[116:119], v[218:221], v[152:155], v[116:119]
	v_mfma_f32_16x16x32_bf16 v[104:107], v[206:209], v[160:163], v[104:107]
	v_mfma_f32_16x16x32_bf16 v[100:103], v[218:221], v[160:163], v[100:103]
	v_mfma_f32_16x16x32_bf16 v[88:91], v[206:209], v[168:171], v[88:91]
	v_mfma_f32_16x16x32_bf16 v[84:87], v[218:221], v[168:171], v[84:87]
	v_mfma_f32_16x16x32_bf16 v[72:75], v[206:209], v[176:179], v[72:75]
	v_mfma_f32_16x16x32_bf16 v[68:71], v[218:221], v[176:179], v[68:71]
	s_setprio 0
	s_mov_b32 m0, s59
	v_lshl_add_u64 v[224:225], s[88:89], 0, v[186:187]
	s_barrier
	ds_read_b128 v[148:151], v204 offset:16384
	ds_read_b128 v[152:155], v204 offset:17408
	ds_read_b128 v[156:159], v204 offset:18432
	ds_read_b128 v[160:163], v204 offset:19456
	ds_read_b128 v[164:167], v204 offset:20480
	ds_read_b128 v[168:171], v204 offset:21504
	ds_read_b128 v[172:175], v204 offset:22528
	ds_read_b128 v[176:179], v204 offset:23552
	global_load_lds_dwordx4 v[224:225], off
	v_lshl_add_u64 v[226:227], s[88:89], 0, v[182:183]
	s_mov_b32 m0, s60
	s_nop 0
	global_load_lds_dwordx4 v[226:227], off
	s_setprio 1
	s_barrier
	s_waitcnt lgkmcnt(0)
	v_mfma_f32_16x16x32_bf16 v[64:67], v[132:135], v[148:151], v[64:67]
	v_mfma_f32_16x16x32_bf16 v[60:63], v[140:143], v[148:151], v[60:63]
	v_mfma_f32_16x16x32_bf16 v[48:51], v[132:135], v[156:159], v[48:51]
	v_mfma_f32_16x16x32_bf16 v[44:47], v[140:143], v[156:159], v[44:47]
	v_mfma_f32_16x16x32_bf16 v[32:35], v[132:135], v[164:167], v[32:35]
	v_mfma_f32_16x16x32_bf16 v[28:31], v[140:143], v[164:167], v[28:31]
	v_mfma_f32_16x16x32_bf16 v[16:19], v[132:135], v[172:175], v[16:19]
	v_mfma_f32_16x16x32_bf16 v[12:15], v[140:143], v[172:175], v[12:15]
	v_mfma_f32_16x16x32_bf16 v[64:67], v[136:139], v[152:155], v[64:67]
	v_mfma_f32_16x16x32_bf16 v[60:63], v[144:147], v[152:155], v[60:63]
	v_mfma_f32_16x16x32_bf16 v[48:51], v[136:139], v[160:163], v[48:51]
	v_mfma_f32_16x16x32_bf16 v[44:47], v[144:147], v[160:163], v[44:47]
	v_mfma_f32_16x16x32_bf16 v[32:35], v[136:139], v[168:171], v[32:35]
	v_mfma_f32_16x16x32_bf16 v[28:31], v[144:147], v[168:171], v[28:31]
	v_mfma_f32_16x16x32_bf16 v[16:19], v[136:139], v[176:179], v[16:19]
	v_mfma_f32_16x16x32_bf16 v[12:15], v[144:147], v[176:179], v[12:15]
	s_setprio 0
	s_barrier
	s_add_u32 vcc_lo, s86, 0x80000
	s_addc_u32 vcc_hi, s87, 0
	s_add_i32 s13, s97, s46
	v_lshl_add_u64 v[2:3], vcc, 0, v[184:185]
	s_mov_b32 m0, s13
	s_nop 0
	global_load_lds_dwordx4 v[2:3], off
	v_lshl_add_u64 v[2:3], vcc, 0, v[180:181]
	s_add_i32 m0, s13, 0x2000
	s_nop 0
	global_load_lds_dwordx4 v[2:3], off
	s_waitcnt vmcnt(6)
	s_setprio 1
	s_barrier
	v_mfma_f32_16x16x32_bf16 v[56:59], v[196:199], v[148:151], v[56:59]
	v_mfma_f32_16x16x32_bf16 v[52:55], v[210:213], v[148:151], v[52:55]
	v_mfma_f32_16x16x32_bf16 v[40:43], v[196:199], v[156:159], v[40:43]
	v_mfma_f32_16x16x32_bf16 v[36:39], v[210:213], v[156:159], v[36:39]
	v_mfma_f32_16x16x32_bf16 v[24:27], v[196:199], v[164:167], v[24:27]
	v_mfma_f32_16x16x32_bf16 v[20:23], v[210:213], v[164:167], v[20:23]
	v_mfma_f32_16x16x32_bf16 v[8:11], v[196:199], v[172:175], v[8:11]
	v_mfma_f32_16x16x32_bf16 v[2:5], v[210:213], v[172:175], v[4:7]
	v_mfma_f32_16x16x32_bf16 v[56:59], v[206:209], v[152:155], v[56:59]
	v_mfma_f32_16x16x32_bf16 v[52:55], v[218:221], v[152:155], v[52:55]
	v_mfma_f32_16x16x32_bf16 v[40:43], v[206:209], v[160:163], v[40:43]
	v_mfma_f32_16x16x32_bf16 v[36:39], v[218:221], v[160:163], v[36:39]
	v_mfma_f32_16x16x32_bf16 v[24:27], v[206:209], v[168:171], v[24:27]
	v_mfma_f32_16x16x32_bf16 v[20:23], v[218:221], v[168:171], v[20:23]
	v_mfma_f32_16x16x32_bf16 v[8:11], v[206:209], v[176:179], v[8:11]
	v_mfma_f32_16x16x32_bf16 v[2:5], v[218:221], v[176:179], v[2:5]
	s_setprio 0
	s_add_i32 s13, 0, 0x18000
	v_add_u32_e32 v0, s13, v202
	s_barrier
	ds_read_b128 v[132:135], v0
	ds_read_b128 v[136:139], v0 offset:1024
	ds_read_b128 v[140:143], v0 offset:2048
	ds_read_b128 v[144:147], v0 offset:3072
	s_add_u32 s88, s88, 0x40000
	s_addc_u32 s89, s89, 0
	s_mov_b32 m0, s61
	v_lshl_add_u64 v[6:7], s[88:89], 0, v[186:187]
	ds_read_b128 v[148:151], v204 offset:32768
	ds_read_b128 v[152:155], v204 offset:33792
	ds_read_b128 v[156:159], v204 offset:34816
	ds_read_b128 v[160:163], v204 offset:35840
	ds_read_b128 v[164:167], v204 offset:36864
	ds_read_b128 v[168:171], v204 offset:37888
	ds_read_b128 v[172:175], v204 offset:38912
	ds_read_b128 v[176:179], v204 offset:39936
	global_load_lds_dwordx4 v[6:7], off
	v_lshl_add_u64 v[6:7], s[88:89], 0, v[182:183]
	s_mov_b32 m0, s76
	s_nop 0
	global_load_lds_dwordx4 v[6:7], off
	s_waitcnt lgkmcnt(8)
	s_setprio 1
	s_barrier
	s_waitcnt lgkmcnt(0)
	v_mfma_f32_16x16x32_bf16 v[128:131], v[132:135], v[148:151], v[128:131]
	v_mfma_f32_16x16x32_bf16 v[124:127], v[140:143], v[148:151], v[124:127]
	v_mfma_f32_16x16x32_bf16 v[112:115], v[132:135], v[156:159], v[112:115]
	v_mfma_f32_16x16x32_bf16 v[108:111], v[140:143], v[156:159], v[108:111]
	v_mfma_f32_16x16x32_bf16 v[96:99], v[132:135], v[164:167], v[96:99]
	v_mfma_f32_16x16x32_bf16 v[92:95], v[140:143], v[164:167], v[92:95]
	v_mfma_f32_16x16x32_bf16 v[80:83], v[132:135], v[172:175], v[80:83]
	v_mfma_f32_16x16x32_bf16 v[76:79], v[140:143], v[172:175], v[76:79]
	v_mfma_f32_16x16x32_bf16 v[128:131], v[136:139], v[152:155], v[128:131]
	v_mfma_f32_16x16x32_bf16 v[124:127], v[144:147], v[152:155], v[124:127]
	v_mfma_f32_16x16x32_bf16 v[112:115], v[136:139], v[160:163], v[112:115]
	v_mfma_f32_16x16x32_bf16 v[108:111], v[144:147], v[160:163], v[108:111]
	v_mfma_f32_16x16x32_bf16 v[96:99], v[136:139], v[168:171], v[96:99]
	v_mfma_f32_16x16x32_bf16 v[92:95], v[144:147], v[168:171], v[92:95]
	v_mfma_f32_16x16x32_bf16 v[80:83], v[136:139], v[176:179], v[80:83]
	v_mfma_f32_16x16x32_bf16 v[76:79], v[144:147], v[176:179], v[76:79]
	s_setprio 0
	s_barrier
	s_add_i32 s88, 0, 0x1c000
	s_add_i32 s13, s13, s46
	v_add_u32_e32 v0, s88, v202
	v_lshl_add_u64 v[6:7], v[214:215], 0, s[48:49]
	s_mov_b32 m0, s13
	ds_read_b128 v[196:199], v0
	ds_read_b128 v[206:209], v0 offset:1024
	ds_read_b128 v[210:213], v0 offset:2048
	ds_read_b128 v[218:221], v0 offset:3072
	global_load_lds_dwordx4 v[6:7], off
	v_lshl_add_u64 v[6:7], v[222:223], 0, s[48:49]
	s_add_i32 m0, s13, 0x2000
	s_nop 0
	global_load_lds_dwordx4 v[6:7], off
	s_setprio 1
	s_barrier
	s_waitcnt lgkmcnt(0)
	v_mfma_f32_16x16x32_bf16 v[120:123], v[196:199], v[148:151], v[120:123]
	v_mfma_f32_16x16x32_bf16 v[116:119], v[210:213], v[148:151], v[116:119]
	v_mfma_f32_16x16x32_bf16 v[104:107], v[196:199], v[156:159], v[104:107]
	v_mfma_f32_16x16x32_bf16 v[100:103], v[210:213], v[156:159], v[100:103]
	v_mfma_f32_16x16x32_bf16 v[88:91], v[196:199], v[164:167], v[88:91]
	v_mfma_f32_16x16x32_bf16 v[84:87], v[210:213], v[164:167], v[84:87]
	v_mfma_f32_16x16x32_bf16 v[72:75], v[196:199], v[172:175], v[72:75]
	v_mfma_f32_16x16x32_bf16 v[68:71], v[210:213], v[172:175], v[68:71]
	v_mfma_f32_16x16x32_bf16 v[120:123], v[206:209], v[152:155], v[120:123]
	v_mfma_f32_16x16x32_bf16 v[116:119], v[218:221], v[152:155], v[116:119]
	v_mfma_f32_16x16x32_bf16 v[104:107], v[206:209], v[160:163], v[104:107]
	v_mfma_f32_16x16x32_bf16 v[100:103], v[218:221], v[160:163], v[100:103]
	v_mfma_f32_16x16x32_bf16 v[88:91], v[206:209], v[168:171], v[88:91]
	v_mfma_f32_16x16x32_bf16 v[84:87], v[218:221], v[168:171], v[84:87]
	v_mfma_f32_16x16x32_bf16 v[72:75], v[206:209], v[176:179], v[72:75]
	v_mfma_f32_16x16x32_bf16 v[68:71], v[218:221], v[176:179], v[68:71]
	s_setprio 0
	s_mov_b32 m0, s77
	v_lshl_add_u64 v[6:7], v[224:225], 0, s[48:49]
	s_barrier
	ds_read_b128 v[148:151], v204 offset:49152
	ds_read_b128 v[152:155], v204 offset:50176
	ds_read_b128 v[156:159], v204 offset:51200
	ds_read_b128 v[160:163], v204 offset:52224
	ds_read_b128 v[164:167], v204 offset:53248
	ds_read_b128 v[168:171], v204 offset:54272
	ds_read_b128 v[172:175], v204 offset:55296
	ds_read_b128 v[176:179], v204 offset:56320
	global_load_lds_dwordx4 v[6:7], off
	v_lshl_add_u64 v[6:7], v[226:227], 0, s[48:49]
	s_mov_b32 m0, s90
	s_nop 0
	global_load_lds_dwordx4 v[6:7], off
	s_setprio 1
	s_barrier
	s_waitcnt lgkmcnt(0)
	v_mfma_f32_16x16x32_bf16 v[64:67], v[132:135], v[148:151], v[64:67]
	v_mfma_f32_16x16x32_bf16 v[60:63], v[140:143], v[148:151], v[60:63]
	v_mfma_f32_16x16x32_bf16 v[48:51], v[132:135], v[156:159], v[48:51]
	v_mfma_f32_16x16x32_bf16 v[44:47], v[140:143], v[156:159], v[44:47]
	v_mfma_f32_16x16x32_bf16 v[32:35], v[132:135], v[164:167], v[32:35]
	v_mfma_f32_16x16x32_bf16 v[28:31], v[140:143], v[164:167], v[28:31]
	v_mfma_f32_16x16x32_bf16 v[16:19], v[132:135], v[172:175], v[16:19]
	v_mfma_f32_16x16x32_bf16 v[12:15], v[140:143], v[172:175], v[12:15]
	v_mfma_f32_16x16x32_bf16 v[64:67], v[136:139], v[152:155], v[64:67]
	v_mfma_f32_16x16x32_bf16 v[60:63], v[144:147], v[152:155], v[60:63]
	v_mfma_f32_16x16x32_bf16 v[48:51], v[136:139], v[160:163], v[48:51]
	v_mfma_f32_16x16x32_bf16 v[44:47], v[144:147], v[160:163], v[44:47]
	v_mfma_f32_16x16x32_bf16 v[32:35], v[136:139], v[168:171], v[32:35]
	v_mfma_f32_16x16x32_bf16 v[28:31], v[144:147], v[168:171], v[28:31]
	v_mfma_f32_16x16x32_bf16 v[16:19], v[136:139], v[176:179], v[16:19]
	v_mfma_f32_16x16x32_bf16 v[12:15], v[144:147], v[176:179], v[12:15]
	s_setprio 0
	s_barrier
	s_add_u32 s86, s86, 0x80080
	s_addc_u32 s87, s87, 0
	s_add_i32 s13, s88, s46
	v_lshl_add_u64 v[6:7], s[86:87], 0, v[184:185]
	s_mov_b32 m0, s13
	s_nop 0
	global_load_lds_dwordx4 v[6:7], off
	v_lshl_add_u64 v[6:7], s[86:87], 0, v[180:181]
	s_add_i32 m0, s13, 0x2000
	s_nop 0
	global_load_lds_dwordx4 v[6:7], off
	s_waitcnt vmcnt(6)
	s_setprio 1
	s_barrier
	v_mfma_f32_16x16x32_bf16 v[56:59], v[196:199], v[148:151], v[56:59]
	v_mfma_f32_16x16x32_bf16 v[52:55], v[210:213], v[148:151], v[52:55]
	v_mfma_f32_16x16x32_bf16 v[40:43], v[196:199], v[156:159], v[40:43]
	v_mfma_f32_16x16x32_bf16 v[36:39], v[210:213], v[156:159], v[36:39]
	v_mfma_f32_16x16x32_bf16 v[24:27], v[196:199], v[164:167], v[24:27]
	v_mfma_f32_16x16x32_bf16 v[20:23], v[210:213], v[164:167], v[20:23]
	v_mfma_f32_16x16x32_bf16 v[6:9], v[196:199], v[172:175], v[8:11]
	v_mfma_f32_16x16x32_bf16 v[2:5], v[210:213], v[172:175], v[2:5]
	v_mfma_f32_16x16x32_bf16 v[56:59], v[206:209], v[152:155], v[56:59]
	v_mfma_f32_16x16x32_bf16 v[52:55], v[218:221], v[152:155], v[52:55]
	v_mfma_f32_16x16x32_bf16 v[40:43], v[206:209], v[160:163], v[40:43]
	v_mfma_f32_16x16x32_bf16 v[36:39], v[218:221], v[160:163], v[36:39]
	v_mfma_f32_16x16x32_bf16 v[24:27], v[206:209], v[168:171], v[24:27]
	v_mfma_f32_16x16x32_bf16 v[20:23], v[218:221], v[168:171], v[20:23]
	v_mfma_f32_16x16x32_bf16 v[8:11], v[206:209], v[176:179], v[6:9]
	v_mfma_f32_16x16x32_bf16 v[4:7], v[218:221], v[176:179], v[2:5]
	s_setprio 0
	s_add_u32 s84, s84, 0x100
	s_addc_u32 s85, 0, s85
	s_cmp_gt_u32 s96, 29
	s_barrier
	s_cbranch_scc1 .LBB0_55

.LBB0_409:
	s_add_u32 s8, s84, 0xfffc0080
	s_addc_u32 s9, s85, -1
	s_add_i32 s10, 0, 0x10000
	v_add_u32_e32 v0, s10, v159
	ds_read_b128 v[142:145], v0
	ds_read_b128 v[146:149], v0 offset:1024
	ds_read_b128 v[150:153], v0 offset:2048
	ds_read_b128 v[154:157], v0 offset:3072
	s_cmp_eq_u32 s46, 12
	s_cselect_b32 s89, s23, s9
	s_cselect_b32 s88, s60, s8
	s_cselect_b32 s87, s21, vcc_hi
	s_cselect_b32 s86, s61, vcc_lo
	v_lshl_add_u64 v[196:197], s[84:85], 0, v[140:141]
	s_add_i32 m0, s25, 0xc000
	ds_read_b128 v[180:183], v177
	ds_read_b128 v[184:187], v177 offset:1024
	ds_read_b128 v[188:191], v177 offset:2048
	ds_read_b128 v[192:195], v177 offset:3072
	ds_read_b128 v[200:203], v177 offset:4096
	ds_read_b128 v[204:207], v177 offset:5120
	ds_read_b128 v[208:211], v177 offset:6144
	ds_read_b128 v[212:215], v177 offset:7168
	global_load_lds_dwordx4 v[196:197], off
	v_lshl_add_u64 v[196:197], s[84:85], 0, v[138:139]
	s_add_i32 m0, s25, 0xe000
	s_nop 0
	global_load_lds_dwordx4 v[196:197], off
	s_waitcnt lgkmcnt(8)
	s_setprio 1
	s_barrier
	s_waitcnt lgkmcnt(0)
	v_mfma_f32_16x16x32_bf16 v[126:129], v[142:145], v[180:183], v[126:129]
	v_mfma_f32_16x16x32_bf16 v[118:121], v[150:153], v[180:183], v[118:121]
	v_mfma_f32_16x16x32_bf16 v[122:125], v[142:145], v[188:191], v[122:125]
	v_mfma_f32_16x16x32_bf16 v[110:113], v[150:153], v[188:191], v[110:113]
	v_mfma_f32_16x16x32_bf16 v[114:117], v[142:145], v[200:203], v[114:117]
	v_mfma_f32_16x16x32_bf16 v[102:105], v[150:153], v[200:203], v[102:105]
	v_mfma_f32_16x16x32_bf16 v[106:109], v[142:145], v[208:211], v[106:109]
	v_mfma_f32_16x16x32_bf16 v[98:101], v[150:153], v[208:211], v[98:101]
	v_mfma_f32_16x16x32_bf16 v[126:129], v[146:149], v[184:187], v[126:129]
	v_mfma_f32_16x16x32_bf16 v[118:121], v[154:157], v[184:187], v[118:121]
	v_mfma_f32_16x16x32_bf16 v[122:125], v[146:149], v[192:195], v[122:125]
	v_mfma_f32_16x16x32_bf16 v[110:113], v[154:157], v[192:195], v[110:113]
	v_mfma_f32_16x16x32_bf16 v[114:117], v[146:149], v[204:207], v[114:117]
	v_mfma_f32_16x16x32_bf16 v[102:105], v[154:157], v[204:207], v[102:105]
	v_mfma_f32_16x16x32_bf16 v[106:109], v[146:149], v[212:215], v[106:109]
	v_mfma_f32_16x16x32_bf16 v[98:101], v[154:157], v[212:215], v[98:101]
	s_setprio 0
	s_barrier
	s_add_i32 s11, 0, 0x14000
	s_add_i32 s8, s10, s59
	v_add_u32_e32 v0, s11, v159
	v_lshl_add_u64 v[196:197], s[86:87], 0, v[132:133]
	s_mov_b32 m0, s8
	ds_read_b128 v[218:221], v0
	ds_read_b128 v[222:225], v0 offset:1024
	ds_read_b128 v[226:229], v0 offset:2048
	ds_read_b128 v[230:233], v0 offset:3072
	global_load_lds_dwordx4 v[196:197], off
	v_lshl_add_u64 v[198:199], s[86:87], 0, v[136:137]
	s_add_i32 m0, s8, 0x2000
	s_nop 0
	global_load_lds_dwordx4 v[198:199], off
	s_setprio 1
	s_barrier
	s_waitcnt lgkmcnt(0)
	v_mfma_f32_16x16x32_bf16 v[62:65], v[218:221], v[180:183], v[62:65]
	v_mfma_f32_16x16x32_bf16 v[54:57], v[226:229], v[180:183], v[54:57]
	v_mfma_f32_16x16x32_bf16 v[58:61], v[218:221], v[188:191], v[58:61]
	v_mfma_f32_16x16x32_bf16 v[46:49], v[226:229], v[188:191], v[46:49]
	v_mfma_f32_16x16x32_bf16 v[50:53], v[218:221], v[200:203], v[50:53]
	v_mfma_f32_16x16x32_bf16 v[38:41], v[226:229], v[200:203], v[38:41]
	v_mfma_f32_16x16x32_bf16 v[42:45], v[218:221], v[208:211], v[42:45]
	v_mfma_f32_16x16x32_bf16 v[34:37], v[226:229], v[208:211], v[34:37]
	v_mfma_f32_16x16x32_bf16 v[62:65], v[222:225], v[184:187], v[62:65]
	v_mfma_f32_16x16x32_bf16 v[54:57], v[230:233], v[184:187], v[54:57]
	v_mfma_f32_16x16x32_bf16 v[58:61], v[222:225], v[192:195], v[58:61]
	v_mfma_f32_16x16x32_bf16 v[46:49], v[230:233], v[192:195], v[46:49]
	v_mfma_f32_16x16x32_bf16 v[50:53], v[222:225], v[204:207], v[50:53]
	v_mfma_f32_16x16x32_bf16 v[38:41], v[230:233], v[204:207], v[38:41]
	v_mfma_f32_16x16x32_bf16 v[42:45], v[222:225], v[212:215], v[42:45]
	v_mfma_f32_16x16x32_bf16 v[34:37], v[230:233], v[212:215], v[34:37]
	s_setprio 0
	s_mov_b32 m0, s25
	v_lshl_add_u64 v[234:235], s[88:89], 0, v[130:131]
	s_barrier
	ds_read_b128 v[180:183], v177 offset:16384
	ds_read_b128 v[184:187], v177 offset:17408
	ds_read_b128 v[188:191], v177 offset:18432
	ds_read_b128 v[192:195], v177 offset:19456
	ds_read_b128 v[200:203], v177 offset:20480
	ds_read_b128 v[204:207], v177 offset:21504
	ds_read_b128 v[208:211], v177 offset:22528
	ds_read_b128 v[212:215], v177 offset:23552
	global_load_lds_dwordx4 v[234:235], off
	v_lshl_add_u64 v[236:237], s[88:89], 0, v[134:135]
	s_mov_b32 m0, s76
	s_nop 0
	global_load_lds_dwordx4 v[236:237], off
	s_setprio 1
	s_barrier
	s_waitcnt lgkmcnt(0)
	v_mfma_f32_16x16x32_bf16 v[94:97], v[142:145], v[180:183], v[94:97]
	v_mfma_f32_16x16x32_bf16 v[86:89], v[150:153], v[180:183], v[86:89]
	v_mfma_f32_16x16x32_bf16 v[90:93], v[142:145], v[188:191], v[90:93]
	v_mfma_f32_16x16x32_bf16 v[78:81], v[150:153], v[188:191], v[78:81]
	v_mfma_f32_16x16x32_bf16 v[82:85], v[142:145], v[200:203], v[82:85]
	v_mfma_f32_16x16x32_bf16 v[70:73], v[150:153], v[200:203], v[70:73]
	v_mfma_f32_16x16x32_bf16 v[74:77], v[142:145], v[208:211], v[74:77]
	v_mfma_f32_16x16x32_bf16 v[66:69], v[150:153], v[208:211], v[66:69]
	v_mfma_f32_16x16x32_bf16 v[94:97], v[146:149], v[184:187], v[94:97]
	v_mfma_f32_16x16x32_bf16 v[86:89], v[154:157], v[184:187], v[86:89]
	v_mfma_f32_16x16x32_bf16 v[90:93], v[146:149], v[192:195], v[90:93]
	v_mfma_f32_16x16x32_bf16 v[78:81], v[154:157], v[192:195], v[78:81]
	v_mfma_f32_16x16x32_bf16 v[82:85], v[146:149], v[204:207], v[82:85]
	v_mfma_f32_16x16x32_bf16 v[70:73], v[154:157], v[204:207], v[70:73]
	v_mfma_f32_16x16x32_bf16 v[74:77], v[146:149], v[212:215], v[74:77]
	v_mfma_f32_16x16x32_bf16 v[66:69], v[154:157], v[212:215], v[66:69]
	s_setprio 0
	s_barrier
	s_add_u32 s8, s86, 0x40000
	s_addc_u32 s9, s87, 0
	s_add_i32 s10, s11, s59
	v_lshl_add_u64 v[142:143], s[8:9], 0, v[132:133]
	s_mov_b32 m0, s10
	s_nop 0
	global_load_lds_dwordx4 v[142:143], off
	v_lshl_add_u64 v[142:143], s[8:9], 0, v[136:137]
	s_add_i32 m0, s10, 0x2000
	s_nop 0
	global_load_lds_dwordx4 v[142:143], off
	s_waitcnt vmcnt(6)
	s_setprio 1
	s_barrier
	v_mfma_f32_16x16x32_bf16 v[30:33], v[218:221], v[180:183], v[30:33]
	v_mfma_f32_16x16x32_bf16 v[22:25], v[226:229], v[180:183], v[22:25]
	v_mfma_f32_16x16x32_bf16 v[26:29], v[218:221], v[188:191], v[26:29]
	v_mfma_f32_16x16x32_bf16 v[14:17], v[226:229], v[188:191], v[14:17]
	v_mfma_f32_16x16x32_bf16 v[18:21], v[218:221], v[200:203], v[18:21]
	v_mfma_f32_16x16x32_bf16 v[6:9], v[226:229], v[200:203], v[6:9]
	v_mfma_f32_16x16x32_bf16 v[10:13], v[218:221], v[208:211], v[10:13]
	v_mfma_f32_16x16x32_bf16 v[2:5], v[226:229], v[208:211], v[2:5]
	v_mfma_f32_16x16x32_bf16 v[30:33], v[222:225], v[184:187], v[30:33]
	v_mfma_f32_16x16x32_bf16 v[22:25], v[230:233], v[184:187], v[22:25]
	v_mfma_f32_16x16x32_bf16 v[26:29], v[222:225], v[192:195], v[26:29]
	v_mfma_f32_16x16x32_bf16 v[14:17], v[230:233], v[192:195], v[14:17]
	v_mfma_f32_16x16x32_bf16 v[18:21], v[222:225], v[204:207], v[18:21]
	v_mfma_f32_16x16x32_bf16 v[6:9], v[230:233], v[204:207], v[6:9]
	v_mfma_f32_16x16x32_bf16 v[10:13], v[222:225], v[212:215], v[10:13]
	v_mfma_f32_16x16x32_bf16 v[2:5], v[230:233], v[212:215], v[2:5]
	s_setprio 0
	s_add_i32 s10, 0, 0x18000
	v_add_u32_e32 v0, s10, v159
	s_barrier
	ds_read_b128 v[142:145], v0
	ds_read_b128 v[146:149], v0 offset:1024
	ds_read_b128 v[150:153], v0 offset:2048
	ds_read_b128 v[154:157], v0 offset:3072
	s_add_u32 s8, s88, 0x40000
	s_addc_u32 s9, s89, 0
	s_mov_b32 m0, s79
	v_lshl_add_u64 v[218:219], s[8:9], 0, v[130:131]
	ds_read_b128 v[180:183], v177 offset:32768
	ds_read_b128 v[184:187], v177 offset:33792
	ds_read_b128 v[188:191], v177 offset:34816
	ds_read_b128 v[192:195], v177 offset:35840
	ds_read_b128 v[200:203], v177 offset:36864
	ds_read_b128 v[204:207], v177 offset:37888
	ds_read_b128 v[208:211], v177 offset:38912
	ds_read_b128 v[212:215], v177 offset:39936
	global_load_lds_dwordx4 v[218:219], off
	v_lshl_add_u64 v[218:219], s[8:9], 0, v[134:135]
	s_mov_b32 m0, s93
	s_nop 0
	global_load_lds_dwordx4 v[218:219], off
	s_waitcnt lgkmcnt(8)
	s_setprio 1
	s_barrier
	s_waitcnt lgkmcnt(0)
	v_mfma_f32_16x16x32_bf16 v[126:129], v[142:145], v[180:183], v[126:129]
	v_mfma_f32_16x16x32_bf16 v[118:121], v[150:153], v[180:183], v[118:121]
	v_mfma_f32_16x16x32_bf16 v[122:125], v[142:145], v[188:191], v[122:125]
	v_mfma_f32_16x16x32_bf16 v[110:113], v[150:153], v[188:191], v[110:113]
	v_mfma_f32_16x16x32_bf16 v[114:117], v[142:145], v[200:203], v[114:117]
	v_mfma_f32_16x16x32_bf16 v[102:105], v[150:153], v[200:203], v[102:105]
	v_mfma_f32_16x16x32_bf16 v[106:109], v[142:145], v[208:211], v[106:109]
	v_mfma_f32_16x16x32_bf16 v[98:101], v[150:153], v[208:211], v[98:101]
	v_mfma_f32_16x16x32_bf16 v[126:129], v[146:149], v[184:187], v[126:129]
	v_mfma_f32_16x16x32_bf16 v[118:121], v[154:157], v[184:187], v[118:121]
	v_mfma_f32_16x16x32_bf16 v[122:125], v[146:149], v[192:195], v[122:125]
	v_mfma_f32_16x16x32_bf16 v[110:113], v[154:157], v[192:195], v[110:113]
	v_mfma_f32_16x16x32_bf16 v[114:117], v[146:149], v[204:207], v[114:117]
	v_mfma_f32_16x16x32_bf16 v[102:105], v[154:157], v[204:207], v[102:105]
	v_mfma_f32_16x16x32_bf16 v[106:109], v[146:149], v[212:215], v[106:109]
	v_mfma_f32_16x16x32_bf16 v[98:101], v[154:157], v[212:215], v[98:101]
	s_setprio 0
	s_barrier
	s_add_i32 s11, 0, 0x1c000
	s_add_i32 s8, s10, s59
	v_add_u32_e32 v0, s11, v159
	v_lshl_add_u64 v[196:197], v[196:197], 0, s[48:49]
	s_mov_b32 m0, s8
	ds_read_b128 v[218:221], v0
	ds_read_b128 v[222:225], v0 offset:1024
	ds_read_b128 v[226:229], v0 offset:2048
	ds_read_b128 v[230:233], v0 offset:3072
	global_load_lds_dwordx4 v[196:197], off
	v_lshl_add_u64 v[196:197], v[198:199], 0, s[48:49]
	s_add_i32 m0, s8, 0x2000
	s_nop 0
	global_load_lds_dwordx4 v[196:197], off
	s_setprio 1
	s_barrier
	s_waitcnt lgkmcnt(0)
	v_mfma_f32_16x16x32_bf16 v[62:65], v[218:221], v[180:183], v[62:65]
	v_mfma_f32_16x16x32_bf16 v[54:57], v[226:229], v[180:183], v[54:57]
	v_mfma_f32_16x16x32_bf16 v[58:61], v[218:221], v[188:191], v[58:61]
	v_mfma_f32_16x16x32_bf16 v[46:49], v[226:229], v[188:191], v[46:49]
	v_mfma_f32_16x16x32_bf16 v[50:53], v[218:221], v[200:203], v[50:53]
	v_mfma_f32_16x16x32_bf16 v[38:41], v[226:229], v[200:203], v[38:41]
	v_mfma_f32_16x16x32_bf16 v[42:45], v[218:221], v[208:211], v[42:45]
	v_mfma_f32_16x16x32_bf16 v[34:37], v[226:229], v[208:211], v[34:37]
	v_mfma_f32_16x16x32_bf16 v[62:65], v[222:225], v[184:187], v[62:65]
	v_mfma_f32_16x16x32_bf16 v[54:57], v[230:233], v[184:187], v[54:57]
	v_mfma_f32_16x16x32_bf16 v[58:61], v[222:225], v[192:195], v[58:61]
	v_mfma_f32_16x16x32_bf16 v[46:49], v[230:233], v[192:195], v[46:49]
	v_mfma_f32_16x16x32_bf16 v[50:53], v[222:225], v[204:207], v[50:53]
	v_mfma_f32_16x16x32_bf16 v[38:41], v[230:233], v[204:207], v[38:41]
	v_mfma_f32_16x16x32_bf16 v[42:45], v[222:225], v[212:215], v[42:45]
	v_mfma_f32_16x16x32_bf16 v[34:37], v[230:233], v[212:215], v[34:37]
	s_setprio 0
	s_mov_b32 m0, s94
	v_lshl_add_u64 v[196:197], v[234:235], 0, s[48:49]
	s_barrier
	ds_read_b128 v[180:183], v177 offset:49152
	ds_read_b128 v[184:187], v177 offset:50176
	ds_read_b128 v[188:191], v177 offset:51200
	ds_read_b128 v[192:195], v177 offset:52224
	ds_read_b128 v[200:203], v177 offset:53248
	ds_read_b128 v[204:207], v177 offset:54272
	ds_read_b128 v[208:211], v177 offset:55296
	ds_read_b128 v[212:215], v177 offset:56320
	global_load_lds_dwordx4 v[196:197], off
	v_lshl_add_u64 v[196:197], v[236:237], 0, s[48:49]
	s_mov_b32 m0, s95
	s_nop 0
	global_load_lds_dwordx4 v[196:197], off
	s_setprio 1
	s_barrier
;     DEVI void operator()(AccRef acc, const pg8::Unit& u, int wr, int wc, int fr, int fq) const {
;         const int sel = u.pn >> 2; bf16_t* dst = (bf16_t*)(ws + (size_t)(sel + 1) * UNIT);
;         const int row0 = u.pm * 256 + wr * 64 + fr, col0 = (u.pn & 3) * 256 + wc * 32 + 8 * fq, bcol0 = u.pn * 256 + wc * 32 + 8 * fq + (u.pn >= 12 ? 8 : 0);
; #pragma unroll
;         for (int bj = 0; bj < 2; ++bj)
; #pragma unroll
;             for (int n = 0; n < 2; ++n) { const f32x4 bv = *(const f32x4*)(bias + bcol0 + bj * 128 + n * 4);
; #pragma unroll
;                 for (int ai = 0; ai < 2; ++ai)
; #pragma unroll
;                     for (int m = 0; m < 4; ++m) acc[ai][bj][m][n] += bv; }
;         if (u.pn < 8) {
	s_waitcnt lgkmcnt(0)
	v_mfma_f32_16x16x32_bf16 v[94:97], v[142:145], v[180:183], v[94:97]
	v_mfma_f32_16x16x32_bf16 v[86:89], v[150:153], v[180:183], v[86:89]
	v_mfma_f32_16x16x32_bf16 v[90:93], v[142:145], v[188:191], v[90:93]
	v_mfma_f32_16x16x32_bf16 v[78:81], v[150:153], v[188:191], v[78:81]
	v_mfma_f32_16x16x32_bf16 v[82:85], v[142:145], v[200:203], v[82:85]
	v_mfma_f32_16x16x32_bf16 v[70:73], v[150:153], v[200:203], v[70:73]
	v_mfma_f32_16x16x32_bf16 v[74:77], v[142:145], v[208:211], v[74:77]
	v_mfma_f32_16x16x32_bf16 v[66:69], v[150:153], v[208:211], v[66:69]
	v_mfma_f32_16x16x32_bf16 v[94:97], v[146:149], v[184:187], v[94:97]
	v_mfma_f32_16x16x32_bf16 v[86:89], v[154:157], v[184:187], v[86:89]
	v_mfma_f32_16x16x32_bf16 v[90:93], v[146:149], v[192:195], v[90:93]
	v_mfma_f32_16x16x32_bf16 v[78:81], v[154:157], v[192:195], v[78:81]
	v_mfma_f32_16x16x32_bf16 v[82:85], v[146:149], v[204:207], v[82:85]
	v_mfma_f32_16x16x32_bf16 v[70:73], v[154:157], v[204:207], v[70:73]
	v_mfma_f32_16x16x32_bf16 v[74:77], v[146:149], v[212:215], v[74:77]
	v_mfma_f32_16x16x32_bf16 v[66:69], v[154:157], v[212:215], v[66:69]
	s_setprio 0
	s_barrier
	s_add_u32 s8, s86, 0x40080
	s_addc_u32 s9, s87, 0
	s_add_i32 s10, s11, s59
	v_lshl_add_u64 v[142:143], s[8:9], 0, v[132:133]
	s_mov_b32 m0, s10
	s_nop 0
	global_load_lds_dwordx4 v[142:143], off
	v_lshl_add_u64 v[142:143], s[8:9], 0, v[136:137]
	s_add_i32 m0, s10, 0x2000
	s_nop 0
	global_load_lds_dwordx4 v[142:143], off
	s_waitcnt vmcnt(6)
	s_setprio 1
	s_barrier
	v_mfma_f32_16x16x32_bf16 v[30:33], v[218:221], v[180:183], v[30:33]
	v_mfma_f32_16x16x32_bf16 v[22:25], v[226:229], v[180:183], v[22:25]
	v_mfma_f32_16x16x32_bf16 v[26:29], v[218:221], v[188:191], v[26:29]
	v_mfma_f32_16x16x32_bf16 v[14:17], v[226:229], v[188:191], v[14:17]
	v_mfma_f32_16x16x32_bf16 v[18:21], v[218:221], v[200:203], v[18:21]
	v_mfma_f32_16x16x32_bf16 v[6:9], v[226:229], v[200:203], v[6:9]
	v_mfma_f32_16x16x32_bf16 v[10:13], v[218:221], v[208:211], v[10:13]
	v_mfma_f32_16x16x32_bf16 v[2:5], v[226:229], v[208:211], v[2:5]
	v_mfma_f32_16x16x32_bf16 v[30:33], v[222:225], v[184:187], v[30:33]
	v_mfma_f32_16x16x32_bf16 v[22:25], v[230:233], v[184:187], v[22:25]
	v_mfma_f32_16x16x32_bf16 v[26:29], v[222:225], v[192:195], v[26:29]
	v_mfma_f32_16x16x32_bf16 v[14:17], v[230:233], v[192:195], v[14:17]
	v_mfma_f32_16x16x32_bf16 v[18:21], v[222:225], v[204:207], v[18:21]
	v_mfma_f32_16x16x32_bf16 v[6:9], v[230:233], v[204:207], v[6:9]
	v_mfma_f32_16x16x32_bf16 v[10:13], v[222:225], v[212:215], v[10:13]
	v_mfma_f32_16x16x32_bf16 v[2:5], v[230:233], v[212:215], v[2:5]
	s_setprio 0
	s_add_i32 s46, s46, 2
	s_add_u32 vcc_lo, vcc_lo, 0x100
	s_addc_u32 vcc_hi, vcc_hi, 0
	s_add_u32 s84, s84, 0x100
	s_addc_u32 s85, s85, 0
	s_cmp_gt_u32 s46, 13
	s_barrier
	s_cbranch_scc0 .LBB0_409
	s_lshl_b32 s21, s24, 8
	s_cmp_gt_i32 s24, 11
	s_cselect_b32 s8, 8, 0
	v_or_b32_e32 v0, s21, v160
	v_add_u32_e32 v142, s8, v0
	v_ashrrev_i32_e32 v143, 31, v142
	v_lshl_add_u64 v[146:147], v[142:143], 2, s[16:17]
	global_load_dwordx4 v[148:151], v[146:147], off offset:16
	global_load_dwordx4 v[142:145], v[146:147], off
	global_load_dwordx4 v[238:241], v[146:147], off offset:528
	global_load_dwordx4 v[242:245], v[146:147], off offset:512
	s_cmp_gt_i32 s24, 7
	s_waitcnt vmcnt(0)
	v_pk_add_f32 v[128:129], v[128:129], v[144:145]
	v_pk_add_f32 v[126:127], v[126:127], v[142:143]
	v_pk_add_f32 v[124:125], v[124:125], v[144:145]
	v_pk_add_f32 v[122:123], v[122:123], v[142:143]
	v_pk_add_f32 v[116:117], v[116:117], v[144:145]
	v_pk_add_f32 v[114:115], v[114:115], v[142:143]
	v_pk_add_f32 v[108:109], v[108:109], v[144:145]
	v_pk_add_f32 v[106:107], v[106:107], v[142:143]
	v_pk_add_f32 v[96:97], v[96:97], v[144:145]
	v_pk_add_f32 v[94:95], v[94:95], v[142:143]
	v_pk_add_f32 v[92:93], v[92:93], v[144:145]
	v_pk_add_f32 v[90:91], v[90:91], v[142:143]
	v_pk_add_f32 v[84:85], v[84:85], v[144:145]
	v_pk_add_f32 v[82:83], v[82:83], v[142:143]
	v_pk_add_f32 v[76:77], v[76:77], v[144:145]
	v_pk_add_f32 v[74:75], v[74:75], v[142:143]
	v_pk_add_f32 v[142:143], v[120:121], v[150:151]
	v_pk_add_f32 v[144:145], v[118:119], v[148:149]
	v_pk_add_f32 v[118:119], v[112:113], v[150:151]
	v_pk_add_f32 v[120:121], v[110:111], v[148:149]
	v_pk_add_f32 v[110:111], v[104:105], v[150:151]
	v_pk_add_f32 v[112:113], v[102:103], v[148:149]
	v_pk_add_f32 v[102:103], v[100:101], v[150:151]
	v_pk_add_f32 v[104:105], v[98:99], v[148:149]
	v_pk_add_f32 v[98:99], v[88:89], v[150:151]
	v_pk_add_f32 v[100:101], v[86:87], v[148:149]
	v_pk_add_f32 v[86:87], v[80:81], v[150:151]
	v_pk_add_f32 v[88:89], v[78:79], v[148:149]
	v_pk_add_f32 v[78:79], v[72:73], v[150:151]
	v_pk_add_f32 v[80:81], v[70:71], v[148:149]
	v_pk_add_f32 v[70:71], v[68:69], v[150:151]
	v_pk_add_f32 v[72:73], v[66:67], v[148:149]
	v_pk_add_f32 v[154:155], v[56:57], v[240:241]
	v_pk_add_f32 v[150:151], v[64:65], v[244:245]
	v_pk_add_f32 v[152:153], v[62:63], v[242:243]
	v_pk_add_f32 v[62:63], v[60:61], v[244:245]
	v_pk_add_f32 v[64:65], v[58:59], v[242:243]
	v_pk_add_f32 v[58:59], v[52:53], v[244:245]
	v_pk_add_f32 v[60:61], v[50:51], v[242:243]
	v_pk_add_f32 v[50:51], v[44:45], v[244:245]
	v_pk_add_f32 v[52:53], v[42:43], v[242:243]
	v_pk_add_f32 v[42:43], v[32:33], v[244:245]
	v_pk_add_f32 v[44:45], v[30:31], v[242:243]
	v_pk_add_f32 v[30:31], v[28:29], v[244:245]
	v_pk_add_f32 v[32:33], v[26:27], v[242:243]
	v_pk_add_f32 v[26:27], v[20:21], v[244:245]
	v_pk_add_f32 v[28:29], v[18:19], v[242:243]
	v_pk_add_f32 v[18:19], v[12:13], v[244:245]
	v_pk_add_f32 v[20:21], v[10:11], v[242:243]
	v_pk_add_f32 v[156:157], v[54:55], v[238:239]
	v_pk_add_f32 v[146:147], v[48:49], v[240:241]
	v_pk_add_f32 v[148:149], v[46:47], v[238:239]
	v_pk_add_f32 v[54:55], v[40:41], v[240:241]
	v_pk_add_f32 v[56:57], v[38:39], v[238:239]
	v_pk_add_f32 v[46:47], v[36:37], v[240:241]
	v_pk_add_f32 v[48:49], v[34:35], v[238:239]
	v_pk_add_f32 v[38:39], v[24:25], v[240:241]
	v_pk_add_f32 v[40:41], v[22:23], v[238:239]
	v_pk_add_f32 v[34:35], v[16:17], v[240:241]
	v_pk_add_f32 v[36:37], v[14:15], v[238:239]
	v_pk_add_f32 v[22:23], v[8:9], v[240:241]
	v_pk_add_f32 v[24:25], v[6:7], v[238:239]
	v_pk_add_f32 v[14:15], v[4:5], v[240:241]
	v_pk_add_f32 v[16:17], v[2:3], v[238:239]
	s_cbranch_scc1 .LBB0_405
;     DEVI void operator()(AccRef acc, const pg8::Unit& u, int wr, int wc, int fr, int fq) const {
;     ...
;                     for (int bj = 0; bj < 2; ++bj) { const f32x4 a = acc[ai][bj][m][0], b = acc[ai][bj][m][1];
;                         float s = (a[0] * a[0] + a[1] * a[1]) + (a[2] * a[2] + a[3] * a[3]) + (b[0] * b[0] + b[1] * b[1]) + (b[2] * b[2] + b[3] * b[3]);
;                         s = xrow16_sum(s);
;                         if (fq == 0) Pt[((ai * 128 + wr * 64 + m * 16 + fr) * 2 + bj) * 4 + wc] = s; }
	v_mul_f32_e32 v0, v127, v127
	v_mul_f32_e32 v2, v129, v129
	v_fmac_f32_e32 v0, v126, v126
	v_fmac_f32_e32 v2, v128, v128
	v_add_f32_e32 v0, v0, v2
	v_mul_f32_e32 v2, v145, v145
	v_fmac_f32_e32 v2, v144, v144
	v_add_f32_e32 v0, v0, v2
	v_mul_f32_e32 v2, v143, v143
	v_fmac_f32_e32 v2, v142, v142
	v_add_f32_e32 v0, v2, v0
	v_mov_b32_e32 v2, v0
	s_nop 1
	v_permlane16_swap_b32_e32 v0, v2
	v_add_f32_e32 v0, v0, v2
	v_mov_b32_e32 v2, v0
	s_nop 1
	v_permlane32_swap_b32_e32 v0, v2
	s_and_saveexec_b64 s[60:61], s[4:5]
	v_add_f32_e32 v0, v0, v2
	ds_write_b32 v162, v0
	s_or_b64 exec, exec, s[60:61]
	v_mul_f32_e32 v0, v153, v153
	v_mul_f32_e32 v2, v151, v151
	v_fmac_f32_e32 v0, v152, v152
	v_fmac_f32_e32 v2, v150, v150
	v_add_f32_e32 v0, v0, v2
	v_mul_f32_e32 v2, v157, v157
	v_fmac_f32_e32 v2, v156, v156
	v_add_f32_e32 v0, v2, v0
	v_mul_f32_e32 v2, v155, v155
	v_fmac_f32_e32 v2, v154, v154
	v_add_f32_e32 v0, v2, v0
	v_mov_b32_e32 v2, v0
	s_nop 1
	v_permlane16_swap_b32_e32 v0, v2
	v_add_f32_e32 v0, v0, v2
	v_mov_b32_e32 v2, v0
	s_nop 1
	v_permlane32_swap_b32_e32 v0, v2
	s_and_saveexec_b64 s[60:61], s[4:5]
	v_add_f32_e32 v0, v0, v2
	ds_write_b32 v162, v0 offset:16
	s_or_b64 exec, exec, s[60:61]
	v_mul_f32_e32 v0, v123, v123
	v_mul_f32_e32 v2, v125, v125
	v_fmac_f32_e32 v0, v122, v122
	v_fmac_f32_e32 v2, v124, v124
	v_add_f32_e32 v0, v0, v2
	v_mul_f32_e32 v2, v121, v121
	v_fmac_f32_e32 v2, v120, v120
	v_add_f32_e32 v0, v0, v2
	v_mul_f32_e32 v2, v119, v119
	v_fmac_f32_e32 v2, v118, v118
	v_add_f32_e32 v0, v2, v0
	v_mov_b32_e32 v2, v0
	s_nop 1
	v_permlane16_swap_b32_e32 v0, v2
	v_add_f32_e32 v0, v0, v2
	v_mov_b32_e32 v2, v0
	s_nop 1
	v_permlane32_swap_b32_e32 v0, v2
	s_and_saveexec_b64 s[60:61], s[4:5]
	v_add_f32_e32 v0, v0, v2
	ds_write_b32 v163, v0
	s_or_b64 exec, exec, s[60:61]
	v_mul_f32_e32 v0, v65, v65
	v_mul_f32_e32 v2, v63, v63
	v_fmac_f32_e32 v0, v64, v64
	v_fmac_f32_e32 v2, v62, v62
	v_add_f32_e32 v0, v0, v2
	v_mul_f32_e32 v2, v149, v149
	v_fmac_f32_e32 v2, v148, v148
	v_add_f32_e32 v0, v0, v2
	v_mul_f32_e32 v2, v147, v147
	v_fmac_f32_e32 v2, v146, v146
	v_add_f32_e32 v0, v2, v0
	v_mov_b32_e32 v2, v0
	s_nop 1
	v_permlane16_swap_b32_e32 v0, v2
	v_add_f32_e32 v0, v0, v2
	v_mov_b32_e32 v2, v0
	s_nop 1
	v_permlane32_swap_b32_e32 v0, v2
	s_and_saveexec_b64 s[60:61], s[4:5]
	v_add_f32_e32 v0, v0, v2
	ds_write_b32 v163, v0 offset:16
	s_or_b64 exec, exec, s[60:61]
	v_mul_f32_e32 v0, v115, v115
	v_mul_f32_e32 v2, v117, v117
	v_fmac_f32_e32 v0, v114, v114
	v_fmac_f32_e32 v2, v116, v116
	v_add_f32_e32 v0, v0, v2
	v_mul_f32_e32 v2, v113, v113
	v_fmac_f32_e32 v2, v112, v112
	v_add_f32_e32 v0, v0, v2
	v_mul_f32_e32 v2, v111, v111
	v_fmac_f32_e32 v2, v110, v110
	v_add_f32_e32 v0, v2, v0
	v_mov_b32_e32 v2, v0
	s_nop 1
	v_permlane16_swap_b32_e32 v0, v2
	v_add_f32_e32 v0, v0, v2
	v_mov_b32_e32 v2, v0
	s_nop 1
	v_permlane32_swap_b32_e32 v0, v2
	s_and_saveexec_b64 s[60:61], s[4:5]
	v_add_f32_e32 v0, v0, v2
	ds_write_b32 v164, v0
	s_or_b64 exec, exec, s[60:61]
	v_mul_f32_e32 v0, v61, v61
	v_mul_f32_e32 v2, v59, v59
	v_fmac_f32_e32 v0, v60, v60
	v_fmac_f32_e32 v2, v58, v58
	v_add_f32_e32 v0, v0, v2
	v_mul_f32_e32 v2, v57, v57
	v_fmac_f32_e32 v2, v56, v56
	v_add_f32_e32 v0, v0, v2
	v_mul_f32_e32 v2, v55, v55
	v_fmac_f32_e32 v2, v54, v54
	v_add_f32_e32 v0, v2, v0
	v_mov_b32_e32 v2, v0
	s_nop 1
	v_permlane16_swap_b32_e32 v0, v2
	v_add_f32_e32 v0, v0, v2
	v_mov_b32_e32 v2, v0
	s_nop 1
	v_permlane32_swap_b32_e32 v0, v2
	s_and_saveexec_b64 s[60:61], s[4:5]
	v_add_f32_e32 v0, v0, v2
	ds_write_b32 v164, v0 offset:16
	s_or_b64 exec, exec, s[60:61]
	v_mul_f32_e32 v0, v107, v107
	v_mul_f32_e32 v2, v109, v109
	v_fmac_f32_e32 v0, v106, v106
	v_fmac_f32_e32 v2, v108, v108
	v_add_f32_e32 v0, v0, v2
	v_mul_f32_e32 v2, v105, v105
	v_fmac_f32_e32 v2, v104, v104
	v_add_f32_e32 v0, v0, v2
	v_mul_f32_e32 v2, v103, v103
	v_fmac_f32_e32 v2, v102, v102
	v_add_f32_e32 v0, v2, v0
	v_mov_b32_e32 v2, v0
	s_nop 1
	v_permlane16_swap_b32_e32 v0, v2
	v_add_f32_e32 v0, v0, v2
	v_mov_b32_e32 v2, v0
	s_nop 1
	v_permlane32_swap_b32_e32 v0, v2
	s_and_saveexec_b64 s[60:61], s[4:5]
	v_add_f32_e32 v0, v0, v2
	ds_write_b32 v165, v0
	s_or_b64 exec, exec, s[60:61]
	v_mul_f32_e32 v0, v53, v53
	v_mul_f32_e32 v2, v51, v51
	v_fmac_f32_e32 v0, v52, v52
	v_fmac_f32_e32 v2, v50, v50
	v_add_f32_e32 v0, v0, v2
	v_mul_f32_e32 v2, v49, v49
	v_fmac_f32_e32 v2, v48, v48
	v_add_f32_e32 v0, v0, v2
	v_mul_f32_e32 v2, v47, v47
	v_fmac_f32_e32 v2, v46, v46
	v_add_f32_e32 v0, v2, v0
	v_mov_b32_e32 v2, v0
	s_nop 1
	v_permlane16_swap_b32_e32 v0, v2
	v_add_f32_e32 v0, v0, v2
	v_mov_b32_e32 v2, v0
	s_nop 1
	v_permlane32_swap_b32_e32 v0, v2
	s_and_saveexec_b64 s[60:61], s[4:5]
	v_add_f32_e32 v0, v0, v2
	ds_write_b32 v165, v0 offset:16
;     DEVI void operator()(AccRef acc, const pg8::Unit& u, int wr, int wc, int fr, int fq) const {
;     ...
;                     for (int bj = 0; bj < 2; ++bj) { const f32x4 a = acc[ai][bj][m][0], b = acc[ai][bj][m][1];
;                         float s = (a[0] * a[0] + a[1] * a[1]) + (a[2] * a[2] + a[3] * a[3]) + (b[0] * b[0] + b[1] * b[1]) + (b[2] * b[2] + b[3] * b[3]);
;                         s = xrow16_sum(s);
;                         if (fq == 0) Pt[((ai * 128 + wr * 64 + m * 16 + fr) * 2 + bj) * 4 + wc] = s; }
	s_or_b64 exec, exec, s[60:61]
	v_mul_f32_e32 v0, v95, v95
	v_mul_f32_e32 v2, v97, v97
	v_fmac_f32_e32 v0, v94, v94
	v_fmac_f32_e32 v2, v96, v96
	v_add_f32_e32 v0, v0, v2
	v_mul_f32_e32 v2, v101, v101
	v_fmac_f32_e32 v2, v100, v100
	v_add_f32_e32 v0, v0, v2
	v_mul_f32_e32 v2, v99, v99
	v_fmac_f32_e32 v2, v98, v98
	v_add_f32_e32 v0, v2, v0
	v_mov_b32_e32 v2, v0
	s_nop 1
	v_permlane16_swap_b32_e32 v0, v2
	v_add_f32_e32 v0, v0, v2
	v_mov_b32_e32 v2, v0
	s_nop 1
	v_permlane32_swap_b32_e32 v0, v2
	s_and_saveexec_b64 s[60:61], s[4:5]
	v_add_f32_e32 v0, v0, v2
	ds_write_b32 v166, v0
	s_or_b64 exec, exec, s[60:61]
	v_mul_f32_e32 v0, v45, v45
	v_mul_f32_e32 v2, v43, v43
	v_fmac_f32_e32 v0, v44, v44
	v_fmac_f32_e32 v2, v42, v42
	v_add_f32_e32 v0, v0, v2
	v_mul_f32_e32 v2, v41, v41
	v_fmac_f32_e32 v2, v40, v40
	v_add_f32_e32 v0, v0, v2
	v_mul_f32_e32 v2, v39, v39
	v_fmac_f32_e32 v2, v38, v38
	v_add_f32_e32 v0, v2, v0
	v_mov_b32_e32 v2, v0
	s_nop 1
	v_permlane16_swap_b32_e32 v0, v2
	v_add_f32_e32 v0, v0, v2
	v_mov_b32_e32 v2, v0
	s_nop 1
	v_permlane32_swap_b32_e32 v0, v2
	s_and_saveexec_b64 s[60:61], s[4:5]
	v_add_f32_e32 v0, v0, v2
	ds_write_b32 v166, v0 offset:16
	s_or_b64 exec, exec, s[60:61]
	v_mul_f32_e32 v0, v91, v91
	v_mul_f32_e32 v2, v93, v93
	v_fmac_f32_e32 v0, v90, v90
	v_fmac_f32_e32 v2, v92, v92
	v_add_f32_e32 v0, v0, v2
	v_mul_f32_e32 v2, v89, v89
	v_fmac_f32_e32 v2, v88, v88
	v_add_f32_e32 v0, v0, v2
	v_mul_f32_e32 v2, v87, v87
	v_fmac_f32_e32 v2, v86, v86
	v_add_f32_e32 v0, v2, v0
	v_mov_b32_e32 v2, v0
	s_nop 1
	v_permlane16_swap_b32_e32 v0, v2
	v_add_f32_e32 v0, v0, v2
	v_mov_b32_e32 v2, v0
	s_nop 1
	v_permlane32_swap_b32_e32 v0, v2
	s_and_saveexec_b64 s[60:61], s[4:5]
	v_add_f32_e32 v0, v0, v2
	ds_write_b32 v167, v0
	s_or_b64 exec, exec, s[60:61]
	v_mul_f32_e32 v0, v33, v33
	v_mul_f32_e32 v2, v31, v31
	v_fmac_f32_e32 v0, v32, v32
	v_fmac_f32_e32 v2, v30, v30
	v_add_f32_e32 v0, v0, v2
	v_mul_f32_e32 v2, v37, v37
	v_fmac_f32_e32 v2, v36, v36
	v_add_f32_e32 v0, v0, v2
	v_mul_f32_e32 v2, v35, v35
	v_fmac_f32_e32 v2, v34, v34
	v_add_f32_e32 v0, v2, v0
	v_mov_b32_e32 v2, v0
	s_nop 1
	v_permlane16_swap_b32_e32 v0, v2
	v_add_f32_e32 v0, v0, v2
	v_mov_b32_e32 v2, v0
	s_nop 1
	v_permlane32_swap_b32_e32 v0, v2
	s_and_saveexec_b64 s[60:61], s[4:5]
	v_add_f32_e32 v0, v0, v2
	ds_write_b32 v167, v0 offset:16
	s_or_b64 exec, exec, s[60:61]
	v_mul_f32_e32 v0, v83, v83
	v_mul_f32_e32 v2, v85, v85
	v_fmac_f32_e32 v0, v82, v82
	v_fmac_f32_e32 v2, v84, v84
	v_add_f32_e32 v0, v0, v2
	v_mul_f32_e32 v2, v81, v81
	v_fmac_f32_e32 v2, v80, v80
	v_add_f32_e32 v0, v0, v2
	v_mul_f32_e32 v2, v79, v79
	v_fmac_f32_e32 v2, v78, v78
	v_add_f32_e32 v0, v2, v0
	v_mov_b32_e32 v2, v0
	s_nop 1
	v_permlane16_swap_b32_e32 v0, v2
	v_add_f32_e32 v0, v0, v2
	v_mov_b32_e32 v2, v0
	s_nop 1
	v_permlane32_swap_b32_e32 v0, v2
	s_and_saveexec_b64 s[60:61], s[4:5]
	v_add_f32_e32 v0, v0, v2
	ds_write_b32 v168, v0
	s_or_b64 exec, exec, s[60:61]
	v_mul_f32_e32 v0, v29, v29
	v_mul_f32_e32 v2, v27, v27
	v_fmac_f32_e32 v0, v28, v28
	v_fmac_f32_e32 v2, v26, v26
	v_add_f32_e32 v0, v0, v2
	v_mul_f32_e32 v2, v25, v25
	v_fmac_f32_e32 v2, v24, v24
	v_add_f32_e32 v0, v0, v2
	v_mul_f32_e32 v2, v23, v23
	v_fmac_f32_e32 v2, v22, v22
	v_add_f32_e32 v0, v2, v0
	v_mov_b32_e32 v2, v0
	s_nop 1
	v_permlane16_swap_b32_e32 v0, v2
	v_add_f32_e32 v0, v0, v2
	v_mov_b32_e32 v2, v0
	s_nop 1
	v_permlane32_swap_b32_e32 v0, v2
	s_and_saveexec_b64 s[60:61], s[4:5]
	v_add_f32_e32 v0, v0, v2
	ds_write_b32 v168, v0 offset:16
	s_or_b64 exec, exec, s[60:61]
	v_mul_f32_e32 v0, v75, v75
	v_mul_f32_e32 v2, v77, v77
	v_fmac_f32_e32 v0, v74, v74
	v_fmac_f32_e32 v2, v76, v76
	v_add_f32_e32 v0, v0, v2
	v_mul_f32_e32 v2, v73, v73
	v_fmac_f32_e32 v2, v72, v72
	v_add_f32_e32 v0, v0, v2
	v_mul_f32_e32 v2, v71, v71
	v_fmac_f32_e32 v2, v70, v70
	v_add_f32_e32 v0, v2, v0
	v_mov_b32_e32 v2, v0
	s_nop 1
	v_permlane16_swap_b32_e32 v0, v2
	v_add_f32_e32 v0, v0, v2
	v_mov_b32_e32 v2, v0
	s_nop 1
	v_permlane32_swap_b32_e32 v0, v2
	s_and_saveexec_b64 s[60:61], s[4:5]
	v_add_f32_e32 v0, v0, v2
	ds_write_b32 v169, v0
	s_or_b64 exec, exec, s[60:61]
	v_mul_f32_e32 v0, v21, v21
	v_mul_f32_e32 v2, v19, v19
	v_fmac_f32_e32 v0, v20, v20
	v_fmac_f32_e32 v2, v18, v18
	v_add_f32_e32 v0, v0, v2
	v_mul_f32_e32 v2, v17, v17
	v_fmac_f32_e32 v2, v16, v16
	v_add_f32_e32 v0, v0, v2
	v_mul_f32_e32 v2, v15, v15
	v_fmac_f32_e32 v2, v14, v14
	v_add_f32_e32 v0, v2, v0
	v_mov_b32_e32 v2, v0
	s_nop 1
	v_permlane16_swap_b32_e32 v0, v2
	v_add_f32_e32 v0, v0, v2
	v_mov_b32_e32 v2, v0
	s_nop 1
	v_permlane32_swap_b32_e32 v0, v2
	s_and_saveexec_b64 s[60:61], s[4:5]
	s_cbranch_execz .LBB0_404
	v_add_f32_e32 v0, v0, v2
	ds_write_b32 v169, v0 offset:16
	s_branch .LBB0_404

.LBB0_511:
	s_add_u32 s18, s14, 0x100
	s_addc_u32 s19, s15, 0
	s_add_i32 s84, 0, 0x10000
	v_add_u32_e32 v0, s84, v189
	ds_read_b128 v[122:125], v0
	ds_read_b128 v[126:129], v0 offset:1024
	ds_read_b128 v[130:133], v0 offset:2048
	ds_read_b128 v[134:137], v0 offset:3072
	s_cmp_eq_u32 s83, 40
	s_cselect_b32 s23, s9, s19
	s_cselect_b32 s22, s8, s18
	s_cselect_b32 s21, s11, s82
	s_cselect_b32 s20, s10, s81
	v_lshl_add_u64 v[186:187], s[14:15], 0, v[184:185]
	s_add_i32 m0, s46, 0xc000
	ds_read_b128 v[146:149], v193
	ds_read_b128 v[150:153], v193 offset:1024
	ds_read_b128 v[154:157], v193 offset:2048
	ds_read_b128 v[158:161], v193 offset:3072
	ds_read_b128 v[162:165], v193 offset:4096
	ds_read_b128 v[166:169], v193 offset:5120
	ds_read_b128 v[170:173], v193 offset:6144
	ds_read_b128 v[174:177], v193 offset:7168
	global_load_lds_dwordx4 v[186:187], off
	v_lshl_add_u64 v[186:187], s[14:15], 0, v[182:183]
	s_add_i32 m0, s46, 0xe000
	s_nop 0
	global_load_lds_dwordx4 v[186:187], off
	s_waitcnt lgkmcnt(8)
	s_setprio 1
	s_barrier
	s_waitcnt lgkmcnt(0)
	v_mfma_f32_16x16x32_bf16 v[142:145], v[122:125], v[146:149], v[142:145]
	v_mfma_f32_16x16x32_bf16 v[138:141], v[130:133], v[146:149], v[138:141]
	v_mfma_f32_16x16x32_bf16 v[110:113], v[122:125], v[154:157], v[110:113]
	v_mfma_f32_16x16x32_bf16 v[106:109], v[130:133], v[154:157], v[106:109]
	v_mfma_f32_16x16x32_bf16 v[94:97], v[122:125], v[162:165], v[94:97]
	v_mfma_f32_16x16x32_bf16 v[90:93], v[130:133], v[162:165], v[90:93]
	v_mfma_f32_16x16x32_bf16 v[78:81], v[122:125], v[170:173], v[78:81]
	v_mfma_f32_16x16x32_bf16 v[74:77], v[130:133], v[170:173], v[74:77]
	v_mfma_f32_16x16x32_bf16 v[142:145], v[126:129], v[150:153], v[142:145]
	v_mfma_f32_16x16x32_bf16 v[138:141], v[134:137], v[150:153], v[138:141]
	v_mfma_f32_16x16x32_bf16 v[110:113], v[126:129], v[158:161], v[110:113]
	v_mfma_f32_16x16x32_bf16 v[106:109], v[134:137], v[158:161], v[106:109]
	v_mfma_f32_16x16x32_bf16 v[94:97], v[126:129], v[166:169], v[94:97]
	v_mfma_f32_16x16x32_bf16 v[90:93], v[134:137], v[166:169], v[90:93]
	v_mfma_f32_16x16x32_bf16 v[78:81], v[126:129], v[174:177], v[78:81]
	v_mfma_f32_16x16x32_bf16 v[74:77], v[134:137], v[174:177], v[74:77]
	s_setprio 0
	s_barrier
	s_add_i32 s85, 0, 0x14000
	s_add_i32 s14, s84, s25
	v_add_u32_e32 v0, s85, v189
	v_lshl_add_u64 v[186:187], s[20:21], 0, v[180:181]
	s_mov_b32 m0, s14
	ds_read_b128 v[194:197], v0
	ds_read_b128 v[200:203], v0 offset:1024
	ds_read_b128 v[204:207], v0 offset:2048
	ds_read_b128 v[208:211], v0 offset:3072
	global_load_lds_dwordx4 v[186:187], off
	v_lshl_add_u64 v[198:199], s[20:21], 0, v[178:179]
	s_add_i32 m0, s14, 0x2000
	s_nop 0
	global_load_lds_dwordx4 v[198:199], off
	s_setprio 1
	s_barrier
	s_waitcnt lgkmcnt(0)
	v_mfma_f32_16x16x32_bf16 v[118:121], v[194:197], v[146:149], v[118:121]
	v_mfma_f32_16x16x32_bf16 v[114:117], v[204:207], v[146:149], v[114:117]
	v_mfma_f32_16x16x32_bf16 v[102:105], v[194:197], v[154:157], v[102:105]
	v_mfma_f32_16x16x32_bf16 v[98:101], v[204:207], v[154:157], v[98:101]
	v_mfma_f32_16x16x32_bf16 v[86:89], v[194:197], v[162:165], v[86:89]
	v_mfma_f32_16x16x32_bf16 v[82:85], v[204:207], v[162:165], v[82:85]
	v_mfma_f32_16x16x32_bf16 v[70:73], v[194:197], v[170:173], v[70:73]
	v_mfma_f32_16x16x32_bf16 v[66:69], v[204:207], v[170:173], v[66:69]
	v_mfma_f32_16x16x32_bf16 v[118:121], v[200:203], v[150:153], v[118:121]
	v_mfma_f32_16x16x32_bf16 v[114:117], v[208:211], v[150:153], v[114:117]
	v_mfma_f32_16x16x32_bf16 v[102:105], v[200:203], v[158:161], v[102:105]
	v_mfma_f32_16x16x32_bf16 v[98:101], v[208:211], v[158:161], v[98:101]
	v_mfma_f32_16x16x32_bf16 v[86:89], v[200:203], v[166:169], v[86:89]
	v_mfma_f32_16x16x32_bf16 v[82:85], v[208:211], v[166:169], v[82:85]
	v_mfma_f32_16x16x32_bf16 v[70:73], v[200:203], v[174:177], v[70:73]
	v_mfma_f32_16x16x32_bf16 v[66:69], v[208:211], v[174:177], v[66:69]
	s_setprio 0
	s_mov_b32 m0, s46
	v_lshl_add_u64 v[212:213], s[22:23], 0, v[180:181]
	s_barrier
	ds_read_b128 v[146:149], v193 offset:16384
	ds_read_b128 v[150:153], v193 offset:17408
	ds_read_b128 v[154:157], v193 offset:18432
	ds_read_b128 v[158:161], v193 offset:19456
	ds_read_b128 v[162:165], v193 offset:20480
	ds_read_b128 v[166:169], v193 offset:21504
	ds_read_b128 v[170:173], v193 offset:22528
	ds_read_b128 v[174:177], v193 offset:23552
	global_load_lds_dwordx4 v[212:213], off
	v_lshl_add_u64 v[214:215], s[22:23], 0, v[178:179]
	s_mov_b32 m0, s57
	s_nop 0
	global_load_lds_dwordx4 v[214:215], off
	s_setprio 1
	s_barrier
	s_waitcnt lgkmcnt(0)
	v_mfma_f32_16x16x32_bf16 v[62:65], v[122:125], v[146:149], v[62:65]
	v_mfma_f32_16x16x32_bf16 v[58:61], v[130:133], v[146:149], v[58:61]
	v_mfma_f32_16x16x32_bf16 v[46:49], v[122:125], v[154:157], v[46:49]
	v_mfma_f32_16x16x32_bf16 v[42:45], v[130:133], v[154:157], v[42:45]
	v_mfma_f32_16x16x32_bf16 v[30:33], v[122:125], v[162:165], v[30:33]
	v_mfma_f32_16x16x32_bf16 v[26:29], v[130:133], v[162:165], v[26:29]
	v_mfma_f32_16x16x32_bf16 v[14:17], v[122:125], v[170:173], v[14:17]
	v_mfma_f32_16x16x32_bf16 v[10:13], v[130:133], v[170:173], v[10:13]
	v_mfma_f32_16x16x32_bf16 v[62:65], v[126:129], v[150:153], v[62:65]
	v_mfma_f32_16x16x32_bf16 v[58:61], v[134:137], v[150:153], v[58:61]
	v_mfma_f32_16x16x32_bf16 v[46:49], v[126:129], v[158:161], v[46:49]
	v_mfma_f32_16x16x32_bf16 v[42:45], v[134:137], v[158:161], v[42:45]
	v_mfma_f32_16x16x32_bf16 v[30:33], v[126:129], v[166:169], v[30:33]
	v_mfma_f32_16x16x32_bf16 v[26:29], v[134:137], v[166:169], v[26:29]
	v_mfma_f32_16x16x32_bf16 v[14:17], v[126:129], v[174:177], v[14:17]
	v_mfma_f32_16x16x32_bf16 v[10:13], v[134:137], v[174:177], v[10:13]
	s_setprio 0
	s_barrier
	s_add_u32 s14, s20, 0xb0000
	s_addc_u32 s15, s21, 0
	s_add_i32 s84, s85, s25
	v_lshl_add_u64 v[122:123], s[14:15], 0, v[180:181]
	s_mov_b32 m0, s84
	s_nop 0
	global_load_lds_dwordx4 v[122:123], off
	v_lshl_add_u64 v[122:123], s[14:15], 0, v[178:179]
	s_add_i32 m0, s84, 0x2000
	s_nop 0
	global_load_lds_dwordx4 v[122:123], off
	s_waitcnt vmcnt(6)
	s_setprio 1
	s_barrier
	v_mfma_f32_16x16x32_bf16 v[54:57], v[194:197], v[146:149], v[54:57]
	v_mfma_f32_16x16x32_bf16 v[50:53], v[204:207], v[146:149], v[50:53]
	v_mfma_f32_16x16x32_bf16 v[38:41], v[194:197], v[154:157], v[38:41]
	v_mfma_f32_16x16x32_bf16 v[34:37], v[204:207], v[154:157], v[34:37]
	v_mfma_f32_16x16x32_bf16 v[22:25], v[194:197], v[162:165], v[22:25]
	v_mfma_f32_16x16x32_bf16 v[18:21], v[204:207], v[162:165], v[18:21]
	v_mfma_f32_16x16x32_bf16 v[6:9], v[194:197], v[170:173], v[6:9]
	v_mfma_f32_16x16x32_bf16 v[2:5], v[204:207], v[170:173], v[2:5]
	v_mfma_f32_16x16x32_bf16 v[54:57], v[200:203], v[150:153], v[54:57]
	v_mfma_f32_16x16x32_bf16 v[50:53], v[208:211], v[150:153], v[50:53]
	v_mfma_f32_16x16x32_bf16 v[38:41], v[200:203], v[158:161], v[38:41]
	v_mfma_f32_16x16x32_bf16 v[34:37], v[208:211], v[158:161], v[34:37]
	v_mfma_f32_16x16x32_bf16 v[22:25], v[200:203], v[166:169], v[22:25]
	v_mfma_f32_16x16x32_bf16 v[18:21], v[208:211], v[166:169], v[18:21]
	v_mfma_f32_16x16x32_bf16 v[6:9], v[200:203], v[174:177], v[6:9]
	v_mfma_f32_16x16x32_bf16 v[2:5], v[208:211], v[174:177], v[2:5]
	s_setprio 0
	s_add_i32 s84, 0, 0x18000
	v_add_u32_e32 v0, s84, v189
	s_barrier
	ds_read_b128 v[122:125], v0
	ds_read_b128 v[126:129], v0 offset:1024
	ds_read_b128 v[130:133], v0 offset:2048
	ds_read_b128 v[134:137], v0 offset:3072
	s_add_u32 s14, s22, 0xb0000
	s_addc_u32 s15, s23, 0
	s_mov_b32 m0, s59
	v_lshl_add_u64 v[194:195], s[14:15], 0, v[180:181]
	ds_read_b128 v[146:149], v193 offset:32768
	ds_read_b128 v[150:153], v193 offset:33792
	ds_read_b128 v[154:157], v193 offset:34816
	ds_read_b128 v[158:161], v193 offset:35840
	ds_read_b128 v[162:165], v193 offset:36864
	ds_read_b128 v[166:169], v193 offset:37888
	ds_read_b128 v[170:173], v193 offset:38912
	ds_read_b128 v[174:177], v193 offset:39936
	global_load_lds_dwordx4 v[194:195], off
	v_lshl_add_u64 v[194:195], s[14:15], 0, v[178:179]
	s_mov_b32 m0, s60
	s_nop 0
	global_load_lds_dwordx4 v[194:195], off
	s_waitcnt lgkmcnt(8)
	s_setprio 1
	s_barrier
	s_waitcnt lgkmcnt(0)
	v_mfma_f32_16x16x32_bf16 v[142:145], v[122:125], v[146:149], v[142:145]
	v_mfma_f32_16x16x32_bf16 v[138:141], v[130:133], v[146:149], v[138:141]
	v_mfma_f32_16x16x32_bf16 v[110:113], v[122:125], v[154:157], v[110:113]
	v_mfma_f32_16x16x32_bf16 v[106:109], v[130:133], v[154:157], v[106:109]
	v_mfma_f32_16x16x32_bf16 v[94:97], v[122:125], v[162:165], v[94:97]
	v_mfma_f32_16x16x32_bf16 v[90:93], v[130:133], v[162:165], v[90:93]
	v_mfma_f32_16x16x32_bf16 v[78:81], v[122:125], v[170:173], v[78:81]
	v_mfma_f32_16x16x32_bf16 v[74:77], v[130:133], v[170:173], v[74:77]
	v_mfma_f32_16x16x32_bf16 v[142:145], v[126:129], v[150:153], v[142:145]
	v_mfma_f32_16x16x32_bf16 v[138:141], v[134:137], v[150:153], v[138:141]
	v_mfma_f32_16x16x32_bf16 v[110:113], v[126:129], v[158:161], v[110:113]
	v_mfma_f32_16x16x32_bf16 v[106:109], v[134:137], v[158:161], v[106:109]
	v_mfma_f32_16x16x32_bf16 v[94:97], v[126:129], v[166:169], v[94:97]
	v_mfma_f32_16x16x32_bf16 v[90:93], v[134:137], v[166:169], v[90:93]
	v_mfma_f32_16x16x32_bf16 v[78:81], v[126:129], v[174:177], v[78:81]
	v_mfma_f32_16x16x32_bf16 v[74:77], v[134:137], v[174:177], v[74:77]
	s_setprio 0
	s_barrier
	s_add_i32 s22, 0, 0x1c000
	s_add_i32 s14, s84, s25
	v_add_u32_e32 v0, s22, v189
	v_lshl_add_u64 v[186:187], v[186:187], 0, s[48:49]
	s_mov_b32 m0, s14
	ds_read_b128 v[194:197], v0
	ds_read_b128 v[200:203], v0 offset:1024
	ds_read_b128 v[204:207], v0 offset:2048
	ds_read_b128 v[208:211], v0 offset:3072
	global_load_lds_dwordx4 v[186:187], off
	v_lshl_add_u64 v[186:187], v[198:199], 0, s[48:49]
	s_add_i32 m0, s14, 0x2000
	s_nop 0
	global_load_lds_dwordx4 v[186:187], off
	s_setprio 1
	s_barrier
	s_waitcnt lgkmcnt(0)
	v_mfma_f32_16x16x32_bf16 v[118:121], v[194:197], v[146:149], v[118:121]
	v_mfma_f32_16x16x32_bf16 v[114:117], v[204:207], v[146:149], v[114:117]
	v_mfma_f32_16x16x32_bf16 v[102:105], v[194:197], v[154:157], v[102:105]
	v_mfma_f32_16x16x32_bf16 v[98:101], v[204:207], v[154:157], v[98:101]
	v_mfma_f32_16x16x32_bf16 v[86:89], v[194:197], v[162:165], v[86:89]
	v_mfma_f32_16x16x32_bf16 v[82:85], v[204:207], v[162:165], v[82:85]
	v_mfma_f32_16x16x32_bf16 v[70:73], v[194:197], v[170:173], v[70:73]
	v_mfma_f32_16x16x32_bf16 v[66:69], v[204:207], v[170:173], v[66:69]
	v_mfma_f32_16x16x32_bf16 v[118:121], v[200:203], v[150:153], v[118:121]
	v_mfma_f32_16x16x32_bf16 v[114:117], v[208:211], v[150:153], v[114:117]
	v_mfma_f32_16x16x32_bf16 v[102:105], v[200:203], v[158:161], v[102:105]
	v_mfma_f32_16x16x32_bf16 v[98:101], v[208:211], v[158:161], v[98:101]
	v_mfma_f32_16x16x32_bf16 v[86:89], v[200:203], v[166:169], v[86:89]
	v_mfma_f32_16x16x32_bf16 v[82:85], v[208:211], v[166:169], v[82:85]
	v_mfma_f32_16x16x32_bf16 v[70:73], v[200:203], v[174:177], v[70:73]
	v_mfma_f32_16x16x32_bf16 v[66:69], v[208:211], v[174:177], v[66:69]
	s_setprio 0
	s_mov_b32 m0, s74
	v_lshl_add_u64 v[186:187], v[212:213], 0, s[48:49]
	s_barrier
	ds_read_b128 v[146:149], v193 offset:49152
	ds_read_b128 v[150:153], v193 offset:50176
	ds_read_b128 v[154:157], v193 offset:51200
	ds_read_b128 v[158:161], v193 offset:52224
	ds_read_b128 v[162:165], v193 offset:53248
	ds_read_b128 v[166:169], v193 offset:54272
	ds_read_b128 v[170:173], v193 offset:55296
	ds_read_b128 v[174:177], v193 offset:56320
	global_load_lds_dwordx4 v[186:187], off
	v_lshl_add_u64 v[186:187], v[214:215], 0, s[48:49]
	s_mov_b32 m0, s75
	s_nop 0
	global_load_lds_dwordx4 v[186:187], off
	s_setprio 1
	s_barrier
;     DEVI void operator()(AccRef acc, const pg8::Unit& u, int wr, int wc, int fr, int fq) const {
;         unsigned o = (unsigned)((u.pm * 256 + wr * 64 + fr) * DM + u.pn * 256 + wc * 32 + 4 * fq) * 4u;
;         const bool lo = fr < 8;
;         unsigned os = (unsigned)((u.pm * 256 + wr * 64 + (fr & 7)) * DM + u.pn * 256 + wc * 32 + 4 * fq) * 4u + (lo ? 0u : 64u);
; #pragma unroll
;         for (int ai = 0; ai < 2; ++ai) {
;             asm volatile("" : "+v"(o), "+v"(os));
;             f32x4 b[4][2][2];
; #pragma unroll
;             for (int m = 0; m < 4; ++m)
; #pragma unroll
;                 for (int bj = 0; bj < 2; ++bj)
; #pragma unroll
;                     for (int n = 0; n < 2; ++n) b[m][bj][n] = *(const f32x4*)((const char*)base + o + (unsigned)(m * 16 * DM * 4 + bj * 512 + n * 64));
	s_waitcnt lgkmcnt(0)
	v_mfma_f32_16x16x32_bf16 v[62:65], v[122:125], v[146:149], v[62:65]
	v_mfma_f32_16x16x32_bf16 v[58:61], v[130:133], v[146:149], v[58:61]
	v_mfma_f32_16x16x32_bf16 v[46:49], v[122:125], v[154:157], v[46:49]
	v_mfma_f32_16x16x32_bf16 v[42:45], v[130:133], v[154:157], v[42:45]
	v_mfma_f32_16x16x32_bf16 v[30:33], v[122:125], v[162:165], v[30:33]
	v_mfma_f32_16x16x32_bf16 v[26:29], v[130:133], v[162:165], v[26:29]
	v_mfma_f32_16x16x32_bf16 v[14:17], v[122:125], v[170:173], v[14:17]
	v_mfma_f32_16x16x32_bf16 v[10:13], v[130:133], v[170:173], v[10:13]
	v_mfma_f32_16x16x32_bf16 v[62:65], v[126:129], v[150:153], v[62:65]
	v_mfma_f32_16x16x32_bf16 v[58:61], v[134:137], v[150:153], v[58:61]
	v_mfma_f32_16x16x32_bf16 v[46:49], v[126:129], v[158:161], v[46:49]
	v_mfma_f32_16x16x32_bf16 v[42:45], v[134:137], v[158:161], v[42:45]
	v_mfma_f32_16x16x32_bf16 v[30:33], v[126:129], v[166:169], v[30:33]
	v_mfma_f32_16x16x32_bf16 v[26:29], v[134:137], v[166:169], v[26:29]
	v_mfma_f32_16x16x32_bf16 v[14:17], v[126:129], v[174:177], v[14:17]
	v_mfma_f32_16x16x32_bf16 v[10:13], v[134:137], v[174:177], v[10:13]
	s_setprio 0
	s_barrier
	s_add_u32 s14, s20, 0xb0080
	s_addc_u32 s15, s21, 0
	s_add_i32 s20, s22, s25
	v_lshl_add_u64 v[122:123], s[14:15], 0, v[180:181]
	s_mov_b32 m0, s20
	s_nop 0
	global_load_lds_dwordx4 v[122:123], off
	v_lshl_add_u64 v[122:123], s[14:15], 0, v[178:179]
	s_add_i32 m0, s20, 0x2000
	s_nop 0
	global_load_lds_dwordx4 v[122:123], off
	s_waitcnt vmcnt(6)
	s_setprio 1
	s_barrier
	v_mfma_f32_16x16x32_bf16 v[54:57], v[194:197], v[146:149], v[54:57]
	v_mfma_f32_16x16x32_bf16 v[50:53], v[204:207], v[146:149], v[50:53]
	v_mfma_f32_16x16x32_bf16 v[38:41], v[194:197], v[154:157], v[38:41]
	v_mfma_f32_16x16x32_bf16 v[34:37], v[204:207], v[154:157], v[34:37]
	v_mfma_f32_16x16x32_bf16 v[22:25], v[194:197], v[162:165], v[22:25]
	v_mfma_f32_16x16x32_bf16 v[18:21], v[204:207], v[162:165], v[18:21]
	v_mfma_f32_16x16x32_bf16 v[6:9], v[194:197], v[170:173], v[6:9]
	v_mfma_f32_16x16x32_bf16 v[2:5], v[204:207], v[170:173], v[2:5]
	v_mfma_f32_16x16x32_bf16 v[54:57], v[200:203], v[150:153], v[54:57]
	v_mfma_f32_16x16x32_bf16 v[50:53], v[208:211], v[150:153], v[50:53]
	v_mfma_f32_16x16x32_bf16 v[38:41], v[200:203], v[158:161], v[38:41]
	v_mfma_f32_16x16x32_bf16 v[34:37], v[208:211], v[158:161], v[34:37]
	v_mfma_f32_16x16x32_bf16 v[22:25], v[200:203], v[166:169], v[22:25]
	v_mfma_f32_16x16x32_bf16 v[18:21], v[208:211], v[166:169], v[18:21]
	v_mfma_f32_16x16x32_bf16 v[6:9], v[200:203], v[174:177], v[6:9]
	v_mfma_f32_16x16x32_bf16 v[2:5], v[208:211], v[174:177], v[2:5]
	s_setprio 0
	s_add_i32 s83, s83, 2
	s_add_u32 s81, s81, 0x100
	s_addc_u32 s82, s82, 0
	s_cmp_gt_u32 s83, 41
	s_mov_b64 s[14:15], s[18:19]
	s_barrier
	s_cbranch_scc0 .LBB0_511
	s_lshl_b32 s14, s79, 8
	s_add_i32 s14, s14, s61
	v_or_b32_e32 v0, s14, v188
	s_lshl_b32 s15, s80, 8
	v_or_b32_e32 v122, s14, v190
	v_lshl_add_u32 v0, v0, 10, s15
	v_lshl_add_u32 v122, v122, 10, s15
	v_or_b32_e32 v0, v0, v192
	v_or_b32_e32 v122, v122, v192
	v_lshlrev_b32_e32 v0, 2, v0
	v_lshl_or_b32 v186, v122, 2, v191
	s_mov_b32 s80, s77
	s_mov_b32 s79, s78
	s_mov_b64 s[18:19], s[10:11]
	s_mov_b64 s[14:15], s[8:9]
	v_add_u32_e32 v187, 0x8000, v186
	s_add_u32 s98, s12, 0x0
	s_addc_u32 s99, s13, 0
	global_load_dwordx4 v[194:197], v0, s[98:99]
	global_load_dwordx4 v[200:203], v0, s[98:99] offset:64
	global_load_dwordx4 v[204:207], v0, s[98:99] offset:512
	global_load_dwordx4 v[208:211], v0, s[98:99] offset:576
	s_add_u32 s98, s12, 0x10000
	s_addc_u32 s99, s13, 0
	global_load_dwordx4 v[174:177], v0, s[98:99]
	global_load_dwordx4 v[170:173], v0, s[98:99] offset:64
	global_load_dwordx4 v[166:169], v0, s[98:99] offset:512
	global_load_dwordx4 v[162:165], v0, s[98:99] offset:576
	s_add_u32 s98, s12, 0x20000
	s_addc_u32 s99, s13, 0
	global_load_dwordx4 v[158:161], v0, s[98:99]
	global_load_dwordx4 v[154:157], v0, s[98:99] offset:64
	global_load_dwordx4 v[150:153], v0, s[98:99] offset:512
	global_load_dwordx4 v[146:149], v0, s[98:99] offset:576
	s_add_u32 s98, s12, 0x30000
	s_addc_u32 s99, s13, 0
	global_load_dwordx4 v[134:137], v0, s[98:99]
	global_load_dwordx4 v[130:133], v0, s[98:99] offset:64
	global_load_dwordx4 v[126:129], v0, s[98:99] offset:512
	global_load_dwordx4 v[122:125], v0, s[98:99] offset:576
	s_waitcnt vmcnt(12)
; template <int CTRL> DEVI float dpp(float x) { return __builtin_bit_cast(float, __builtin_amdgcn_mov_dpp(__builtin_bit_cast(int, x), CTRL, 0xf, 0xf, true)); }
;     DEVI void operator()(AccRef acc, const pg8::Unit& u, int wr, int wc, int fr, int fq) const {
;     ...
; #pragma unroll
;             for (int m = 0; m < 4; ++m)
; #pragma unroll
;                 for (int bj = 0; bj < 2; ++bj) { const f32x4 d0 = b[m][bj][0] + alpha * acc[ai][bj][m][0], d1 = b[m][bj][1] + alpha * acc[ai][bj][m][1];
;                     f32x4 t0, t1;
; #pragma unroll
;                     for (int i = 0; i < 4; ++i) { t0[i] = dpp<0x128>(d0[i]); t1[i] = dpp<0x128>(d1[i]); }
;                     const f32x4 sa = lo ? d0 : t1, sb = lo ? t0 : d1;
;                     const unsigned oo = os + (unsigned)(m * 16 * DM * 4 + bj * 512);
;                     *(f32x4*)((char*)out + oo) = sa; *(f32x4*)((char*)out + oo + 8u * DM * 4u) = sb; }
;             o += 128u * DM * 4u; os += 128u * DM * 4u; }
	v_pk_fma_f32 v[142:143], v[142:143], 0.5, v[194:195] op_sel_hi:[1,0,1]
	v_pk_fma_f32 v[144:145], v[144:145], 0.5, v[196:197] op_sel_hi:[1,0,1]
	v_pk_fma_f32 v[138:139], v[138:139], 0.5, v[200:201] op_sel_hi:[1,0,1]
	v_pk_fma_f32 v[140:141], v[140:141], 0.5, v[202:203] op_sel_hi:[1,0,1]
	v_pk_fma_f32 v[118:119], v[118:119], 0.5, v[204:205] op_sel_hi:[1,0,1]
	v_pk_fma_f32 v[120:121], v[120:121], 0.5, v[206:207] op_sel_hi:[1,0,1]
	v_pk_fma_f32 v[114:115], v[114:115], 0.5, v[208:209] op_sel_hi:[1,0,1]
	v_pk_fma_f32 v[116:117], v[116:117], 0.5, v[210:211] op_sel_hi:[1,0,1]
	s_mov_b64 vcc, s[4:5]
	v_cndmask_b32_dpp v194, v138, v142, vcc row_ror:8 row_mask:0xf bank_mask:0xf bound_ctrl:1
	v_cndmask_b32_dpp v195, v139, v143, vcc row_ror:8 row_mask:0xf bank_mask:0xf bound_ctrl:1
	v_cndmask_b32_dpp v196, v140, v144, vcc row_ror:8 row_mask:0xf bank_mask:0xf bound_ctrl:1
	v_cndmask_b32_dpp v197, v141, v145, vcc row_ror:8 row_mask:0xf bank_mask:0xf bound_ctrl:1
	v_cndmask_b32_dpp v204, v114, v118, vcc row_ror:8 row_mask:0xf bank_mask:0xf bound_ctrl:1
	v_cndmask_b32_dpp v205, v115, v119, vcc row_ror:8 row_mask:0xf bank_mask:0xf bound_ctrl:1
	v_cndmask_b32_dpp v206, v116, v120, vcc row_ror:8 row_mask:0xf bank_mask:0xf bound_ctrl:1
	v_cndmask_b32_dpp v207, v117, v121, vcc row_ror:8 row_mask:0xf bank_mask:0xf bound_ctrl:1
	s_not_b64 vcc, s[4:5]
	v_cndmask_b32_dpp v200, v142, v138, vcc row_ror:8 row_mask:0xf bank_mask:0xf bound_ctrl:1
	v_cndmask_b32_dpp v201, v143, v139, vcc row_ror:8 row_mask:0xf bank_mask:0xf bound_ctrl:1
	v_cndmask_b32_dpp v202, v144, v140, vcc row_ror:8 row_mask:0xf bank_mask:0xf bound_ctrl:1
	v_cndmask_b32_dpp v203, v145, v141, vcc row_ror:8 row_mask:0xf bank_mask:0xf bound_ctrl:1
	v_cndmask_b32_dpp v208, v118, v114, vcc row_ror:8 row_mask:0xf bank_mask:0xf bound_ctrl:1
	v_cndmask_b32_dpp v209, v119, v115, vcc row_ror:8 row_mask:0xf bank_mask:0xf bound_ctrl:1
	v_cndmask_b32_dpp v210, v120, v116, vcc row_ror:8 row_mask:0xf bank_mask:0xf bound_ctrl:1
	v_cndmask_b32_dpp v211, v121, v117, vcc row_ror:8 row_mask:0xf bank_mask:0xf bound_ctrl:1
	s_add_u32 s100, s28, 0x0
	s_addc_u32 s101, s29, 0
	global_store_dwordx4 v186, v[194:197], s[100:101]
	global_store_dwordx4 v187, v[200:203], s[100:101]
	global_store_dwordx4 v186, v[204:207], s[100:101] offset:512
	global_store_dwordx4 v187, v[208:211], s[100:101] offset:512
	s_add_u32 s98, s12, 0x80000
	s_addc_u32 s99, s13, 0
	global_load_dwordx4 v[142:145], v0, s[98:99]
	global_load_dwordx4 v[138:141], v0, s[98:99] offset:64
	global_load_dwordx4 v[118:121], v0, s[98:99] offset:512
	global_load_dwordx4 v[114:117], v0, s[98:99] offset:576
	s_waitcnt vmcnt(16)
	v_pk_fma_f32 v[110:111], v[110:111], 0.5, v[174:175] op_sel_hi:[1,0,1]
	v_pk_fma_f32 v[112:113], v[112:113], 0.5, v[176:177] op_sel_hi:[1,0,1]
	v_pk_fma_f32 v[106:107], v[106:107], 0.5, v[170:171] op_sel_hi:[1,0,1]
	v_pk_fma_f32 v[108:109], v[108:109], 0.5, v[172:173] op_sel_hi:[1,0,1]
	v_pk_fma_f32 v[102:103], v[102:103], 0.5, v[166:167] op_sel_hi:[1,0,1]
	v_pk_fma_f32 v[104:105], v[104:105], 0.5, v[168:169] op_sel_hi:[1,0,1]
	v_pk_fma_f32 v[98:99], v[98:99], 0.5, v[162:163] op_sel_hi:[1,0,1]
	v_pk_fma_f32 v[100:101], v[100:101], 0.5, v[164:165] op_sel_hi:[1,0,1]
	s_mov_b64 vcc, s[4:5]
	v_cndmask_b32_dpp v174, v106, v110, vcc row_ror:8 row_mask:0xf bank_mask:0xf bound_ctrl:1
	v_cndmask_b32_dpp v175, v107, v111, vcc row_ror:8 row_mask:0xf bank_mask:0xf bound_ctrl:1
	v_cndmask_b32_dpp v176, v108, v112, vcc row_ror:8 row_mask:0xf bank_mask:0xf bound_ctrl:1
	v_cndmask_b32_dpp v177, v109, v113, vcc row_ror:8 row_mask:0xf bank_mask:0xf bound_ctrl:1
	v_cndmask_b32_dpp v166, v98, v102, vcc row_ror:8 row_mask:0xf bank_mask:0xf bound_ctrl:1
	v_cndmask_b32_dpp v167, v99, v103, vcc row_ror:8 row_mask:0xf bank_mask:0xf bound_ctrl:1
	v_cndmask_b32_dpp v168, v100, v104, vcc row_ror:8 row_mask:0xf bank_mask:0xf bound_ctrl:1
	v_cndmask_b32_dpp v169, v101, v105, vcc row_ror:8 row_mask:0xf bank_mask:0xf bound_ctrl:1
	s_not_b64 vcc, s[4:5]
	v_cndmask_b32_dpp v170, v110, v106, vcc row_ror:8 row_mask:0xf bank_mask:0xf bound_ctrl:1
	v_cndmask_b32_dpp v171, v111, v107, vcc row_ror:8 row_mask:0xf bank_mask:0xf bound_ctrl:1
	v_cndmask_b32_dpp v172, v112, v108, vcc row_ror:8 row_mask:0xf bank_mask:0xf bound_ctrl:1
	v_cndmask_b32_dpp v173, v113, v109, vcc row_ror:8 row_mask:0xf bank_mask:0xf bound_ctrl:1
	v_cndmask_b32_dpp v162, v102, v98, vcc row_ror:8 row_mask:0xf bank_mask:0xf bound_ctrl:1
	v_cndmask_b32_dpp v163, v103, v99, vcc row_ror:8 row_mask:0xf bank_mask:0xf bound_ctrl:1
	v_cndmask_b32_dpp v164, v104, v100, vcc row_ror:8 row_mask:0xf bank_mask:0xf bound_ctrl:1
	v_cndmask_b32_dpp v165, v105, v101, vcc row_ror:8 row_mask:0xf bank_mask:0xf bound_ctrl:1
	s_add_u32 s100, s28, 0x10000
	s_addc_u32 s101, s29, 0
	global_store_dwordx4 v186, v[174:177], s[100:101]
	global_store_dwordx4 v187, v[170:173], s[100:101]
	global_store_dwordx4 v186, v[166:169], s[100:101] offset:512
	global_store_dwordx4 v187, v[162:165], s[100:101] offset:512
	s_add_u32 s98, s12, 0x90000
	s_addc_u32 s99, s13, 0
	global_load_dwordx4 v[110:113], v0, s[98:99]
	global_load_dwordx4 v[106:109], v0, s[98:99] offset:64
	global_load_dwordx4 v[102:105], v0, s[98:99] offset:512
	global_load_dwordx4 v[98:101], v0, s[98:99] offset:576
	s_waitcnt vmcnt(20)
; template <int CTRL> DEVI float dpp(float x) { return __builtin_bit_cast(float, __builtin_amdgcn_mov_dpp(__builtin_bit_cast(int, x), CTRL, 0xf, 0xf, true)); }
;     DEVI void operator()(AccRef acc, const pg8::Unit& u, int wr, int wc, int fr, int fq) const {
;     ...
; #pragma unroll
;             for (int m = 0; m < 4; ++m)
; #pragma unroll
;                 for (int bj = 0; bj < 2; ++bj) { const f32x4 d0 = b[m][bj][0] + alpha * acc[ai][bj][m][0], d1 = b[m][bj][1] + alpha * acc[ai][bj][m][1];
;                     f32x4 t0, t1;
; #pragma unroll
;                     for (int i = 0; i < 4; ++i) { t0[i] = dpp<0x128>(d0[i]); t1[i] = dpp<0x128>(d1[i]); }
;                     const f32x4 sa = lo ? d0 : t1, sb = lo ? t0 : d1;
;                     const unsigned oo = os + (unsigned)(m * 16 * DM * 4 + bj * 512);
;                     *(f32x4*)((char*)out + oo) = sa; *(f32x4*)((char*)out + oo + 8u * DM * 4u) = sb; }
;             o += 128u * DM * 4u; os += 128u * DM * 4u; }
	v_pk_fma_f32 v[94:95], v[94:95], 0.5, v[158:159] op_sel_hi:[1,0,1]
	v_pk_fma_f32 v[96:97], v[96:97], 0.5, v[160:161] op_sel_hi:[1,0,1]
	v_pk_fma_f32 v[90:91], v[90:91], 0.5, v[154:155] op_sel_hi:[1,0,1]
	v_pk_fma_f32 v[92:93], v[92:93], 0.5, v[156:157] op_sel_hi:[1,0,1]
	v_pk_fma_f32 v[86:87], v[86:87], 0.5, v[150:151] op_sel_hi:[1,0,1]
	v_pk_fma_f32 v[88:89], v[88:89], 0.5, v[152:153] op_sel_hi:[1,0,1]
	v_pk_fma_f32 v[82:83], v[82:83], 0.5, v[146:147] op_sel_hi:[1,0,1]
	v_pk_fma_f32 v[84:85], v[84:85], 0.5, v[148:149] op_sel_hi:[1,0,1]
	s_mov_b64 vcc, s[4:5]
	v_cndmask_b32_dpp v158, v90, v94, vcc row_ror:8 row_mask:0xf bank_mask:0xf bound_ctrl:1
	v_cndmask_b32_dpp v159, v91, v95, vcc row_ror:8 row_mask:0xf bank_mask:0xf bound_ctrl:1
	v_cndmask_b32_dpp v160, v92, v96, vcc row_ror:8 row_mask:0xf bank_mask:0xf bound_ctrl:1
	v_cndmask_b32_dpp v161, v93, v97, vcc row_ror:8 row_mask:0xf bank_mask:0xf bound_ctrl:1
	v_cndmask_b32_dpp v150, v82, v86, vcc row_ror:8 row_mask:0xf bank_mask:0xf bound_ctrl:1
	v_cndmask_b32_dpp v151, v83, v87, vcc row_ror:8 row_mask:0xf bank_mask:0xf bound_ctrl:1
	v_cndmask_b32_dpp v152, v84, v88, vcc row_ror:8 row_mask:0xf bank_mask:0xf bound_ctrl:1
	v_cndmask_b32_dpp v153, v85, v89, vcc row_ror:8 row_mask:0xf bank_mask:0xf bound_ctrl:1
	s_not_b64 vcc, s[4:5]
	v_cndmask_b32_dpp v154, v94, v90, vcc row_ror:8 row_mask:0xf bank_mask:0xf bound_ctrl:1
	v_cndmask_b32_dpp v155, v95, v91, vcc row_ror:8 row_mask:0xf bank_mask:0xf bound_ctrl:1
	v_cndmask_b32_dpp v156, v96, v92, vcc row_ror:8 row_mask:0xf bank_mask:0xf bound_ctrl:1
	v_cndmask_b32_dpp v157, v97, v93, vcc row_ror:8 row_mask:0xf bank_mask:0xf bound_ctrl:1
	v_cndmask_b32_dpp v146, v86, v82, vcc row_ror:8 row_mask:0xf bank_mask:0xf bound_ctrl:1
	v_cndmask_b32_dpp v147, v87, v83, vcc row_ror:8 row_mask:0xf bank_mask:0xf bound_ctrl:1
	v_cndmask_b32_dpp v148, v88, v84, vcc row_ror:8 row_mask:0xf bank_mask:0xf bound_ctrl:1
	v_cndmask_b32_dpp v149, v89, v85, vcc row_ror:8 row_mask:0xf bank_mask:0xf bound_ctrl:1
	s_add_u32 s100, s28, 0x20000
	s_addc_u32 s101, s29, 0
	global_store_dwordx4 v186, v[158:161], s[100:101]
	global_store_dwordx4 v187, v[154:157], s[100:101]
	global_store_dwordx4 v186, v[150:153], s[100:101] offset:512
	global_store_dwordx4 v187, v[146:149], s[100:101] offset:512
	s_add_u32 s98, s12, 0xa0000
	s_addc_u32 s99, s13, 0
	global_load_dwordx4 v[94:97], v0, s[98:99]
	global_load_dwordx4 v[90:93], v0, s[98:99] offset:64
	global_load_dwordx4 v[86:89], v0, s[98:99] offset:512
	global_load_dwordx4 v[82:85], v0, s[98:99] offset:576
	s_waitcnt vmcnt(24)
	v_pk_fma_f32 v[78:79], v[78:79], 0.5, v[134:135] op_sel_hi:[1,0,1]
	v_pk_fma_f32 v[80:81], v[80:81], 0.5, v[136:137] op_sel_hi:[1,0,1]
	v_pk_fma_f32 v[74:75], v[74:75], 0.5, v[130:131] op_sel_hi:[1,0,1]
	v_pk_fma_f32 v[76:77], v[76:77], 0.5, v[132:133] op_sel_hi:[1,0,1]
	v_pk_fma_f32 v[70:71], v[70:71], 0.5, v[126:127] op_sel_hi:[1,0,1]
	v_pk_fma_f32 v[72:73], v[72:73], 0.5, v[128:129] op_sel_hi:[1,0,1]
	v_pk_fma_f32 v[66:67], v[66:67], 0.5, v[122:123] op_sel_hi:[1,0,1]
	v_pk_fma_f32 v[68:69], v[68:69], 0.5, v[124:125] op_sel_hi:[1,0,1]
	s_mov_b64 vcc, s[4:5]
	v_cndmask_b32_dpp v134, v74, v78, vcc row_ror:8 row_mask:0xf bank_mask:0xf bound_ctrl:1
	v_cndmask_b32_dpp v135, v75, v79, vcc row_ror:8 row_mask:0xf bank_mask:0xf bound_ctrl:1
	v_cndmask_b32_dpp v136, v76, v80, vcc row_ror:8 row_mask:0xf bank_mask:0xf bound_ctrl:1
	v_cndmask_b32_dpp v137, v77, v81, vcc row_ror:8 row_mask:0xf bank_mask:0xf bound_ctrl:1
	v_cndmask_b32_dpp v126, v66, v70, vcc row_ror:8 row_mask:0xf bank_mask:0xf bound_ctrl:1
	v_cndmask_b32_dpp v127, v67, v71, vcc row_ror:8 row_mask:0xf bank_mask:0xf bound_ctrl:1
	v_cndmask_b32_dpp v128, v68, v72, vcc row_ror:8 row_mask:0xf bank_mask:0xf bound_ctrl:1
	v_cndmask_b32_dpp v129, v69, v73, vcc row_ror:8 row_mask:0xf bank_mask:0xf bound_ctrl:1
	s_not_b64 vcc, s[4:5]
	v_cndmask_b32_dpp v130, v78, v74, vcc row_ror:8 row_mask:0xf bank_mask:0xf bound_ctrl:1
	v_cndmask_b32_dpp v131, v79, v75, vcc row_ror:8 row_mask:0xf bank_mask:0xf bound_ctrl:1
	v_cndmask_b32_dpp v132, v80, v76, vcc row_ror:8 row_mask:0xf bank_mask:0xf bound_ctrl:1
	v_cndmask_b32_dpp v133, v81, v77, vcc row_ror:8 row_mask:0xf bank_mask:0xf bound_ctrl:1
	v_cndmask_b32_dpp v122, v70, v66, vcc row_ror:8 row_mask:0xf bank_mask:0xf bound_ctrl:1
	v_cndmask_b32_dpp v123, v71, v67, vcc row_ror:8 row_mask:0xf bank_mask:0xf bound_ctrl:1
	v_cndmask_b32_dpp v124, v72, v68, vcc row_ror:8 row_mask:0xf bank_mask:0xf bound_ctrl:1
	v_cndmask_b32_dpp v125, v73, v69, vcc row_ror:8 row_mask:0xf bank_mask:0xf bound_ctrl:1
	s_add_u32 s100, s28, 0x30000
	s_addc_u32 s101, s29, 0
	global_store_dwordx4 v186, v[134:137], s[100:101]
	global_store_dwordx4 v187, v[130:133], s[100:101]
	global_store_dwordx4 v186, v[126:129], s[100:101] offset:512
	global_store_dwordx4 v187, v[122:125], s[100:101] offset:512
	s_add_u32 s98, s12, 0xb0000
	s_addc_u32 s99, s13, 0
	global_load_dwordx4 v[78:81], v0, s[98:99]
	global_load_dwordx4 v[74:77], v0, s[98:99] offset:64
	global_load_dwordx4 v[70:73], v0, s[98:99] offset:512
	global_load_dwordx4 v[66:69], v0, s[98:99] offset:576
	s_waitcnt vmcnt(24)
; template <int CTRL> DEVI float dpp(float x) { return __builtin_bit_cast(float, __builtin_amdgcn_mov_dpp(__builtin_bit_cast(int, x), CTRL, 0xf, 0xf, true)); }
;     DEVI void operator()(AccRef acc, const pg8::Unit& u, int wr, int wc, int fr, int fq) const {
;     ...
; #pragma unroll
;             for (int m = 0; m < 4; ++m)
; #pragma unroll
;                 for (int bj = 0; bj < 2; ++bj) { const f32x4 d0 = b[m][bj][0] + alpha * acc[ai][bj][m][0], d1 = b[m][bj][1] + alpha * acc[ai][bj][m][1];
;                     f32x4 t0, t1;
; #pragma unroll
;                     for (int i = 0; i < 4; ++i) { t0[i] = dpp<0x128>(d0[i]); t1[i] = dpp<0x128>(d1[i]); }
;                     const f32x4 sa = lo ? d0 : t1, sb = lo ? t0 : d1;
;                     const unsigned oo = os + (unsigned)(m * 16 * DM * 4 + bj * 512);
;                     *(f32x4*)((char*)out + oo) = sa; *(f32x4*)((char*)out + oo + 8u * DM * 4u) = sb; }
;             o += 128u * DM * 4u; os += 128u * DM * 4u; }
	v_pk_fma_f32 v[62:63], v[62:63], 0.5, v[142:143] op_sel_hi:[1,0,1]
	v_pk_fma_f32 v[64:65], v[64:65], 0.5, v[144:145] op_sel_hi:[1,0,1]
	v_pk_fma_f32 v[58:59], v[58:59], 0.5, v[138:139] op_sel_hi:[1,0,1]
	v_pk_fma_f32 v[60:61], v[60:61], 0.5, v[140:141] op_sel_hi:[1,0,1]
	v_pk_fma_f32 v[54:55], v[54:55], 0.5, v[118:119] op_sel_hi:[1,0,1]
	v_pk_fma_f32 v[56:57], v[56:57], 0.5, v[120:121] op_sel_hi:[1,0,1]
	v_pk_fma_f32 v[50:51], v[50:51], 0.5, v[114:115] op_sel_hi:[1,0,1]
	v_pk_fma_f32 v[52:53], v[52:53], 0.5, v[116:117] op_sel_hi:[1,0,1]
	s_mov_b64 vcc, s[4:5]
	v_cndmask_b32_dpp v142, v58, v62, vcc row_ror:8 row_mask:0xf bank_mask:0xf bound_ctrl:1
	v_cndmask_b32_dpp v143, v59, v63, vcc row_ror:8 row_mask:0xf bank_mask:0xf bound_ctrl:1
	v_cndmask_b32_dpp v144, v60, v64, vcc row_ror:8 row_mask:0xf bank_mask:0xf bound_ctrl:1
	v_cndmask_b32_dpp v145, v61, v65, vcc row_ror:8 row_mask:0xf bank_mask:0xf bound_ctrl:1
	v_cndmask_b32_dpp v118, v50, v54, vcc row_ror:8 row_mask:0xf bank_mask:0xf bound_ctrl:1
	v_cndmask_b32_dpp v119, v51, v55, vcc row_ror:8 row_mask:0xf bank_mask:0xf bound_ctrl:1
	v_cndmask_b32_dpp v120, v52, v56, vcc row_ror:8 row_mask:0xf bank_mask:0xf bound_ctrl:1
	v_cndmask_b32_dpp v121, v53, v57, vcc row_ror:8 row_mask:0xf bank_mask:0xf bound_ctrl:1
	s_not_b64 vcc, s[4:5]
	v_cndmask_b32_dpp v138, v62, v58, vcc row_ror:8 row_mask:0xf bank_mask:0xf bound_ctrl:1
	v_cndmask_b32_dpp v139, v63, v59, vcc row_ror:8 row_mask:0xf bank_mask:0xf bound_ctrl:1
	v_cndmask_b32_dpp v140, v64, v60, vcc row_ror:8 row_mask:0xf bank_mask:0xf bound_ctrl:1
	v_cndmask_b32_dpp v141, v65, v61, vcc row_ror:8 row_mask:0xf bank_mask:0xf bound_ctrl:1
	v_cndmask_b32_dpp v114, v54, v50, vcc row_ror:8 row_mask:0xf bank_mask:0xf bound_ctrl:1
	v_cndmask_b32_dpp v115, v55, v51, vcc row_ror:8 row_mask:0xf bank_mask:0xf bound_ctrl:1
	v_cndmask_b32_dpp v116, v56, v52, vcc row_ror:8 row_mask:0xf bank_mask:0xf bound_ctrl:1
	v_cndmask_b32_dpp v117, v57, v53, vcc row_ror:8 row_mask:0xf bank_mask:0xf bound_ctrl:1
	s_add_u32 s100, s28, 0x80000
	s_addc_u32 s101, s29, 0
	global_store_dwordx4 v186, v[142:145], s[100:101]
	global_store_dwordx4 v187, v[138:141], s[100:101]
	global_store_dwordx4 v186, v[118:121], s[100:101] offset:512
	global_store_dwordx4 v187, v[114:117], s[100:101] offset:512
	s_waitcnt vmcnt(20)
	v_pk_fma_f32 v[46:47], v[46:47], 0.5, v[110:111] op_sel_hi:[1,0,1]
	v_pk_fma_f32 v[48:49], v[48:49], 0.5, v[112:113] op_sel_hi:[1,0,1]
	v_pk_fma_f32 v[42:43], v[42:43], 0.5, v[106:107] op_sel_hi:[1,0,1]
	v_pk_fma_f32 v[44:45], v[44:45], 0.5, v[108:109] op_sel_hi:[1,0,1]
	v_pk_fma_f32 v[38:39], v[38:39], 0.5, v[102:103] op_sel_hi:[1,0,1]
	v_pk_fma_f32 v[40:41], v[40:41], 0.5, v[104:105] op_sel_hi:[1,0,1]
	v_pk_fma_f32 v[34:35], v[34:35], 0.5, v[98:99] op_sel_hi:[1,0,1]
	v_pk_fma_f32 v[36:37], v[36:37], 0.5, v[100:101] op_sel_hi:[1,0,1]
	s_mov_b64 vcc, s[4:5]
	v_cndmask_b32_dpp v110, v42, v46, vcc row_ror:8 row_mask:0xf bank_mask:0xf bound_ctrl:1
	v_cndmask_b32_dpp v111, v43, v47, vcc row_ror:8 row_mask:0xf bank_mask:0xf bound_ctrl:1
	v_cndmask_b32_dpp v112, v44, v48, vcc row_ror:8 row_mask:0xf bank_mask:0xf bound_ctrl:1
	v_cndmask_b32_dpp v113, v45, v49, vcc row_ror:8 row_mask:0xf bank_mask:0xf bound_ctrl:1
	v_cndmask_b32_dpp v102, v34, v38, vcc row_ror:8 row_mask:0xf bank_mask:0xf bound_ctrl:1
	v_cndmask_b32_dpp v103, v35, v39, vcc row_ror:8 row_mask:0xf bank_mask:0xf bound_ctrl:1
	v_cndmask_b32_dpp v104, v36, v40, vcc row_ror:8 row_mask:0xf bank_mask:0xf bound_ctrl:1
	v_cndmask_b32_dpp v105, v37, v41, vcc row_ror:8 row_mask:0xf bank_mask:0xf bound_ctrl:1
	s_not_b64 vcc, s[4:5]
	v_cndmask_b32_dpp v106, v46, v42, vcc row_ror:8 row_mask:0xf bank_mask:0xf bound_ctrl:1
	v_cndmask_b32_dpp v107, v47, v43, vcc row_ror:8 row_mask:0xf bank_mask:0xf bound_ctrl:1
	v_cndmask_b32_dpp v108, v48, v44, vcc row_ror:8 row_mask:0xf bank_mask:0xf bound_ctrl:1
	v_cndmask_b32_dpp v109, v49, v45, vcc row_ror:8 row_mask:0xf bank_mask:0xf bound_ctrl:1
	v_cndmask_b32_dpp v98, v38, v34, vcc row_ror:8 row_mask:0xf bank_mask:0xf bound_ctrl:1
	v_cndmask_b32_dpp v99, v39, v35, vcc row_ror:8 row_mask:0xf bank_mask:0xf bound_ctrl:1
	v_cndmask_b32_dpp v100, v40, v36, vcc row_ror:8 row_mask:0xf bank_mask:0xf bound_ctrl:1
	v_cndmask_b32_dpp v101, v41, v37, vcc row_ror:8 row_mask:0xf bank_mask:0xf bound_ctrl:1
	s_add_u32 s100, s28, 0x90000
	s_addc_u32 s101, s29, 0
	global_store_dwordx4 v186, v[110:113], s[100:101]
	global_store_dwordx4 v187, v[106:109], s[100:101]
	global_store_dwordx4 v186, v[102:105], s[100:101] offset:512
	global_store_dwordx4 v187, v[98:101], s[100:101] offset:512
	s_waitcnt vmcnt(16)
; template <int CTRL> DEVI float dpp(float x) { return __builtin_bit_cast(float, __builtin_amdgcn_mov_dpp(__builtin_bit_cast(int, x), CTRL, 0xf, 0xf, true)); }
; #define PG8_WAIT_V(n) asm volatile("s_waitcnt vmcnt(" #n ")" ::: "memory")
; #define PG8_BAR __builtin_amdgcn_s_barrier()
; template <class Epi, class Sched>
; __device__ __forceinline__ void gemm_phase(PG8_LAS unsigned char* lds, const Gemm g, const Sched& S, const Epi& E, int wv) {
;     ...
;         if (!has_next) break;
; #pragma unroll
;         for (int a = 0; a < 2; ++a)
; #pragma unroll
;             for (int b = 0; b < 2; ++b)
; #pragma unroll
;                 for (int m = 0; m < 4; ++m)
; #pragma unroll
;                     for (int n = 0; n < 2; ++n) acc[a][b][m][n] = (f32x4){0.f, 0.f, 0.f, 0.f};
;         cur = nxt; cA = nA; cB = nB; ++ui;
;     }
;     PG8_WAIT_V(0);
;     if (wr == 0) PG8_BAR;
;     PG8_BAR;
;     DEVI void operator()(AccRef acc, const pg8::Unit& u, int wr, int wc, int fr, int fq) const {
;     ...
; #pragma unroll
;             for (int m = 0; m < 4; ++m)
; #pragma unroll
;                 for (int bj = 0; bj < 2; ++bj) { const f32x4 d0 = b[m][bj][0] + alpha * acc[ai][bj][m][0], d1 = b[m][bj][1] + alpha * acc[ai][bj][m][1];
;                     f32x4 t0, t1;
; #pragma unroll
;                     for (int i = 0; i < 4; ++i) { t0[i] = dpp<0x128>(d0[i]); t1[i] = dpp<0x128>(d1[i]); }
;                     const f32x4 sa = lo ? d0 : t1, sb = lo ? t0 : d1;
;                     const unsigned oo = os + (unsigned)(m * 16 * DM * 4 + bj * 512);
;                     *(f32x4*)((char*)out + oo) = sa; *(f32x4*)((char*)out + oo + 8u * DM * 4u) = sb; }
;             o += 128u * DM * 4u; os += 128u * DM * 4u; }
	v_pk_fma_f32 v[30:31], v[30:31], 0.5, v[94:95] op_sel_hi:[1,0,1]
	v_pk_fma_f32 v[32:33], v[32:33], 0.5, v[96:97] op_sel_hi:[1,0,1]
	v_pk_fma_f32 v[26:27], v[26:27], 0.5, v[90:91] op_sel_hi:[1,0,1]
	v_pk_fma_f32 v[28:29], v[28:29], 0.5, v[92:93] op_sel_hi:[1,0,1]
	v_pk_fma_f32 v[22:23], v[22:23], 0.5, v[86:87] op_sel_hi:[1,0,1]
	v_pk_fma_f32 v[24:25], v[24:25], 0.5, v[88:89] op_sel_hi:[1,0,1]
	v_pk_fma_f32 v[18:19], v[18:19], 0.5, v[82:83] op_sel_hi:[1,0,1]
	v_pk_fma_f32 v[20:21], v[20:21], 0.5, v[84:85] op_sel_hi:[1,0,1]
	s_mov_b64 vcc, s[4:5]
	v_cndmask_b32_dpp v94, v26, v30, vcc row_ror:8 row_mask:0xf bank_mask:0xf bound_ctrl:1
	v_cndmask_b32_dpp v95, v27, v31, vcc row_ror:8 row_mask:0xf bank_mask:0xf bound_ctrl:1
	v_cndmask_b32_dpp v96, v28, v32, vcc row_ror:8 row_mask:0xf bank_mask:0xf bound_ctrl:1
	v_cndmask_b32_dpp v97, v29, v33, vcc row_ror:8 row_mask:0xf bank_mask:0xf bound_ctrl:1
	v_cndmask_b32_dpp v86, v18, v22, vcc row_ror:8 row_mask:0xf bank_mask:0xf bound_ctrl:1
	v_cndmask_b32_dpp v87, v19, v23, vcc row_ror:8 row_mask:0xf bank_mask:0xf bound_ctrl:1
	v_cndmask_b32_dpp v88, v20, v24, vcc row_ror:8 row_mask:0xf bank_mask:0xf bound_ctrl:1
	v_cndmask_b32_dpp v89, v21, v25, vcc row_ror:8 row_mask:0xf bank_mask:0xf bound_ctrl:1
	s_not_b64 vcc, s[4:5]
	v_cndmask_b32_dpp v90, v30, v26, vcc row_ror:8 row_mask:0xf bank_mask:0xf bound_ctrl:1
	v_cndmask_b32_dpp v91, v31, v27, vcc row_ror:8 row_mask:0xf bank_mask:0xf bound_ctrl:1
	v_cndmask_b32_dpp v92, v32, v28, vcc row_ror:8 row_mask:0xf bank_mask:0xf bound_ctrl:1
	v_cndmask_b32_dpp v93, v33, v29, vcc row_ror:8 row_mask:0xf bank_mask:0xf bound_ctrl:1
	v_cndmask_b32_dpp v82, v22, v18, vcc row_ror:8 row_mask:0xf bank_mask:0xf bound_ctrl:1
	v_cndmask_b32_dpp v83, v23, v19, vcc row_ror:8 row_mask:0xf bank_mask:0xf bound_ctrl:1
	v_cndmask_b32_dpp v84, v24, v20, vcc row_ror:8 row_mask:0xf bank_mask:0xf bound_ctrl:1
	v_cndmask_b32_dpp v85, v25, v21, vcc row_ror:8 row_mask:0xf bank_mask:0xf bound_ctrl:1
	s_add_u32 s100, s28, 0xa0000
	s_addc_u32 s101, s29, 0
	global_store_dwordx4 v186, v[94:97], s[100:101]
	global_store_dwordx4 v187, v[90:93], s[100:101]
	global_store_dwordx4 v186, v[86:89], s[100:101] offset:512
	global_store_dwordx4 v187, v[82:85], s[100:101] offset:512
	s_waitcnt vmcnt(12)
	v_pk_fma_f32 v[14:15], v[14:15], 0.5, v[78:79] op_sel_hi:[1,0,1]
	v_pk_fma_f32 v[16:17], v[16:17], 0.5, v[80:81] op_sel_hi:[1,0,1]
	v_pk_fma_f32 v[10:11], v[10:11], 0.5, v[74:75] op_sel_hi:[1,0,1]
	v_pk_fma_f32 v[12:13], v[12:13], 0.5, v[76:77] op_sel_hi:[1,0,1]
	v_pk_fma_f32 v[6:7], v[6:7], 0.5, v[70:71] op_sel_hi:[1,0,1]
	v_pk_fma_f32 v[8:9], v[8:9], 0.5, v[72:73] op_sel_hi:[1,0,1]
	v_pk_fma_f32 v[2:3], v[2:3], 0.5, v[66:67] op_sel_hi:[1,0,1]
	v_pk_fma_f32 v[4:5], v[4:5], 0.5, v[68:69] op_sel_hi:[1,0,1]
	s_mov_b64 vcc, s[4:5]
	v_cndmask_b32_dpp v78, v10, v14, vcc row_ror:8 row_mask:0xf bank_mask:0xf bound_ctrl:1
	v_cndmask_b32_dpp v79, v11, v15, vcc row_ror:8 row_mask:0xf bank_mask:0xf bound_ctrl:1
	v_cndmask_b32_dpp v80, v12, v16, vcc row_ror:8 row_mask:0xf bank_mask:0xf bound_ctrl:1
	v_cndmask_b32_dpp v81, v13, v17, vcc row_ror:8 row_mask:0xf bank_mask:0xf bound_ctrl:1
	v_cndmask_b32_dpp v70, v2, v6, vcc row_ror:8 row_mask:0xf bank_mask:0xf bound_ctrl:1
	v_cndmask_b32_dpp v71, v3, v7, vcc row_ror:8 row_mask:0xf bank_mask:0xf bound_ctrl:1
	v_cndmask_b32_dpp v72, v4, v8, vcc row_ror:8 row_mask:0xf bank_mask:0xf bound_ctrl:1
	v_cndmask_b32_dpp v73, v5, v9, vcc row_ror:8 row_mask:0xf bank_mask:0xf bound_ctrl:1
	s_not_b64 vcc, s[4:5]
	v_cndmask_b32_dpp v74, v14, v10, vcc row_ror:8 row_mask:0xf bank_mask:0xf bound_ctrl:1
	v_cndmask_b32_dpp v75, v15, v11, vcc row_ror:8 row_mask:0xf bank_mask:0xf bound_ctrl:1
	v_cndmask_b32_dpp v76, v16, v12, vcc row_ror:8 row_mask:0xf bank_mask:0xf bound_ctrl:1
	v_cndmask_b32_dpp v77, v17, v13, vcc row_ror:8 row_mask:0xf bank_mask:0xf bound_ctrl:1
	v_cndmask_b32_dpp v66, v6, v2, vcc row_ror:8 row_mask:0xf bank_mask:0xf bound_ctrl:1
	v_cndmask_b32_dpp v67, v7, v3, vcc row_ror:8 row_mask:0xf bank_mask:0xf bound_ctrl:1
	v_cndmask_b32_dpp v68, v8, v4, vcc row_ror:8 row_mask:0xf bank_mask:0xf bound_ctrl:1
	v_cndmask_b32_dpp v69, v9, v5, vcc row_ror:8 row_mask:0xf bank_mask:0xf bound_ctrl:1
	s_add_u32 s100, s28, 0xb0000
	s_addc_u32 s101, s29, 0
	global_store_dwordx4 v186, v[78:81], s[100:101]
	global_store_dwordx4 v187, v[74:77], s[100:101]
	global_store_dwordx4 v186, v[70:73], s[100:101] offset:512
	global_store_dwordx4 v187, v[66:69], s[100:101] offset:512
	s_and_b64 vcc, exec, s[6:7]
	s_cbranch_vccz .LBB0_500
	s_waitcnt vmcnt(0)
	s_cmpk_gt_u32 s24, 0xff
	s_cbranch_scc1 .LBB0_515
	s_barrier

; template <class Epi, class Sched>
; __device__ __forceinline__ void gemm_phase(PG8_LAS unsigned char* lds, const Gemm g, const Sched& S, const Epi& E, int wv) {
;     ...
;         if constexpr (Epi::HOIST) if (pre) { PG8_ITER_F(0); t0_ = 2; }
.LBB0_524:
	s_and_b64 vcc, exec, s[22:23]
	s_cbranch_vccz .LBB0_526
	s_add_i32 s7, 0, 0x10000
	v_add_u32_e32 v0, s7, v147
	ds_read_b128 v[2:5], v0
	ds_read_b128 v[6:9], v0 offset:1024
	ds_read_b128 v[10:13], v0 offset:2048
	ds_read_b128 v[14:17], v0 offset:3072
	ds_read_b128 v[18:21], v149
	ds_read_b128 v[22:25], v149 offset:1024
	ds_read_b128 v[26:29], v149 offset:2048
	ds_read_b128 v[30:33], v149 offset:3072
	ds_read_b128 v[34:37], v149 offset:4096
	ds_read_b128 v[38:41], v149 offset:5120
	ds_read_b128 v[42:45], v149 offset:6144
	ds_read_b128 v[46:49], v149 offset:7168
	s_waitcnt lgkmcnt(8)
	s_setprio 1
	s_barrier
	s_waitcnt lgkmcnt(0)
	v_mfma_f32_16x16x32_bf16 v[50:53], v[2:5], v[18:21], 0
	v_mfma_f32_16x16x32_bf16 v[62:65], v[10:13], v[26:29], 0
	v_mfma_f32_16x16x32_bf16 v[66:69], v[2:5], v[34:37], 0
	v_mfma_f32_16x16x32_bf16 v[70:73], v[10:13], v[34:37], 0
	v_mfma_f32_16x16x32_bf16 v[74:77], v[2:5], v[42:45], 0
	v_mfma_f32_16x16x32_bf16 v[78:81], v[10:13], v[42:45], 0
	v_mfma_f32_16x16x32_bf16 v[50:53], v[6:9], v[22:25], v[50:53]
	v_mfma_f32_16x16x32_bf16 v[54:57], v[10:13], v[18:21], 0
	v_mfma_f32_16x16x32_bf16 v[58:61], v[2:5], v[26:29], 0
	v_mfma_f32_16x16x32_bf16 v[62:65], v[14:17], v[30:33], v[62:65]
	v_mfma_f32_16x16x32_bf16 v[66:69], v[6:9], v[38:41], v[66:69]
	v_mfma_f32_16x16x32_bf16 v[70:73], v[14:17], v[38:41], v[70:73]
	v_mfma_f32_16x16x32_bf16 v[74:77], v[6:9], v[46:49], v[74:77]
	v_mfma_f32_16x16x32_bf16 v[80:83], v[14:17], v[46:49], v[78:81]
	v_mfma_f32_16x16x32_bf16 v[194:197], v[14:17], v[22:25], v[54:57]
	v_mfma_f32_16x16x32_bf16 v[212:215], v[6:9], v[30:33], v[58:61]
	s_setprio 0
	s_barrier
	s_add_i32 s9, 0, 0x14000
	v_lshl_add_u64 v[144:145], s[18:19], 0, v[136:137]
	s_add_i32 s7, s7, s25
	v_add_u32_e32 v0, s9, v147
	v_lshl_add_u64 v[78:79], v[144:145], 0, s[50:51]
	s_mov_b32 m0, s7
	v_lshl_add_u64 v[198:199], s[18:19], 0, v[132:133]
	ds_read_b128 v[84:87], v0
	ds_read_b128 v[88:91], v0 offset:1024
	ds_read_b128 v[92:95], v0 offset:2048
	ds_read_b128 v[96:99], v0 offset:3072
	global_load_lds_dwordx4 v[78:79], off
	v_lshl_add_u64 v[78:79], v[198:199], 0, s[50:51]
	s_add_i32 m0, s7, 0x2000
	s_nop 0
	global_load_lds_dwordx4 v[78:79], off
	s_setprio 1
	s_barrier
	s_waitcnt lgkmcnt(0)
	v_mfma_f32_16x16x32_bf16 v[100:103], v[84:87], v[18:21], 0
	v_mfma_f32_16x16x32_bf16 v[18:21], v[92:95], v[18:21], 0
	v_mfma_f32_16x16x32_bf16 v[104:107], v[88:91], v[22:25], v[100:103]
	v_mfma_f32_16x16x32_bf16 v[18:21], v[96:99], v[22:25], v[18:21]
	v_mfma_f32_16x16x32_bf16 v[22:25], v[84:87], v[26:29], 0
	v_mfma_f32_16x16x32_bf16 v[26:29], v[92:95], v[26:29], 0
	v_mfma_f32_16x16x32_bf16 v[22:25], v[88:91], v[30:33], v[22:25]
	v_mfma_f32_16x16x32_bf16 v[26:29], v[96:99], v[30:33], v[26:29]
	v_mfma_f32_16x16x32_bf16 v[30:33], v[84:87], v[34:37], 0
	v_mfma_f32_16x16x32_bf16 v[34:37], v[92:95], v[34:37], 0
	v_mfma_f32_16x16x32_bf16 v[30:33], v[88:91], v[38:41], v[30:33]
	v_mfma_f32_16x16x32_bf16 v[34:37], v[96:99], v[38:41], v[34:37]
	v_mfma_f32_16x16x32_bf16 v[38:41], v[84:87], v[42:45], 0
	v_mfma_f32_16x16x32_bf16 v[42:45], v[92:95], v[42:45], 0
	v_mfma_f32_16x16x32_bf16 v[38:41], v[88:91], v[46:49], v[38:41]
	v_mfma_f32_16x16x32_bf16 v[42:45], v[96:99], v[46:49], v[42:45]
	s_setprio 0
	v_lshl_add_u64 v[140:141], s[20:21], 0, v[138:139]
	s_mov_b32 m0, s11
	v_lshl_add_u64 v[78:79], v[140:141], 0, s[50:51]
	v_lshl_add_u64 v[142:143], s[20:21], 0, v[134:135]
	s_barrier
	ds_read_b128 v[46:49], v149 offset:16384
	ds_read_b128 v[100:103], v149 offset:17408
	ds_read_b128 v[108:111], v149 offset:18432
	ds_read_b128 v[112:115], v149 offset:19456
	ds_read_b128 v[116:119], v149 offset:20480
	ds_read_b128 v[120:123], v149 offset:21504
	ds_read_b128 v[124:127], v149 offset:22528
	ds_read_b128 v[128:131], v149 offset:23552
	global_load_lds_dwordx4 v[78:79], off
	v_lshl_add_u64 v[78:79], v[142:143], 0, s[50:51]
	s_mov_b32 m0, s57
	s_nop 0
	global_load_lds_dwordx4 v[78:79], off
	s_setprio 1
	s_barrier
	s_waitcnt lgkmcnt(0)
	v_mfma_f32_16x16x32_bf16 v[150:153], v[2:5], v[46:49], 0
	v_mfma_f32_16x16x32_bf16 v[154:157], v[10:13], v[46:49], 0
	v_mfma_f32_16x16x32_bf16 v[158:161], v[2:5], v[108:111], 0
	v_mfma_f32_16x16x32_bf16 v[166:169], v[2:5], v[116:119], 0
	v_mfma_f32_16x16x32_bf16 v[2:5], v[2:5], v[124:127], 0
	v_mfma_f32_16x16x32_bf16 v[54:57], v[6:9], v[100:103], v[150:153]
	v_mfma_f32_16x16x32_bf16 v[152:155], v[14:17], v[100:103], v[154:157]
	v_mfma_f32_16x16x32_bf16 v[156:159], v[6:9], v[112:115], v[158:161]
	v_mfma_f32_16x16x32_bf16 v[166:169], v[6:9], v[120:123], v[166:169]
	v_mfma_f32_16x16x32_bf16 v[2:5], v[6:9], v[128:131], v[2:5]
	v_mfma_f32_16x16x32_bf16 v[6:9], v[10:13], v[124:127], 0
	v_mfma_f32_16x16x32_bf16 v[162:165], v[10:13], v[108:111], 0
	v_mfma_f32_16x16x32_bf16 v[170:173], v[10:13], v[116:119], 0
	v_mfma_f32_16x16x32_bf16 v[6:9], v[14:17], v[128:131], v[6:9]
	v_mfma_f32_16x16x32_bf16 v[160:163], v[14:17], v[112:115], v[162:165]
	v_mfma_f32_16x16x32_bf16 v[170:173], v[14:17], v[120:123], v[170:173]
	s_setprio 0
	s_barrier
	s_add_u32 s14, s18, 0x40100
	s_addc_u32 s15, s19, 0
	s_add_i32 s7, s9, s25
	v_lshl_add_u64 v[10:11], s[14:15], 0, v[136:137]
	s_mov_b32 m0, s7
	s_nop 0
	global_load_lds_dwordx4 v[10:11], off
	v_lshl_add_u64 v[10:11], s[14:15], 0, v[132:133]
	s_add_i32 m0, s7, 0x2000
	s_nop 0
	global_load_lds_dwordx4 v[10:11], off
	s_setprio 1
	s_barrier
	v_mfma_f32_16x16x32_bf16 v[10:13], v[84:87], v[46:49], 0
	v_mfma_f32_16x16x32_bf16 v[174:177], v[88:91], v[100:103], v[10:13]
	v_mfma_f32_16x16x32_bf16 v[10:13], v[92:95], v[46:49], 0
	v_mfma_f32_16x16x32_bf16 v[178:181], v[96:99], v[100:103], v[10:13]
	v_mfma_f32_16x16x32_bf16 v[10:13], v[84:87], v[108:111], 0
	v_mfma_f32_16x16x32_bf16 v[182:185], v[88:91], v[112:115], v[10:13]
	v_mfma_f32_16x16x32_bf16 v[10:13], v[92:95], v[108:111], 0
	v_mfma_f32_16x16x32_bf16 v[186:189], v[96:99], v[112:115], v[10:13]
	v_mfma_f32_16x16x32_bf16 v[10:13], v[84:87], v[116:119], 0
	v_mfma_f32_16x16x32_bf16 v[190:193], v[88:91], v[120:123], v[10:13]
	v_mfma_f32_16x16x32_bf16 v[10:13], v[92:95], v[116:119], 0
	v_mfma_f32_16x16x32_bf16 v[200:203], v[96:99], v[120:123], v[10:13]
	v_mfma_f32_16x16x32_bf16 v[10:13], v[84:87], v[124:127], 0
	v_mfma_f32_16x16x32_bf16 v[204:207], v[88:91], v[128:131], v[10:13]
	v_mfma_f32_16x16x32_bf16 v[10:13], v[92:95], v[124:127], 0
	v_mfma_f32_16x16x32_bf16 v[208:211], v[96:99], v[128:131], v[10:13]
	s_setprio 0
	s_add_i32 s7, 0, 0x18000
	v_add_u32_e32 v0, s7, v147
	s_barrier
	s_nop 2
	ds_read_b128 v[10:13], v0
	ds_read_b128 v[14:17], v0 offset:1024
	v_mov_b64_e32 v[164:165], v[220:221]
	ds_read_b128 v[218:221], v0 offset:2048
	v_mov_b64_e32 v[58:59], v[222:223]
	ds_read_b128 v[222:225], v0 offset:3072
	s_add_u32 s14, s20, 0x40100
	s_addc_u32 s15, s21, 0
	s_mov_b32 m0, s58
	v_lshl_add_u64 v[78:79], s[14:15], 0, v[138:139]
	ds_read_b128 v[46:49], v149 offset:32768
	ds_read_b128 v[88:91], v149 offset:33792
	ds_read_b128 v[96:99], v149 offset:34816
	ds_read_b128 v[226:229], v149 offset:35840
	ds_read_b128 v[230:233], v149 offset:36864
	ds_read_b128 v[234:237], v149 offset:37888
	ds_read_b128 v[238:241], v149 offset:38912
	ds_read_b128 v[242:245], v149 offset:39936
	global_load_lds_dwordx4 v[78:79], off
	v_lshl_add_u64 v[78:79], s[14:15], 0, v[134:135]
	s_mov_b32 m0, s59
	v_mov_b32_e32 v151, v1
	global_load_lds_dwordx4 v[78:79], off
	s_waitcnt lgkmcnt(8)
	s_setprio 1
	s_barrier
	s_waitcnt lgkmcnt(0)
	v_mfma_f32_16x16x32_bf16 v[50:53], v[10:13], v[46:49], v[50:53]
	v_mfma_f32_16x16x32_bf16 v[124:127], v[14:17], v[88:91], v[50:53]
	v_mfma_f32_16x16x32_bf16 v[50:53], v[218:221], v[46:49], v[194:197]
	v_mfma_f32_16x16x32_bf16 v[116:119], v[222:225], v[88:91], v[50:53]
	v_mfma_f32_16x16x32_bf16 v[50:53], v[10:13], v[96:99], v[212:215]
	v_mfma_f32_16x16x32_bf16 v[108:111], v[14:17], v[226:229], v[50:53]
	v_mfma_f32_16x16x32_bf16 v[50:53], v[218:221], v[96:99], v[62:65]
	v_mfma_f32_16x16x32_bf16 v[100:103], v[222:225], v[226:229], v[50:53]
	v_mfma_f32_16x16x32_bf16 v[50:53], v[10:13], v[230:233], v[66:69]
	v_mfma_f32_16x16x32_bf16 v[92:95], v[14:17], v[234:237], v[50:53]
	v_mfma_f32_16x16x32_bf16 v[50:53], v[218:221], v[230:233], v[70:73]
	v_mfma_f32_16x16x32_bf16 v[84:87], v[222:225], v[234:237], v[50:53]
	v_mfma_f32_16x16x32_bf16 v[50:53], v[10:13], v[238:241], v[74:77]
	v_mfma_f32_16x16x32_bf16 v[76:79], v[14:17], v[242:245], v[50:53]
	v_mfma_f32_16x16x32_bf16 v[50:53], v[218:221], v[238:241], v[80:83]
	v_mfma_f32_16x16x32_bf16 v[64:67], v[222:225], v[242:245], v[50:53]
	s_setprio 0
	s_barrier
	s_add_i32 s9, 0, 0x1c000
	s_add_i32 s7, s7, s25
	v_add_u32_e32 v0, s9, v147
	s_nop 1
	v_lshl_add_u64 v[50:51], v[144:145], 0, s[62:63]
	s_mov_b32 m0, s7
	ds_read_b128 v[246:249], v0
	v_mov_b32_e32 v150, v148
	v_mov_b32_e32 v148, v254
	v_mov_b32_e32 v254, v216
	v_mov_b32_e32 v1, v217
	v_mov_b64_e32 v[216:217], v[252:253]
	ds_read_b128 v[250:253], v0 offset:1024
	ds_read_b128 v[194:197], v0 offset:2048
	ds_read_b128 v[212:215], v0 offset:3072
	global_load_lds_dwordx4 v[50:51], off
	v_lshl_add_u64 v[50:51], v[198:199], 0, s[62:63]
	s_add_i32 m0, s7, 0x2000
	s_nop 0
	global_load_lds_dwordx4 v[50:51], off
	s_setprio 1
	s_barrier
; template <class Epi, class Sched>
; __device__ __forceinline__ void gemm_phase(PG8_LAS unsigned char* lds, const Gemm g, const Sched& S, const Epi& E, int wv) {
;     ...
;         if constexpr (Epi::HOIST) if (pre) { PG8_ITER_F(0); t0_ = 2; }
	s_waitcnt lgkmcnt(0)
	v_mfma_f32_16x16x32_bf16 v[18:21], v[194:197], v[46:49], v[18:21]
	v_mfma_f32_16x16x32_bf16 v[120:123], v[212:215], v[88:91], v[18:21]
	v_mfma_f32_16x16x32_bf16 v[18:21], v[246:249], v[96:99], v[22:25]
	v_mfma_f32_16x16x32_bf16 v[112:115], v[250:253], v[226:229], v[18:21]
	v_mfma_f32_16x16x32_bf16 v[18:21], v[194:197], v[96:99], v[26:29]
	v_mfma_f32_16x16x32_bf16 v[50:53], v[246:249], v[46:49], v[104:107]
	v_mfma_f32_16x16x32_bf16 v[104:107], v[212:215], v[226:229], v[18:21]
	v_mfma_f32_16x16x32_bf16 v[18:21], v[246:249], v[230:233], v[30:33]
	v_mfma_f32_16x16x32_bf16 v[96:99], v[250:253], v[234:237], v[18:21]
	v_mfma_f32_16x16x32_bf16 v[18:21], v[194:197], v[230:233], v[34:37]
	v_mfma_f32_16x16x32_bf16 v[128:131], v[250:253], v[88:91], v[50:53]
	v_mfma_f32_16x16x32_bf16 v[88:91], v[212:215], v[234:237], v[18:21]
	v_mfma_f32_16x16x32_bf16 v[18:21], v[246:249], v[238:241], v[38:41]
	v_mfma_f32_16x16x32_bf16 v[80:83], v[250:253], v[242:245], v[18:21]
	v_mfma_f32_16x16x32_bf16 v[18:21], v[194:197], v[238:241], v[42:45]
	v_mfma_f32_16x16x32_bf16 v[72:75], v[212:215], v[242:245], v[18:21]
	s_setprio 0
	s_mov_b32 m0, s60
	s_nop 4
	v_lshl_add_u64 v[18:19], v[140:141], 0, s[62:63]
	s_barrier
	ds_read_b128 v[24:27], v149 offset:49152
	ds_read_b128 v[32:35], v149 offset:50176
	ds_read_b128 v[40:43], v149 offset:51200
	ds_read_b128 v[226:229], v149 offset:52224
	ds_read_b128 v[230:233], v149 offset:53248
	ds_read_b128 v[234:237], v149 offset:54272
	ds_read_b128 v[238:241], v149 offset:55296
	ds_read_b128 v[242:245], v149 offset:56320
	global_load_lds_dwordx4 v[18:19], off
	v_lshl_add_u64 v[18:19], v[142:143], 0, s[62:63]
	s_mov_b32 m0, s61
	s_nop 0
	global_load_lds_dwordx4 v[18:19], off
	s_setprio 1
	s_barrier
	s_waitcnt lgkmcnt(0)
	v_mfma_f32_16x16x32_bf16 v[18:21], v[10:13], v[24:27], v[54:57]
	v_mfma_f32_16x16x32_bf16 v[60:63], v[14:17], v[32:35], v[18:21]
	v_mfma_f32_16x16x32_bf16 v[18:21], v[218:221], v[24:27], v[152:155]
	v_mfma_f32_16x16x32_bf16 v[52:55], v[222:225], v[32:35], v[18:21]
	v_mfma_f32_16x16x32_bf16 v[18:21], v[10:13], v[40:43], v[156:159]
	v_mfma_f32_16x16x32_bf16 v[44:47], v[14:17], v[226:229], v[18:21]
	v_mfma_f32_16x16x32_bf16 v[18:21], v[218:221], v[40:43], v[160:163]
	v_mfma_f32_16x16x32_bf16 v[36:39], v[222:225], v[226:229], v[18:21]
	v_mfma_f32_16x16x32_bf16 v[18:21], v[10:13], v[230:233], v[166:169]
	v_mfma_f32_16x16x32_bf16 v[2:5], v[10:13], v[238:241], v[2:5]
	v_mfma_f32_16x16x32_bf16 v[28:31], v[14:17], v[234:237], v[18:21]
	v_mfma_f32_16x16x32_bf16 v[18:21], v[218:221], v[230:233], v[170:173]
	v_mfma_f32_16x16x32_bf16 v[12:15], v[14:17], v[242:245], v[2:5]
	v_mfma_f32_16x16x32_bf16 v[2:5], v[218:221], v[238:241], v[6:9]
	v_mov_b64_e32 v[220:221], v[164:165]
	v_mfma_f32_16x16x32_bf16 v[20:23], v[222:225], v[234:237], v[18:21]
	v_mfma_f32_16x16x32_bf16 v[4:7], v[222:225], v[242:245], v[2:5]
	v_mov_b64_e32 v[222:223], v[58:59]
	s_setprio 0
	s_barrier
	s_add_u32 s14, s18, 0x40180
	s_addc_u32 s15, s19, 0
	s_add_i32 s7, s9, s25
	v_lshl_add_u64 v[2:3], s[14:15], 0, v[136:137]
	s_mov_b32 m0, s7
	s_nop 0
	global_load_lds_dwordx4 v[2:3], off
	v_lshl_add_u64 v[2:3], s[14:15], 0, v[132:133]
	s_add_i32 m0, s7, 0x2000
	s_nop 0
	global_load_lds_dwordx4 v[2:3], off
	s_waitcnt vmcnt(6)
	s_setprio 1
	s_barrier
	v_mfma_f32_16x16x32_bf16 v[8:11], v[246:249], v[24:27], v[174:177]
	v_mfma_f32_16x16x32_bf16 v[68:71], v[250:253], v[32:35], v[8:11]
	v_mfma_f32_16x16x32_bf16 v[8:11], v[194:197], v[24:27], v[178:181]
	v_mfma_f32_16x16x32_bf16 v[56:59], v[212:215], v[32:35], v[8:11]
	v_mfma_f32_16x16x32_bf16 v[8:11], v[246:249], v[40:43], v[182:185]
	v_mfma_f32_16x16x32_bf16 v[48:51], v[250:253], v[226:229], v[8:11]
	v_mfma_f32_16x16x32_bf16 v[8:11], v[194:197], v[40:43], v[186:189]
	v_mfma_f32_16x16x32_bf16 v[40:43], v[212:215], v[226:229], v[8:11]
	v_mfma_f32_16x16x32_bf16 v[8:11], v[246:249], v[230:233], v[190:193]
	v_mfma_f32_16x16x32_bf16 v[32:35], v[250:253], v[234:237], v[8:11]
	v_mfma_f32_16x16x32_bf16 v[8:11], v[194:197], v[230:233], v[200:203]
	v_mfma_f32_16x16x32_bf16 v[24:27], v[212:215], v[234:237], v[8:11]
	v_mfma_f32_16x16x32_bf16 v[8:11], v[246:249], v[238:241], v[204:207]
	v_mfma_f32_16x16x32_bf16 v[16:19], v[250:253], v[242:245], v[8:11]
	v_mov_b64_e32 v[252:253], v[216:217]
	v_mov_b32_e32 v217, v1
	v_mov_b32_e32 v216, v254
	v_mfma_f32_16x16x32_bf16 v[8:11], v[194:197], v[238:241], v[208:211]
	v_mov_b32_e32 v254, v148
	v_mov_b32_e32 v148, v150
	v_mov_b32_e32 v1, v151
	v_mfma_f32_16x16x32_bf16 v[8:11], v[212:215], v[242:245], v[8:11]
	s_setprio 0
	s_barrier
	s_mov_b32 s22, 2
	s_branch .LBB0_527

.LBB0_528:
	s_add_u32 s20, s81, s46
	s_addc_u32 s21, s82, 0
	s_add_u32 s83, s79, s46
	s_addc_u32 s84, s80, 0
	s_add_i32 s85, 0, 0x10000
	v_add_u32_e32 v0, s85, v147
	ds_read_b128 v[150:153], v0
	ds_read_b128 v[154:157], v0 offset:1024
	ds_read_b128 v[158:161], v0 offset:2048
	ds_read_b128 v[162:165], v0 offset:3072
	s_cmp_eq_u32 s46, s18
	s_cselect_b32 s23, s9, s21
	s_cselect_b32 s22, s76, s20
	s_cselect_b32 s21, s7, s84
	s_cselect_b32 s20, s77, s83
	s_add_i32 s84, s11, 0xc000
	v_lshl_add_u64 v[140:141], v[144:145], 0, s[46:47]
	s_mov_b32 m0, s84
	s_add_i32 s83, s11, 0xe000
	ds_read_b128 v[166:169], v149
	ds_read_b128 v[170:173], v149 offset:1024
	ds_read_b128 v[174:177], v149 offset:2048
	ds_read_b128 v[178:181], v149 offset:3072
	ds_read_b128 v[182:185], v149 offset:4096
	ds_read_b128 v[186:189], v149 offset:5120
	ds_read_b128 v[190:193], v149 offset:6144
	ds_read_b128 v[194:197], v149 offset:7168
	global_load_lds_dwordx4 v[140:141], off
	v_lshl_add_u64 v[140:141], v[2:3], 0, s[46:47]
	s_mov_b32 m0, s83
	s_nop 0
	global_load_lds_dwordx4 v[140:141], off
	s_waitcnt lgkmcnt(8)
	s_setprio 1
	s_barrier
	s_waitcnt lgkmcnt(0)
	v_mfma_f32_16x16x32_bf16 v[124:127], v[150:153], v[166:169], v[124:127]
	v_mfma_f32_16x16x32_bf16 v[116:119], v[158:161], v[166:169], v[116:119]
	v_mfma_f32_16x16x32_bf16 v[108:111], v[150:153], v[174:177], v[108:111]
	v_mfma_f32_16x16x32_bf16 v[100:103], v[158:161], v[174:177], v[100:103]
	v_mfma_f32_16x16x32_bf16 v[92:95], v[150:153], v[182:185], v[92:95]
	v_mfma_f32_16x16x32_bf16 v[84:87], v[158:161], v[182:185], v[84:87]
	v_mfma_f32_16x16x32_bf16 v[76:79], v[150:153], v[190:193], v[76:79]
	v_mfma_f32_16x16x32_bf16 v[64:67], v[158:161], v[190:193], v[64:67]
	v_mfma_f32_16x16x32_bf16 v[124:127], v[154:157], v[170:173], v[124:127]
	v_mfma_f32_16x16x32_bf16 v[116:119], v[162:165], v[170:173], v[116:119]
	v_mfma_f32_16x16x32_bf16 v[108:111], v[154:157], v[178:181], v[108:111]
	v_mfma_f32_16x16x32_bf16 v[100:103], v[162:165], v[178:181], v[100:103]
	v_mfma_f32_16x16x32_bf16 v[92:95], v[154:157], v[186:189], v[92:95]
	v_mfma_f32_16x16x32_bf16 v[84:87], v[162:165], v[186:189], v[84:87]
	v_mfma_f32_16x16x32_bf16 v[76:79], v[154:157], v[194:197], v[76:79]
	v_mfma_f32_16x16x32_bf16 v[64:67], v[162:165], v[194:197], v[64:67]
	s_setprio 0
	s_barrier
	s_add_i32 s88, 0, 0x14000
	s_add_i32 s85, s85, s25
	v_add_u32_e32 v0, s88, v147
	v_lshl_add_u64 v[140:141], s[20:21], 0, v[136:137]
	s_mov_b32 m0, s85
	ds_read_b128 v[200:203], v0
	ds_read_b128 v[204:207], v0 offset:1024
	ds_read_b128 v[208:211], v0 offset:2048
	ds_read_b128 v[212:215], v0 offset:3072
	global_load_lds_dwordx4 v[140:141], off
	v_lshl_add_u64 v[142:143], s[20:21], 0, v[132:133]
	s_add_i32 m0, s85, 0x2000
	s_nop 0
	global_load_lds_dwordx4 v[142:143], off
	s_setprio 1
	s_barrier
	s_waitcnt lgkmcnt(0)
	v_mfma_f32_16x16x32_bf16 v[128:131], v[200:203], v[166:169], v[128:131]
	v_mfma_f32_16x16x32_bf16 v[120:123], v[208:211], v[166:169], v[120:123]
	v_mfma_f32_16x16x32_bf16 v[112:115], v[200:203], v[174:177], v[112:115]
	v_mfma_f32_16x16x32_bf16 v[104:107], v[208:211], v[174:177], v[104:107]
	v_mfma_f32_16x16x32_bf16 v[96:99], v[200:203], v[182:185], v[96:99]
	v_mfma_f32_16x16x32_bf16 v[88:91], v[208:211], v[182:185], v[88:91]
	v_mfma_f32_16x16x32_bf16 v[80:83], v[200:203], v[190:193], v[80:83]
	v_mfma_f32_16x16x32_bf16 v[72:75], v[208:211], v[190:193], v[72:75]
	v_mfma_f32_16x16x32_bf16 v[128:131], v[204:207], v[170:173], v[128:131]
	v_mfma_f32_16x16x32_bf16 v[120:123], v[212:215], v[170:173], v[120:123]
	v_mfma_f32_16x16x32_bf16 v[112:115], v[204:207], v[178:181], v[112:115]
	v_mfma_f32_16x16x32_bf16 v[104:107], v[212:215], v[178:181], v[104:107]
	v_mfma_f32_16x16x32_bf16 v[96:99], v[204:207], v[186:189], v[96:99]
	v_mfma_f32_16x16x32_bf16 v[88:91], v[212:215], v[186:189], v[88:91]
	v_mfma_f32_16x16x32_bf16 v[80:83], v[204:207], v[194:197], v[80:83]
	v_mfma_f32_16x16x32_bf16 v[72:75], v[212:215], v[194:197], v[72:75]
	s_setprio 0
	s_mov_b32 m0, s11
	v_lshl_add_u64 v[198:199], s[22:23], 0, v[138:139]
	s_barrier
	ds_read_b128 v[166:169], v149 offset:16384
	ds_read_b128 v[170:173], v149 offset:17408
	ds_read_b128 v[174:177], v149 offset:18432
	ds_read_b128 v[178:181], v149 offset:19456
	ds_read_b128 v[182:185], v149 offset:20480
	ds_read_b128 v[186:189], v149 offset:21504
	ds_read_b128 v[190:193], v149 offset:22528
	ds_read_b128 v[194:197], v149 offset:23552
	global_load_lds_dwordx4 v[198:199], off
	v_lshl_add_u64 v[218:219], s[22:23], 0, v[134:135]
	s_mov_b32 m0, s57
	s_nop 0
	global_load_lds_dwordx4 v[218:219], off
	s_setprio 1
	s_barrier
	s_waitcnt lgkmcnt(0)
	v_mfma_f32_16x16x32_bf16 v[60:63], v[150:153], v[166:169], v[60:63]
	v_mfma_f32_16x16x32_bf16 v[52:55], v[158:161], v[166:169], v[52:55]
	v_mfma_f32_16x16x32_bf16 v[44:47], v[150:153], v[174:177], v[44:47]
	v_mfma_f32_16x16x32_bf16 v[36:39], v[158:161], v[174:177], v[36:39]
	v_mfma_f32_16x16x32_bf16 v[28:31], v[150:153], v[182:185], v[28:31]
	v_mfma_f32_16x16x32_bf16 v[20:23], v[158:161], v[182:185], v[20:23]
	v_mfma_f32_16x16x32_bf16 v[12:15], v[150:153], v[190:193], v[12:15]
	v_mfma_f32_16x16x32_bf16 v[4:7], v[158:161], v[190:193], v[4:7]
	v_mfma_f32_16x16x32_bf16 v[60:63], v[154:157], v[170:173], v[60:63]
	v_mfma_f32_16x16x32_bf16 v[52:55], v[162:165], v[170:173], v[52:55]
	v_mfma_f32_16x16x32_bf16 v[44:47], v[154:157], v[178:181], v[44:47]
	v_mfma_f32_16x16x32_bf16 v[36:39], v[162:165], v[178:181], v[36:39]
	v_mfma_f32_16x16x32_bf16 v[28:31], v[154:157], v[186:189], v[28:31]
	v_mfma_f32_16x16x32_bf16 v[20:23], v[162:165], v[186:189], v[20:23]
	v_mfma_f32_16x16x32_bf16 v[12:15], v[154:157], v[194:197], v[12:15]
	v_mfma_f32_16x16x32_bf16 v[4:7], v[162:165], v[194:197], v[4:7]
	s_setprio 0
	s_barrier
	s_add_u32 s86, s20, 0x40000
	s_addc_u32 s87, s21, 0
	s_add_i32 s85, s88, s25
	v_lshl_add_u64 v[150:151], s[86:87], 0, v[136:137]
	s_mov_b32 m0, s85
	s_nop 0
	global_load_lds_dwordx4 v[150:151], off
	v_lshl_add_u64 v[150:151], s[86:87], 0, v[132:133]
	s_add_i32 m0, s85, 0x2000
	s_nop 0
	global_load_lds_dwordx4 v[150:151], off
	s_waitcnt vmcnt(6)
	s_setprio 1
	s_barrier
	v_mfma_f32_16x16x32_bf16 v[68:71], v[200:203], v[166:169], v[68:71]
	v_mfma_f32_16x16x32_bf16 v[56:59], v[208:211], v[166:169], v[56:59]
	v_mfma_f32_16x16x32_bf16 v[48:51], v[200:203], v[174:177], v[48:51]
	v_mfma_f32_16x16x32_bf16 v[40:43], v[208:211], v[174:177], v[40:43]
	v_mfma_f32_16x16x32_bf16 v[32:35], v[200:203], v[182:185], v[32:35]
	v_mfma_f32_16x16x32_bf16 v[24:27], v[208:211], v[182:185], v[24:27]
	v_mfma_f32_16x16x32_bf16 v[16:19], v[200:203], v[190:193], v[16:19]
	v_mfma_f32_16x16x32_bf16 v[8:11], v[208:211], v[190:193], v[8:11]
	v_mfma_f32_16x16x32_bf16 v[68:71], v[204:207], v[170:173], v[68:71]
	v_mfma_f32_16x16x32_bf16 v[56:59], v[212:215], v[170:173], v[56:59]
	v_mfma_f32_16x16x32_bf16 v[48:51], v[204:207], v[178:181], v[48:51]
	v_mfma_f32_16x16x32_bf16 v[40:43], v[212:215], v[178:181], v[40:43]
	v_mfma_f32_16x16x32_bf16 v[32:35], v[204:207], v[186:189], v[32:35]
	v_mfma_f32_16x16x32_bf16 v[24:27], v[212:215], v[186:189], v[24:27]
	v_mfma_f32_16x16x32_bf16 v[16:19], v[204:207], v[194:197], v[16:19]
	v_mfma_f32_16x16x32_bf16 v[8:11], v[212:215], v[194:197], v[8:11]
	s_setprio 0
	s_add_i32 s85, 0, 0x18000
	v_add_u32_e32 v0, s85, v147
	s_barrier
	ds_read_b128 v[150:153], v0
	ds_read_b128 v[154:157], v0 offset:1024
	ds_read_b128 v[158:161], v0 offset:2048
	ds_read_b128 v[162:165], v0 offset:3072
	s_add_u32 s22, s22, 0x40000
	s_addc_u32 s23, s23, 0
	s_mov_b32 m0, s58
	v_lshl_add_u64 v[200:201], s[22:23], 0, v[138:139]
	ds_read_b128 v[166:169], v149 offset:32768
	ds_read_b128 v[170:173], v149 offset:33792
	ds_read_b128 v[174:177], v149 offset:34816
	ds_read_b128 v[178:181], v149 offset:35840
	ds_read_b128 v[182:185], v149 offset:36864
	ds_read_b128 v[186:189], v149 offset:37888
	ds_read_b128 v[190:193], v149 offset:38912
	ds_read_b128 v[194:197], v149 offset:39936
	global_load_lds_dwordx4 v[200:201], off
	v_lshl_add_u64 v[200:201], s[22:23], 0, v[134:135]
	s_mov_b32 m0, s59
	s_nop 0
	global_load_lds_dwordx4 v[200:201], off
	s_waitcnt lgkmcnt(8)
	s_setprio 1
	s_barrier
	s_waitcnt lgkmcnt(0)
	v_mfma_f32_16x16x32_bf16 v[124:127], v[150:153], v[166:169], v[124:127]
	v_mfma_f32_16x16x32_bf16 v[116:119], v[158:161], v[166:169], v[116:119]
	v_mfma_f32_16x16x32_bf16 v[108:111], v[150:153], v[174:177], v[108:111]
	v_mfma_f32_16x16x32_bf16 v[100:103], v[158:161], v[174:177], v[100:103]
	v_mfma_f32_16x16x32_bf16 v[92:95], v[150:153], v[182:185], v[92:95]
	v_mfma_f32_16x16x32_bf16 v[84:87], v[158:161], v[182:185], v[84:87]
	v_mfma_f32_16x16x32_bf16 v[76:79], v[150:153], v[190:193], v[76:79]
	v_mfma_f32_16x16x32_bf16 v[64:67], v[158:161], v[190:193], v[64:67]
	v_mfma_f32_16x16x32_bf16 v[124:127], v[154:157], v[170:173], v[124:127]
	v_mfma_f32_16x16x32_bf16 v[116:119], v[162:165], v[170:173], v[116:119]
	v_mfma_f32_16x16x32_bf16 v[108:111], v[154:157], v[178:181], v[108:111]
	v_mfma_f32_16x16x32_bf16 v[100:103], v[162:165], v[178:181], v[100:103]
	v_mfma_f32_16x16x32_bf16 v[92:95], v[154:157], v[186:189], v[92:95]
	v_mfma_f32_16x16x32_bf16 v[84:87], v[162:165], v[186:189], v[84:87]
	v_mfma_f32_16x16x32_bf16 v[76:79], v[154:157], v[194:197], v[76:79]
	v_mfma_f32_16x16x32_bf16 v[64:67], v[162:165], v[194:197], v[64:67]
	s_setprio 0
	s_barrier
	s_add_i32 s22, 0, 0x1c000
	s_add_i32 s23, s85, s25
	v_add_u32_e32 v0, s22, v147
	v_lshl_add_u64 v[140:141], v[140:141], 0, s[48:49]
	s_mov_b32 m0, s23
	ds_read_b128 v[200:203], v0
	ds_read_b128 v[204:207], v0 offset:1024
	ds_read_b128 v[208:211], v0 offset:2048
	ds_read_b128 v[212:215], v0 offset:3072
	global_load_lds_dwordx4 v[140:141], off
	v_lshl_add_u64 v[140:141], v[142:143], 0, s[48:49]
	s_add_i32 m0, s23, 0x2000
	s_nop 0
	global_load_lds_dwordx4 v[140:141], off
	s_setprio 1
	s_barrier
	s_waitcnt lgkmcnt(0)
	v_mfma_f32_16x16x32_bf16 v[128:131], v[200:203], v[166:169], v[128:131]
	v_mfma_f32_16x16x32_bf16 v[120:123], v[208:211], v[166:169], v[120:123]
	v_mfma_f32_16x16x32_bf16 v[112:115], v[200:203], v[174:177], v[112:115]
	v_mfma_f32_16x16x32_bf16 v[104:107], v[208:211], v[174:177], v[104:107]
	v_mfma_f32_16x16x32_bf16 v[96:99], v[200:203], v[182:185], v[96:99]
	v_mfma_f32_16x16x32_bf16 v[88:91], v[208:211], v[182:185], v[88:91]
	v_mfma_f32_16x16x32_bf16 v[80:83], v[200:203], v[190:193], v[80:83]
	v_mfma_f32_16x16x32_bf16 v[72:75], v[208:211], v[190:193], v[72:75]
	v_mfma_f32_16x16x32_bf16 v[128:131], v[204:207], v[170:173], v[128:131]
	v_mfma_f32_16x16x32_bf16 v[120:123], v[212:215], v[170:173], v[120:123]
	v_mfma_f32_16x16x32_bf16 v[112:115], v[204:207], v[178:181], v[112:115]
	v_mfma_f32_16x16x32_bf16 v[104:107], v[212:215], v[178:181], v[104:107]
	v_mfma_f32_16x16x32_bf16 v[96:99], v[204:207], v[186:189], v[96:99]
	v_mfma_f32_16x16x32_bf16 v[88:91], v[212:215], v[186:189], v[88:91]
	v_mfma_f32_16x16x32_bf16 v[80:83], v[204:207], v[194:197], v[80:83]
	v_mfma_f32_16x16x32_bf16 v[72:75], v[212:215], v[194:197], v[72:75]
	s_setprio 0
	s_mov_b32 m0, s60
	v_lshl_add_u64 v[140:141], v[198:199], 0, s[48:49]
	s_barrier
	ds_read_b128 v[166:169], v149 offset:49152
	ds_read_b128 v[170:173], v149 offset:50176
	ds_read_b128 v[174:177], v149 offset:51200
	ds_read_b128 v[178:181], v149 offset:52224
	ds_read_b128 v[182:185], v149 offset:53248
	ds_read_b128 v[186:189], v149 offset:54272
	ds_read_b128 v[190:193], v149 offset:55296
	ds_read_b128 v[194:197], v149 offset:56320
	global_load_lds_dwordx4 v[140:141], off
	v_lshl_add_u64 v[140:141], v[218:219], 0, s[48:49]
	s_mov_b32 m0, s61
	s_nop 0
	global_load_lds_dwordx4 v[140:141], off
	s_setprio 1
	s_barrier
; DEVI unsigned cvtpk(float lo, float hi) { unsigned r; asm volatile("v_cvt_pk_bf16_f32 %0, %1, %2" : "=v"(r) : "v"(lo), "v"(hi)); return r; }
; DEVI float sigmoidf_(float x) { return __builtin_amdgcn_rcpf(1.f + __expf(-x)); }
;     DEVI void operator()(AccRef acc, const pg8::Unit& u, int wr, int wc, int fr, int fq) const {
;         const int row0 = u.pm * 256 + wr * 64 + fr, col = u.pn * 128 + wc * 32 + 8 * fq;
; #pragma unroll
;         for (int ai = 0; ai < 2; ++ai)
; #pragma unroll
;             for (int m = 0; m < 4; ++m) { bf16_t* rowp = Hm + (size_t)(row0 + ai * 128 + m * 16) * DFF + col; float h[8];
; #pragma unroll
;                 for (int j = 0; j < 8; ++j) { const float gt = acc[ai][0][m][j >> 2][j & 3], up = acc[ai][1][m][j >> 2][j & 3]; h[j] = gt * sigmoidf_(gt) * up; }
;                 u32x4 w; w.x = cvtpk(h[0], h[1]); w.y = cvtpk(h[2], h[3]); w.z = cvtpk(h[4], h[5]); w.w = cvtpk(h[6], h[7]);
;                 if (ai == 0 && m == 0) asm volatile("s_waitcnt vmcnt(0)" ::: "memory");
;                 __builtin_nontemporal_store(w, (u32x4*)rowp); }
	s_waitcnt lgkmcnt(0)
	v_mfma_f32_16x16x32_bf16 v[60:63], v[150:153], v[166:169], v[60:63]
	v_mfma_f32_16x16x32_bf16 v[52:55], v[158:161], v[166:169], v[52:55]
	v_mfma_f32_16x16x32_bf16 v[44:47], v[150:153], v[174:177], v[44:47]
	v_mfma_f32_16x16x32_bf16 v[36:39], v[158:161], v[174:177], v[36:39]
	v_mfma_f32_16x16x32_bf16 v[28:31], v[150:153], v[182:185], v[28:31]
	v_mfma_f32_16x16x32_bf16 v[20:23], v[158:161], v[182:185], v[20:23]
	v_mfma_f32_16x16x32_bf16 v[12:15], v[150:153], v[190:193], v[12:15]
	v_mfma_f32_16x16x32_bf16 v[4:7], v[158:161], v[190:193], v[4:7]
	v_mfma_f32_16x16x32_bf16 v[60:63], v[154:157], v[170:173], v[60:63]
	v_mfma_f32_16x16x32_bf16 v[52:55], v[162:165], v[170:173], v[52:55]
	v_mfma_f32_16x16x32_bf16 v[44:47], v[154:157], v[178:181], v[44:47]
	v_mfma_f32_16x16x32_bf16 v[36:39], v[162:165], v[178:181], v[36:39]
	v_mfma_f32_16x16x32_bf16 v[28:31], v[154:157], v[186:189], v[28:31]
	v_mfma_f32_16x16x32_bf16 v[20:23], v[162:165], v[186:189], v[20:23]
	v_mfma_f32_16x16x32_bf16 v[12:15], v[154:157], v[194:197], v[12:15]
	v_mfma_f32_16x16x32_bf16 v[4:7], v[162:165], v[194:197], v[4:7]
	s_setprio 0
	s_barrier
	s_add_u32 s20, s20, 0x40080
	s_addc_u32 s21, s21, 0
	s_add_i32 s22, s22, s25
	v_lshl_add_u64 v[140:141], s[20:21], 0, v[136:137]
	s_mov_b32 m0, s22
	s_nop 0
	global_load_lds_dwordx4 v[140:141], off
	v_lshl_add_u64 v[140:141], s[20:21], 0, v[132:133]
	s_add_i32 m0, s22, 0x2000
	s_nop 0
	global_load_lds_dwordx4 v[140:141], off
	s_waitcnt vmcnt(6)
	s_setprio 1
	s_barrier
	v_mfma_f32_16x16x32_bf16 v[68:71], v[200:203], v[166:169], v[68:71]
	v_mfma_f32_16x16x32_bf16 v[56:59], v[208:211], v[166:169], v[56:59]
	v_mfma_f32_16x16x32_bf16 v[48:51], v[200:203], v[174:177], v[48:51]
	v_mfma_f32_16x16x32_bf16 v[40:43], v[208:211], v[174:177], v[40:43]
	v_mfma_f32_16x16x32_bf16 v[32:35], v[200:203], v[182:185], v[32:35]
	v_mfma_f32_16x16x32_bf16 v[24:27], v[208:211], v[182:185], v[24:27]
	v_mfma_f32_16x16x32_bf16 v[16:19], v[200:203], v[190:193], v[16:19]
	v_mfma_f32_16x16x32_bf16 v[8:11], v[208:211], v[190:193], v[8:11]
	v_mfma_f32_16x16x32_bf16 v[68:71], v[204:207], v[170:173], v[68:71]
	v_mfma_f32_16x16x32_bf16 v[56:59], v[212:215], v[170:173], v[56:59]
	v_mfma_f32_16x16x32_bf16 v[48:51], v[204:207], v[178:181], v[48:51]
	v_mfma_f32_16x16x32_bf16 v[40:43], v[212:215], v[178:181], v[40:43]
	v_mfma_f32_16x16x32_bf16 v[32:35], v[204:207], v[186:189], v[32:35]
	v_mfma_f32_16x16x32_bf16 v[24:27], v[212:215], v[186:189], v[24:27]
	v_mfma_f32_16x16x32_bf16 v[16:19], v[204:207], v[194:197], v[16:19]
	v_mfma_f32_16x16x32_bf16 v[8:11], v[212:215], v[194:197], v[8:11]
	s_setprio 0
	s_add_i32 s78, s78, 2
	s_add_u32 s79, s79, 0x100
	s_addc_u32 s80, s80, 0
	s_add_u32 s81, s81, 0x100
	s_addc_u32 s82, s82, 0
	s_add_u32 s18, s18, 0xffffff00
	s_addc_u32 s19, s19, -1
	v_lshl_add_u64 v[2:3], v[2:3], 0, s[50:51]
	s_cmp_gt_u32 s78, 13
	v_lshl_add_u64 v[144:145], v[144:145], 0, s[50:51]
	s_barrier
	s_cbranch_scc0 .LBB0_528
	s_add_u32 s18, s76, 0x40080
	s_addc_u32 s19, s9, 0
	s_mov_b32 m0, s84
	v_lshl_add_u64 v[2:3], s[18:19], 0, v[138:139]
	global_load_lds_dwordx4 v[2:3], off
	v_lshl_add_u64 v[2:3], s[18:19], 0, v[134:135]
	s_mov_b32 m0, s83
	v_lshl_or_b32 v140, s75, 7, v148
	global_load_lds_dwordx4 v[2:3], off
	v_mul_f32_e32 v2, 0xbfb8aa3b, v124
	v_exp_f32_e32 v142, v2
	v_mul_f32_e32 v2, 0xbfb8aa3b, v125
	v_exp_f32_e32 v143, v2
	v_lshl_add_u32 v0, s10, 8, v146
	v_add_f32_e32 v142, 1.0, v142
	v_rcp_f32_e32 v144, v142
	v_add_f32_e32 v142, 1.0, v143
	v_rcp_f32_e32 v145, v142
	v_ashrrev_i32_e32 v141, 31, v140
	v_mul_f32_e32 v124, v124, v144
	v_mul_f32_e32 v124, v124, v128
	v_mul_f32_e32 v128, 0xbfb8aa3b, v126
	v_mul_f32_e32 v144, 0xbfb8aa3b, v127
	v_exp_f32_e32 v128, v128
	v_exp_f32_e32 v144, v144
	v_mul_f32_e32 v125, v125, v145
	v_mul_f32_e32 v125, v125, v129
	v_add_f32_e32 v128, 1.0, v128
	v_add_f32_e32 v129, 1.0, v144
	v_mul_f32_e32 v144, 0xbfb8aa3b, v116
	v_rcp_f32_e32 v128, v128
	v_exp_f32_e32 v144, v144
	v_rcp_f32_e32 v129, v129
	v_mov_b64_e32 v[2:3], s[68:69]
	v_mul_f32_e32 v126, v126, v128
	v_add_f32_e32 v128, 1.0, v144
	v_mul_f32_e32 v127, v127, v129
	v_rcp_f32_e32 v128, v128
	v_mul_f32_e32 v129, 0xbfb8aa3b, v117
	v_exp_f32_e32 v129, v129
	v_mad_i64_i32 v[142:143], s[18:19], v0, s3, v[2:3]
	v_mul_f32_e32 v116, v116, v128
	v_mul_f32_e32 v120, v116, v120
	v_add_f32_e32 v116, 1.0, v129
	v_mul_f32_e32 v128, 0xbfb8aa3b, v118
	v_rcp_f32_e32 v116, v116
	v_exp_f32_e32 v128, v128
	v_mul_f32_e32 v129, 0xbfb8aa3b, v119
	v_exp_f32_e32 v129, v129
	v_mul_f32_e32 v116, v117, v116
	v_add_f32_e32 v117, 1.0, v128
	v_rcp_f32_e32 v117, v117
	v_mul_f32_e32 v121, v116, v121
	v_add_f32_e32 v128, 1.0, v129
	v_rcp_f32_e32 v128, v128
	v_mul_f32_e32 v116, v118, v117
	v_cvt_pk_bf16_f32 v118, v124, v125
	v_mul_f32_e32 v124, 0xbfb8aa3b, v108
	v_exp_f32_e32 v124, v124
	v_mul_f32_e32 v125, 0xbfb8aa3b, v109
	v_exp_f32_e32 v125, v125
	v_mul_f32_e32 v129, v116, v122
	v_add_f32_e32 v124, 1.0, v124
	v_rcp_f32_e32 v124, v124
	v_mul_f32_e32 v116, v119, v128
	v_mul_f32_e32 v128, v116, v123
	v_lshlrev_b64 v[116:117], 1, v[140:141]
	v_lshl_add_u64 v[122:123], v[142:143], 0, v[116:117]
	v_add_f32_e32 v125, 1.0, v125
	v_mul_f32_e32 v108, v108, v124
	v_mul_f32_e32 v126, v126, v130
	v_mul_f32_e32 v127, v127, v131
	v_cvt_pk_bf16_f32 v119, v126, v127
	v_cvt_pk_bf16_f32 v120, v120, v121
	v_cvt_pk_bf16_f32 v121, v129, v128
	s_waitcnt vmcnt(0)
; DEVI unsigned cvtpk(float lo, float hi) { unsigned r; asm volatile("v_cvt_pk_bf16_f32 %0, %1, %2" : "=v"(r) : "v"(lo), "v"(hi)); return r; }
; DEVI float sigmoidf_(float x) { return __builtin_amdgcn_rcpf(1.f + __expf(-x)); }
;     DEVI void operator()(AccRef acc, const pg8::Unit& u, int wr, int wc, int fr, int fq) const {
;         const int row0 = u.pm * 256 + wr * 64 + fr, col = u.pn * 128 + wc * 32 + 8 * fq;
; #pragma unroll
;         for (int ai = 0; ai < 2; ++ai)
; #pragma unroll
;             for (int m = 0; m < 4; ++m) { bf16_t* rowp = Hm + (size_t)(row0 + ai * 128 + m * 16) * DFF + col; float h[8];
; #pragma unroll
;                 for (int j = 0; j < 8; ++j) { const float gt = acc[ai][0][m][j >> 2][j & 3], up = acc[ai][1][m][j >> 2][j & 3]; h[j] = gt * sigmoidf_(gt) * up; }
;                 u32x4 w; w.x = cvtpk(h[0], h[1]); w.y = cvtpk(h[2], h[3]); w.z = cvtpk(h[4], h[5]); w.w = cvtpk(h[6], h[7]);
;                 if (ai == 0 && m == 0) asm volatile("s_waitcnt vmcnt(0)" ::: "memory");
;                 __builtin_nontemporal_store(w, (u32x4*)rowp); }
	v_rcp_f32_e32 v125, v125
	flat_store_dwordx4 v[122:123], v[118:121]
	v_mul_f32_e32 v108, v108, v112
	v_mul_f32_e32 v112, 0xbfb8aa3b, v110
	v_mul_f32_e32 v118, 0xbfb8aa3b, v111
	v_exp_f32_e32 v112, v112
	v_exp_f32_e32 v118, v118
	v_mul_f32_e32 v109, v109, v125
	v_mul_f32_e32 v109, v109, v113
	v_add_f32_e32 v112, 1.0, v112
	v_add_f32_e32 v113, 1.0, v118
	v_mul_f32_e32 v118, 0xbfb8aa3b, v100
	v_rcp_f32_e32 v112, v112
	v_exp_f32_e32 v118, v118
	v_rcp_f32_e32 v113, v113
	s_mov_b64 s[22:23], -1
	v_mul_f32_e32 v110, v110, v112
	v_add_f32_e32 v112, 1.0, v118
	v_mul_f32_e32 v111, v111, v113
	v_rcp_f32_e32 v112, v112
	v_mul_f32_e32 v113, 0xbfb8aa3b, v101
	v_exp_f32_e32 v113, v113
	v_mul_f32_e32 v110, v110, v114
	v_mul_f32_e32 v100, v100, v112
	v_mul_f32_e32 v104, v100, v104
	v_add_f32_e32 v100, 1.0, v113
	v_mul_f32_e32 v112, 0xbfb8aa3b, v102
	v_rcp_f32_e32 v100, v100
	v_exp_f32_e32 v112, v112
	v_mul_f32_e32 v113, 0xbfb8aa3b, v103
	v_exp_f32_e32 v113, v113
	v_mul_f32_e32 v100, v101, v100
	v_add_f32_e32 v101, 1.0, v112
	v_rcp_f32_e32 v101, v101
	v_add_f32_e32 v112, 1.0, v113
	v_rcp_f32_e32 v112, v112
	v_mul_f32_e32 v105, v100, v105
	v_mul_f32_e32 v100, v102, v101
	v_mul_f32_e32 v106, v100, v106
	v_mul_f32_e32 v100, v103, v112
	v_mul_f32_e32 v103, v100, v107
	v_mul_f32_e32 v111, v111, v115
	v_cvt_pk_bf16_f32 v100, v108, v109
	v_cvt_pk_bf16_f32 v101, v110, v111
	v_cvt_pk_bf16_f32 v102, v104, v105
	v_cvt_pk_bf16_f32 v103, v106, v103
	v_mul_f32_e32 v106, 0xbfb8aa3b, v92
	v_exp_f32_e32 v106, v106
	v_mul_f32_e32 v107, 0xbfb8aa3b, v93
	v_exp_f32_e32 v107, v107
	v_or_b32_e32 v104, 16, v0
	v_add_f32_e32 v106, 1.0, v106
	v_rcp_f32_e32 v106, v106
	v_mad_i64_i32 v[104:105], s[18:19], v104, s3, v[2:3]
	v_lshl_add_u64 v[104:105], v[104:105], 0, v[116:117]
	v_add_f32_e32 v107, 1.0, v107
	v_mul_f32_e32 v92, v92, v106
	v_rcp_f32_e32 v107, v107
	flat_store_dwordx4 v[104:105], v[100:103]
	v_mul_f32_e32 v92, v92, v96
	v_mul_f32_e32 v96, 0xbfb8aa3b, v94
	v_mul_f32_e32 v100, 0xbfb8aa3b, v95
	v_exp_f32_e32 v96, v96
	v_exp_f32_e32 v100, v100
	v_mul_f32_e32 v93, v93, v107
	v_mul_f32_e32 v93, v93, v97
	v_add_f32_e32 v96, 1.0, v96
	v_add_f32_e32 v97, 1.0, v100
	v_mul_f32_e32 v100, 0xbfb8aa3b, v84
	v_rcp_f32_e32 v96, v96
	v_exp_f32_e32 v100, v100
	v_rcp_f32_e32 v97, v97
	s_and_b64 vcc, exec, s[4:5]
	v_mul_f32_e32 v94, v94, v96
	v_add_f32_e32 v96, 1.0, v100
	v_mul_f32_e32 v95, v95, v97
	v_rcp_f32_e32 v96, v96
	v_mul_f32_e32 v97, 0xbfb8aa3b, v85
	v_exp_f32_e32 v97, v97
	v_mul_f32_e32 v94, v94, v98
	v_mul_f32_e32 v84, v84, v96
	v_mul_f32_e32 v88, v84, v88
	v_add_f32_e32 v84, 1.0, v97
	v_mul_f32_e32 v96, 0xbfb8aa3b, v86
	v_rcp_f32_e32 v84, v84
	v_exp_f32_e32 v96, v96
	v_mul_f32_e32 v97, 0xbfb8aa3b, v87
	v_exp_f32_e32 v97, v97
	v_mul_f32_e32 v84, v85, v84
	v_add_f32_e32 v85, 1.0, v96
	v_rcp_f32_e32 v85, v85
	v_add_f32_e32 v96, 1.0, v97
	v_rcp_f32_e32 v96, v96
	v_mul_f32_e32 v89, v84, v89
	v_mul_f32_e32 v84, v86, v85
	v_mul_f32_e32 v90, v84, v90
	v_mul_f32_e32 v84, v87, v96
	v_mul_f32_e32 v87, v84, v91
	v_mul_f32_e32 v95, v95, v99
	v_cvt_pk_bf16_f32 v84, v92, v93
	v_cvt_pk_bf16_f32 v85, v94, v95
	v_cvt_pk_bf16_f32 v86, v88, v89
	v_cvt_pk_bf16_f32 v87, v90, v87
	v_mul_f32_e32 v90, 0xbfb8aa3b, v76
	v_exp_f32_e32 v90, v90
	v_mul_f32_e32 v91, 0xbfb8aa3b, v77
	v_exp_f32_e32 v91, v91
	v_or_b32_e32 v88, 32, v0
	v_add_f32_e32 v90, 1.0, v90
	v_rcp_f32_e32 v90, v90
	v_mad_i64_i32 v[88:89], s[18:19], v88, s3, v[2:3]
	v_lshl_add_u64 v[88:89], v[88:89], 0, v[116:117]
	v_add_f32_e32 v91, 1.0, v91
	v_mul_f32_e32 v76, v76, v90
	v_rcp_f32_e32 v91, v91
	flat_store_dwordx4 v[88:89], v[84:87]
	v_mul_f32_e32 v76, v76, v80
	v_mul_f32_e32 v80, 0xbfb8aa3b, v78
	v_mul_f32_e32 v84, 0xbfb8aa3b, v79
	v_exp_f32_e32 v80, v80
	v_exp_f32_e32 v84, v84
	v_mul_f32_e32 v77, v77, v91
	v_mul_f32_e32 v77, v77, v81
	v_add_f32_e32 v80, 1.0, v80
	v_add_f32_e32 v81, 1.0, v84
	v_mul_f32_e32 v84, 0xbfb8aa3b, v64
	v_rcp_f32_e32 v80, v80
	v_exp_f32_e32 v84, v84
	v_rcp_f32_e32 v81, v81
	s_mov_b32 s75, s6
	v_mul_f32_e32 v78, v78, v80
	v_add_f32_e32 v80, 1.0, v84
	v_mul_f32_e32 v79, v79, v81
	v_rcp_f32_e32 v80, v80
	v_mul_f32_e32 v81, 0xbfb8aa3b, v65
	v_exp_f32_e32 v81, v81
	v_mul_f32_e32 v78, v78, v82
	v_mul_f32_e32 v64, v64, v80
	v_mul_f32_e32 v72, v64, v72
	v_add_f32_e32 v64, 1.0, v81
	v_mul_f32_e32 v80, 0xbfb8aa3b, v66
	v_rcp_f32_e32 v64, v64
	v_exp_f32_e32 v80, v80
	v_mul_f32_e32 v81, 0xbfb8aa3b, v67
	v_exp_f32_e32 v81, v81
	v_mul_f32_e32 v64, v65, v64
	v_add_f32_e32 v65, 1.0, v80
	v_rcp_f32_e32 v65, v65
	v_add_f32_e32 v80, 1.0, v81
	v_rcp_f32_e32 v80, v80
	v_mul_f32_e32 v73, v64, v73
	v_mul_f32_e32 v64, v66, v65
	v_mul_f32_e32 v74, v64, v74
	v_mul_f32_e32 v64, v67, v80
	v_mul_f32_e32 v79, v79, v83
	v_mul_f32_e32 v67, v64, v75
	v_cvt_pk_bf16_f32 v64, v76, v77
	v_cvt_pk_bf16_f32 v65, v78, v79
	v_cvt_pk_bf16_f32 v66, v72, v73
	v_or_b32_e32 v72, 48, v0
	v_mad_i64_i32 v[72:73], s[18:19], v72, s3, v[2:3]
	v_lshl_add_u64 v[72:73], v[72:73], 0, v[116:117]
	v_cvt_pk_bf16_f32 v67, v74, v67
	flat_store_dwordx4 v[72:73], v[64:67]
	v_mul_f32_e32 v74, 0xbfb8aa3b, v60
	v_mul_f32_e32 v75, 0xbfb8aa3b, v61
	v_mul_f32_e32 v64, 0xbfb8aa3b, v62
	v_exp_f32_e32 v64, v64
	v_mul_f32_e32 v65, 0xbfb8aa3b, v63
	v_exp_f32_e32 v65, v65
	v_mul_f32_e32 v66, 0xbfb8aa3b, v52
	v_add_f32_e32 v64, 1.0, v64
	v_rcp_f32_e32 v64, v64
	v_add_f32_e32 v65, 1.0, v65
	v_exp_f32_e32 v66, v66
	v_rcp_f32_e32 v65, v65
	v_mul_f32_e32 v62, v62, v64
	v_exp_f32_e32 v74, v74
	v_add_f32_e32 v64, 1.0, v66
	v_mul_f32_e32 v63, v63, v65
	v_rcp_f32_e32 v64, v64
	v_mul_f32_e32 v65, 0xbfb8aa3b, v53
	v_exp_f32_e32 v65, v65
	v_exp_f32_e32 v75, v75
	v_mul_f32_e32 v52, v52, v64
; DEVI unsigned cvtpk(float lo, float hi) { unsigned r; asm volatile("v_cvt_pk_bf16_f32 %0, %1, %2" : "=v"(r) : "v"(lo), "v"(hi)); return r; }
; DEVI float sigmoidf_(float x) { return __builtin_amdgcn_rcpf(1.f + __expf(-x)); }
; #define PG8_WAIT_V(n) asm volatile("s_waitcnt vmcnt(" #n ")" ::: "memory")
; #define PG8_BAR __builtin_amdgcn_s_barrier()
; template <class Epi, class Sched>
; __device__ __forceinline__ void gemm_phase(PG8_LAS unsigned char* lds, const Gemm g, const Sched& S, const Epi& E, int wv) {
;     ...
;     PG8_WAIT_V(0);
;     if (wr == 0) PG8_BAR;
;     DEVI void operator()(AccRef acc, const pg8::Unit& u, int wr, int wc, int fr, int fq) const {
;         const int row0 = u.pm * 256 + wr * 64 + fr, col = u.pn * 128 + wc * 32 + 8 * fq;
; #pragma unroll
;         for (int ai = 0; ai < 2; ++ai)
; #pragma unroll
;             for (int m = 0; m < 4; ++m) { bf16_t* rowp = Hm + (size_t)(row0 + ai * 128 + m * 16) * DFF + col; float h[8];
; #pragma unroll
;                 for (int j = 0; j < 8; ++j) { const float gt = acc[ai][0][m][j >> 2][j & 3], up = acc[ai][1][m][j >> 2][j & 3]; h[j] = gt * sigmoidf_(gt) * up; }
;                 u32x4 w; w.x = cvtpk(h[0], h[1]); w.y = cvtpk(h[2], h[3]); w.z = cvtpk(h[4], h[5]); w.w = cvtpk(h[6], h[7]);
;                 if (ai == 0 && m == 0) asm volatile("s_waitcnt vmcnt(0)" ::: "memory");
;                 __builtin_nontemporal_store(w, (u32x4*)rowp); }
	v_mul_f32_e32 v56, v52, v56
	v_add_f32_e32 v52, 1.0, v65
	v_mul_f32_e32 v64, 0xbfb8aa3b, v54
	v_rcp_f32_e32 v52, v52
	v_exp_f32_e32 v64, v64
	v_mul_f32_e32 v65, 0xbfb8aa3b, v55
	v_exp_f32_e32 v65, v65
	v_mul_f32_e32 v52, v53, v52
	v_add_f32_e32 v53, 1.0, v64
	v_rcp_f32_e32 v53, v53
	v_add_f32_e32 v64, 1.0, v65
	v_add_f32_e32 v74, 1.0, v74
	v_add_f32_e32 v75, 1.0, v75
	v_rcp_f32_e32 v64, v64
	v_rcp_f32_e32 v74, v74
	v_rcp_f32_e32 v75, v75
	v_mul_f32_e32 v57, v52, v57
	v_mul_f32_e32 v52, v54, v53
	v_mul_f32_e32 v58, v52, v58
	v_mul_f32_e32 v52, v55, v64
	v_mul_f32_e32 v60, v60, v74
	v_mul_f32_e32 v61, v61, v75
	v_mul_f32_e32 v55, v52, v59
	v_mul_f32_e32 v60, v60, v68
	v_mul_f32_e32 v61, v61, v69
	v_mul_f32_e32 v62, v62, v70
	v_mul_f32_e32 v63, v63, v71
	v_cvt_pk_bf16_f32 v52, v60, v61
	v_cvt_pk_bf16_f32 v53, v62, v63
	v_cvt_pk_bf16_f32 v54, v56, v57
	v_cvt_pk_bf16_f32 v55, v58, v55
	v_mul_f32_e32 v58, 0xbfb8aa3b, v44
	v_exp_f32_e32 v58, v58
	v_mul_f32_e32 v59, 0xbfb8aa3b, v45
	v_exp_f32_e32 v59, v59
	v_add_u32_e32 v56, 0x80, v0
	v_add_f32_e32 v58, 1.0, v58
	v_rcp_f32_e32 v58, v58
	v_mad_i64_i32 v[56:57], s[18:19], v56, s3, v[2:3]
	v_lshl_add_u64 v[56:57], v[56:57], 0, v[116:117]
	v_add_f32_e32 v59, 1.0, v59
	v_mul_f32_e32 v44, v44, v58
	v_rcp_f32_e32 v59, v59
	flat_store_dwordx4 v[56:57], v[52:55]
	v_mul_f32_e32 v44, v44, v48
	v_mul_f32_e32 v48, 0xbfb8aa3b, v46
	v_mul_f32_e32 v52, 0xbfb8aa3b, v47
	v_exp_f32_e32 v48, v48
	v_exp_f32_e32 v52, v52
	v_mul_f32_e32 v45, v45, v59
	v_mul_f32_e32 v45, v45, v49
	v_add_f32_e32 v48, 1.0, v48
	v_add_f32_e32 v49, 1.0, v52
	v_mul_f32_e32 v52, 0xbfb8aa3b, v36
	v_rcp_f32_e32 v48, v48
	v_exp_f32_e32 v52, v52
	v_rcp_f32_e32 v49, v49
	s_mov_b32 s10, s8
	v_mul_f32_e32 v46, v46, v48
	v_add_f32_e32 v48, 1.0, v52
	v_mul_f32_e32 v47, v47, v49
	v_rcp_f32_e32 v48, v48
	v_mul_f32_e32 v49, 0xbfb8aa3b, v37
	v_exp_f32_e32 v49, v49
	v_mul_f32_e32 v46, v46, v50
	v_mul_f32_e32 v36, v36, v48
	v_mul_f32_e32 v40, v36, v40
	v_add_f32_e32 v36, 1.0, v49
	v_mul_f32_e32 v48, 0xbfb8aa3b, v38
	v_rcp_f32_e32 v36, v36
	v_exp_f32_e32 v48, v48
	v_mul_f32_e32 v49, 0xbfb8aa3b, v39
	v_exp_f32_e32 v49, v49
	v_mul_f32_e32 v36, v37, v36
	v_add_f32_e32 v37, 1.0, v48
	v_rcp_f32_e32 v37, v37
	v_add_f32_e32 v48, 1.0, v49
	v_rcp_f32_e32 v48, v48
	v_mul_f32_e32 v41, v36, v41
	v_mul_f32_e32 v36, v38, v37
	v_mul_f32_e32 v42, v36, v42
	v_mul_f32_e32 v36, v39, v48
	v_mul_f32_e32 v39, v36, v43
	v_mul_f32_e32 v47, v47, v51
	v_cvt_pk_bf16_f32 v36, v44, v45
	v_cvt_pk_bf16_f32 v37, v46, v47
	v_cvt_pk_bf16_f32 v38, v40, v41
	v_cvt_pk_bf16_f32 v39, v42, v39
	v_mul_f32_e32 v42, 0xbfb8aa3b, v28
	v_exp_f32_e32 v42, v42
	v_mul_f32_e32 v43, 0xbfb8aa3b, v29
	v_exp_f32_e32 v43, v43
	v_add_u32_e32 v40, 0x90, v0
	v_add_f32_e32 v42, 1.0, v42
	v_rcp_f32_e32 v42, v42
	v_mad_i64_i32 v[40:41], s[18:19], v40, s3, v[2:3]
	v_lshl_add_u64 v[40:41], v[40:41], 0, v[116:117]
	v_add_f32_e32 v43, 1.0, v43
	v_mul_f32_e32 v28, v28, v42
	v_rcp_f32_e32 v43, v43
	flat_store_dwordx4 v[40:41], v[36:39]
	v_mul_f32_e32 v28, v28, v32
	v_mul_f32_e32 v32, 0xbfb8aa3b, v30
	v_mul_f32_e32 v36, 0xbfb8aa3b, v31
	v_exp_f32_e32 v32, v32
	v_exp_f32_e32 v36, v36
	v_mul_f32_e32 v29, v29, v43
	v_mul_f32_e32 v29, v29, v33
	v_add_f32_e32 v32, 1.0, v32
	v_add_f32_e32 v33, 1.0, v36
	v_mul_f32_e32 v36, 0xbfb8aa3b, v20
	v_rcp_f32_e32 v32, v32
	v_exp_f32_e32 v36, v36
	v_rcp_f32_e32 v33, v33
	s_mov_b64 s[20:21], s[12:13]
	v_mul_f32_e32 v30, v30, v32
	v_add_f32_e32 v32, 1.0, v36
	v_mul_f32_e32 v31, v31, v33
	v_rcp_f32_e32 v32, v32
	v_mul_f32_e32 v33, 0xbfb8aa3b, v21
	v_exp_f32_e32 v33, v33
	v_mul_f32_e32 v30, v30, v34
	v_mul_f32_e32 v20, v20, v32
	v_mul_f32_e32 v24, v20, v24
	v_add_f32_e32 v20, 1.0, v33
	v_mul_f32_e32 v32, 0xbfb8aa3b, v22
	v_rcp_f32_e32 v20, v20
	v_exp_f32_e32 v32, v32
	v_mul_f32_e32 v33, 0xbfb8aa3b, v23
	v_exp_f32_e32 v33, v33
	v_mul_f32_e32 v20, v21, v20
	v_add_f32_e32 v21, 1.0, v32
	v_rcp_f32_e32 v21, v21
	v_add_f32_e32 v32, 1.0, v33
	v_rcp_f32_e32 v32, v32
	v_mul_f32_e32 v25, v20, v25
	v_mul_f32_e32 v20, v22, v21
	v_mul_f32_e32 v26, v20, v26
	v_mul_f32_e32 v20, v23, v32
	v_mul_f32_e32 v23, v20, v27
	v_mul_f32_e32 v31, v31, v35
	v_cvt_pk_bf16_f32 v20, v28, v29
	v_cvt_pk_bf16_f32 v21, v30, v31
	v_cvt_pk_bf16_f32 v22, v24, v25
	v_cvt_pk_bf16_f32 v23, v26, v23
	v_mul_f32_e32 v26, 0xbfb8aa3b, v12
	v_exp_f32_e32 v26, v26
	v_mul_f32_e32 v27, 0xbfb8aa3b, v13
	v_exp_f32_e32 v27, v27
	v_add_u32_e32 v24, 0xa0, v0
	v_add_f32_e32 v26, 1.0, v26
	v_rcp_f32_e32 v26, v26
	v_mad_i64_i32 v[24:25], s[18:19], v24, s3, v[2:3]
	v_lshl_add_u64 v[24:25], v[24:25], 0, v[116:117]
	v_add_f32_e32 v27, 1.0, v27
	v_mul_f32_e32 v12, v12, v26
	v_rcp_f32_e32 v27, v27
	flat_store_dwordx4 v[24:25], v[20:23]
	v_mul_f32_e32 v12, v12, v16
	v_mul_f32_e32 v16, 0xbfb8aa3b, v14
	v_mul_f32_e32 v20, 0xbfb8aa3b, v15
	v_exp_f32_e32 v16, v16
	v_exp_f32_e32 v20, v20
	v_mul_f32_e32 v13, v13, v27
	v_mul_f32_e32 v13, v13, v17
	v_add_f32_e32 v16, 1.0, v16
	v_add_f32_e32 v17, 1.0, v20
	v_mul_f32_e32 v20, 0xbfb8aa3b, v4
	v_rcp_f32_e32 v16, v16
	v_exp_f32_e32 v20, v20
	v_rcp_f32_e32 v17, v17
	v_add_u32_e32 v0, 0xb0, v0
	v_mul_f32_e32 v14, v14, v16
	v_add_f32_e32 v16, 1.0, v20
	v_mul_f32_e32 v15, v15, v17
	v_rcp_f32_e32 v16, v16
	v_mul_f32_e32 v17, 0xbfb8aa3b, v5
	v_exp_f32_e32 v17, v17
	v_mad_i64_i32 v[2:3], s[18:19], v0, s3, v[2:3]
	v_mul_f32_e32 v4, v4, v16
	v_mul_f32_e32 v8, v4, v8
	v_add_f32_e32 v4, 1.0, v17
	v_mul_f32_e32 v16, 0xbfb8aa3b, v6
	v_rcp_f32_e32 v4, v4
	v_exp_f32_e32 v16, v16
	v_mul_f32_e32 v17, 0xbfb8aa3b, v7
	v_exp_f32_e32 v17, v17
	v_mul_f32_e32 v4, v5, v4
	v_add_f32_e32 v5, 1.0, v16
	v_rcp_f32_e32 v5, v5
	v_add_f32_e32 v16, 1.0, v17
	v_rcp_f32_e32 v16, v16
	v_mul_f32_e32 v9, v4, v9
	v_mul_f32_e32 v4, v6, v5
	v_mul_f32_e32 v10, v4, v10
	v_mul_f32_e32 v4, v7, v16
	v_mul_f32_e32 v7, v4, v11
	v_lshl_add_u64 v[2:3], v[2:3], 0, v[116:117]
	s_mov_b64 s[18:19], s[14:15]
	v_mul_f32_e32 v14, v14, v18
	v_mul_f32_e32 v15, v15, v19
	v_cvt_pk_bf16_f32 v4, v12, v13
	v_cvt_pk_bf16_f32 v5, v14, v15
	v_cvt_pk_bf16_f32 v6, v8, v9
	v_cvt_pk_bf16_f32 v7, v10, v7
	flat_store_dwordx4 v[2:3], v[4:7]
	s_cbranch_vccz .LBB0_522
	s_waitcnt vmcnt(0)
	s_cmpk_gt_u32 s24, 0xff
	s_cbranch_scc1 .LBB0_532
	s_barrier
